# cache-policy hint: conv phase u loads (read exactly once) marked nt so they do not displace the twice-read a halo rows
# baseline (speedup 1.0000x reference)
; __device__ __forceinline__ void phase_conv(KP p, int l, int tid) {
;     ...
;   for (int it = blockIdx.x * NTH + tid; it < total; it += gridDim.x * NTH) {
;     const int cc = it % 1408; const int rs = it / 1408; const int sgm = rs & 3, r0 = (rs >> 2) * RB; const int c0 = cc * 4;
;     f32x4 w[9];
; #pragma unroll
;     for (int k = 0; k < 9; ++k) w[k] = *(const f32x4*)(cw + k * DFF + c0);
;     const f32x4 bsv = *(const f32x4*)(cbias + c0);
;     const bf16_t* rowp[RB + 2]; bool rv[RB + 2];
; #pragma unroll
;     for (int di = 0; di < RB + 2; ++di) { const int rr = r0 + di - 1; rv[di] = (rr >= 0) && (rr < 256); const int rc = rr < 0 ? 0 : (rr > 255 ? 255 : rr); rowp[di] = A + (size_t)(rc * 64) * DFF + c0; }
;     float win[3][RB + 2][4];
;     const int j0 = sgm * 16;
;     {
;       u32x2 ra[2][RB + 2];
; #pragma unroll
;       for (int s = 0; s < 2; ++s) { const int col = j0 - 1 + s; const int cl = col < 0 ? 0 : col;
; #pragma unroll
;         for (int di = 0; di < RB + 2; ++di) ra[s][di] = *(const u32x2*)(rowp[di] + (size_t)cl * DFF); }
; #pragma unroll
;       for (int s = 0; s < 2; ++s) { const int col = j0 - 1 + s;
; #pragma unroll
;         for (int di = 0; di < RB + 2; ++di) { const bool ok = rv[di] && (col >= 0); unpack4(ra[s][di], win[s][di]);
; #pragma unroll
;           for (int k = 0; k < 4; ++k) win[s][di][k] = ok ? win[s][di][k] : 0.f; } }
;     }
; #pragma unroll 1
;     for (int jb = j0; jb < j0 + 16; jb += CB) {
;       u32x2 an[CB][RB + 2], ur[CB][RB];
; #pragma unroll
;       for (int q = 0; q < CB; ++q) { const int col = jb + q + 1; const int cl = col > 63 ? 63 : col;
; #pragma unroll
;         for (int di = 0; di < RB + 2; ++di) an[q][di] = *(const u32x2*)(rowp[di] + (size_t)cl * DFF);
; #pragma unroll
;         for (int rr = 0; rr < RB; ++rr) ur[q][rr] = *(const u32x2*)(U + (size_t)((r0 + rr) * 64 + jb + q) * DFF + c0); }
.Lcv_item:
	v_lshrrev_b32_e32 v222, 7, v142
	v_mul_u32_u24_e32 v223, 0xba3, v222
	v_lshrrev_b32_e32 v223, 16, v223
	v_mul_u32_u24_e32 v224, 22, v223
	v_sub_u32_e32 v224, v222, v224
	v_and_b32_e32 v225, 63, v142
	v_lshl_add_u32 v224, v224, 6, v225
	v_bfe_u32 v225, v142, 6, 1
	v_lshrrev_b32_e32 v222, 2, v223
	v_lshl_add_u32 v222, v222, 1, v225
	v_and_b32_e32 v225, 3, v223
	v_lshl_or_b32 v222, v222, 2, v225
	v_lshlrev_b32_e32 v223, 3, v224
	v_lshlrev_b32_e32 v224, 4, v224
	global_load_dwordx4 v[0:3], v224, s[20:21]
	v_add_u32_e32 v225, 0x5800, v224
	global_load_dwordx4 v[4:7], v225, s[20:21]
	v_add_u32_e32 v225, 0xb000, v224
	global_load_dwordx4 v[8:11], v225, s[20:21]
	v_add_u32_e32 v225, 0x10800, v224
	global_load_dwordx4 v[12:15], v225, s[20:21]
	v_add_u32_e32 v225, 0x16000, v224
	global_load_dwordx4 v[16:19], v225, s[20:21]
	v_add_u32_e32 v225, 0x1b800, v224
	global_load_dwordx4 v[20:23], v225, s[20:21]
	v_add_u32_e32 v225, 0x21000, v224
	global_load_dwordx4 v[24:27], v225, s[20:21]
	v_add_u32_e32 v225, 0x26800, v224
	global_load_dwordx4 v[28:31], v225, s[20:21]
	v_add_u32_e32 v225, 0x2c000, v224
	global_load_dwordx4 v[32:35], v225, s[20:21]
	global_load_dwordx4 v[36:39], v224, s[22:23]
	v_and_b32_e32 v224, 3, v222
	v_lshrrev_b32_e32 v222, 1, v222
	v_and_b32_e32 v222, -2, v222
	v_cmp_lt_u32_e32 vcc, 0, v222
	s_nop 1
	v_cndmask_b32_e32 v200, 0, v186, vcc
	v_mov_b32_e32 v201, v200
	v_cmp_gt_u32_e32 vcc, 0xfe, v222
	s_nop 1
	v_cndmask_b32_e32 v202, 0, v186, vcc
	v_mov_b32_e32 v203, v202
	v_sub_u32_e64 v225, v222, 1 clamp
	v_mul_u32_u24_e32 v206, 0xb0000, v225
	v_mul_u32_u24_e32 v207, 0xb0000, v222
	v_add_u32_e32 v208, 0xb0000, v207
	v_add_u32_e32 v225, 2, v222
	v_min_u32_e32 v225, 0xff, v225
	v_mul_u32_u24_e32 v209, 0xb0000, v225
	v_add_u32_e32 v206, v206, v223
	v_add_u32_e32 v207, v207, v223
	v_add_u32_e32 v208, v208, v223
	v_add_u32_e32 v209, v209, v223
	v_lshlrev_b32_e32 v224, 4, v224
	v_mul_u32_u24_e32 v210, 0x2c00, v224
	v_cmp_lt_u32_e32 vcc, 0, v224
	s_nop 1
	v_cndmask_b32_e32 v204, 0, v186, vcc
	v_mov_b32_e32 v205, v204
	v_sub_u32_e64 v225, v224, 1 clamp
	v_mul_u32_u24_e32 v225, 0x2c00, v225
	v_add_u32_e32 v212, v206, v225
	global_load_dwordx2 v[96:97], v212, s[6:7]
	v_add_u32_e32 v213, v207, v225
	global_load_dwordx2 v[98:99], v213, s[6:7]
	v_add_u32_e32 v214, v208, v225
	global_load_dwordx2 v[100:101], v214, s[6:7]
	v_add_u32_e32 v215, v209, v225
	global_load_dwordx2 v[102:103], v215, s[6:7]
	v_add_u32_e32 v212, v206, v210
	global_load_dwordx2 v[88:89], v212, s[6:7]
	v_add_u32_e32 v213, v207, v210
	global_load_dwordx2 v[90:91], v213, s[6:7]
	v_add_u32_e32 v214, v208, v210
	global_load_dwordx2 v[92:93], v214, s[6:7]
	v_add_u32_e32 v215, v209, v210
	global_load_dwordx2 v[94:95], v215, s[6:7]
	s_waitcnt vmcnt(0)
	v_lshlrev_b32_e32 v40, 16, v96
	v_and_b32_e32 v41, 0xffff0000, v96
	v_lshlrev_b32_e32 v42, 16, v97
	v_and_b32_e32 v43, 0xffff0000, v97
	v_lshlrev_b32_e32 v44, 16, v98
	v_and_b32_e32 v45, 0xffff0000, v98
	v_lshlrev_b32_e32 v46, 16, v99
	v_and_b32_e32 v47, 0xffff0000, v99
	v_lshlrev_b32_e32 v48, 16, v100
	v_and_b32_e32 v49, 0xffff0000, v100
	v_lshlrev_b32_e32 v50, 16, v101
	v_and_b32_e32 v51, 0xffff0000, v101
	v_lshlrev_b32_e32 v52, 16, v102
	v_and_b32_e32 v53, 0xffff0000, v102
	v_lshlrev_b32_e32 v54, 16, v103
	v_and_b32_e32 v55, 0xffff0000, v103
	v_pk_mul_f32 v[40:41], v[40:41], v[200:201]
	v_pk_mul_f32 v[42:43], v[42:43], v[200:201]
	v_pk_mul_f32 v[52:53], v[52:53], v[202:203]
	v_pk_mul_f32 v[54:55], v[54:55], v[202:203]
	v_pk_mul_f32 v[40:41], v[40:41], v[204:205]
	v_pk_mul_f32 v[42:43], v[42:43], v[204:205]
	v_pk_mul_f32 v[44:45], v[44:45], v[204:205]
	v_pk_mul_f32 v[46:47], v[46:47], v[204:205]
	v_pk_mul_f32 v[48:49], v[48:49], v[204:205]
	v_pk_mul_f32 v[50:51], v[50:51], v[204:205]
	v_pk_mul_f32 v[52:53], v[52:53], v[204:205]
	v_pk_mul_f32 v[54:55], v[54:55], v[204:205]
	v_lshlrev_b32_e32 v56, 16, v88
	v_and_b32_e32 v57, 0xffff0000, v88
	v_lshlrev_b32_e32 v58, 16, v89
	v_and_b32_e32 v59, 0xffff0000, v89
	v_lshlrev_b32_e32 v60, 16, v90
	v_and_b32_e32 v61, 0xffff0000, v90
	v_lshlrev_b32_e32 v62, 16, v91
	v_and_b32_e32 v63, 0xffff0000, v91
	v_lshlrev_b32_e32 v64, 16, v92
	v_and_b32_e32 v65, 0xffff0000, v92
	v_lshlrev_b32_e32 v66, 16, v93
	v_and_b32_e32 v67, 0xffff0000, v93
	v_lshlrev_b32_e32 v68, 16, v94
	v_and_b32_e32 v69, 0xffff0000, v94
	v_lshlrev_b32_e32 v70, 16, v95
	v_and_b32_e32 v71, 0xffff0000, v95
	v_pk_mul_f32 v[56:57], v[56:57], v[200:201]
	v_pk_mul_f32 v[58:59], v[58:59], v[200:201]
	v_pk_mul_f32 v[68:69], v[68:69], v[202:203]
	v_pk_mul_f32 v[70:71], v[70:71], v[202:203]
	v_add_u32_e32 v211, 0x2c00, v210
	v_add_u32_e32 v212, v206, v211
	global_load_dwordx2 v[88:89], v212, s[6:7]
	v_add_u32_e32 v213, v207, v211
	global_load_dwordx2 v[90:91], v213, s[6:7]
	v_add_u32_e32 v214, v208, v211
	global_load_dwordx2 v[92:93], v214, s[6:7]
	v_add_u32_e32 v215, v209, v211
	global_load_dwordx2 v[94:95], v215, s[6:7]
	v_add_u32_e32 v216, v207, v210
	global_load_dwordx2 v[112:113], v216, s[8:9] nt
	v_add_u32_e32 v217, v208, v210
	global_load_dwordx2 v[114:115], v217, s[8:9] nt
	v_add_u32_e32 v210, 0x2c00, v210
	v_add_u32_e32 v211, 0x2c00, v210
	v_add_u32_e32 v212, v206, v211
	global_load_dwordx2 v[96:97], v212, s[6:7]
	v_add_u32_e32 v213, v207, v211
	global_load_dwordx2 v[98:99], v213, s[6:7]
	v_add_u32_e32 v214, v208, v211
	global_load_dwordx2 v[100:101], v214, s[6:7]
	v_add_u32_e32 v215, v209, v211
	global_load_dwordx2 v[102:103], v215, s[6:7]
	v_add_u32_e32 v218, v207, v210
	global_load_dwordx2 v[116:117], v218, s[8:9] nt
	v_add_u32_e32 v219, v208, v210
	global_load_dwordx2 v[118:119], v219, s[8:9] nt
	v_cmp_gt_u32_e32 vcc, 48, v224
	s_nop 1
	v_cndmask_b32_e32 v204, 0, v186, vcc
	v_mov_b32_e32 v205, v204
	v_add_u32_e32 v210, 0x2c00, v210
	v_add_u32_e32 v211, 0x2c00, v210
	v_add_u32_e32 v212, v206, v211
	global_load_dwordx2 v[104:105], v212, s[6:7]
	v_add_u32_e32 v213, v207, v211
	global_load_dwordx2 v[106:107], v213, s[6:7]
	v_add_u32_e32 v214, v208, v211
	global_load_dwordx2 v[108:109], v214, s[6:7]
	v_add_u32_e32 v215, v209, v211
	global_load_dwordx2 v[110:111], v215, s[6:7]
	v_add_u32_e32 v220, v207, v210
	global_load_dwordx2 v[120:121], v220, s[8:9] nt
	v_add_u32_e32 v221, v208, v210
	global_load_dwordx2 v[122:123], v221, s[8:9] nt
	s_waitcnt vmcnt(12)
; __device__ __forceinline__ unsigned cvt_pk_bf16(float lo, float hi) { unsigned r; asm volatile("v_cvt_pk_bf16_f32 %0, %1, %2" : "=v"(r) : "v"(lo), "v"(hi)); return r; }
; __device__ __forceinline__ float gelu_as(float v) {
;   const float av = fabsf(v); const float t = __builtin_amdgcn_rcpf(av * 0.2316418882f + 1.0f);
;   float q = t * 0.5307027145f + (-0.7265760135f); q = q * t + 0.7107068705f; q = q * t + (-0.142248368f); q = q * t + 0.127414796f; q = q * t;
;   const float e = __builtin_amdgcn_exp2f((v * v) * (-0.72134752044f));
;   const float m = v * (q * e);
;   return v < 0.f ? m : v - m;
; }
; __device__ __forceinline__ void phase_conv(KP p, int l, int tid) {
;     ...
;         for (int di = 0; di < RB + 2; ++di) { const bool ok = rv[di] && (col < 64); unpack4(an[q][di], win[2][di]);
; #pragma unroll
;           for (int k = 0; k < 4; ++k) win[2][di][k] = ok ? win[2][di][k] : 0.f; }
; #pragma unroll
;         for (int rr = 0; rr < RB; ++rr) {
;           float uv[4]; unpack4(ur[q][rr], uv);
;           float o[4];
; #pragma unroll
;           for (int k = 0; k < 4; ++k) {
;             float a = bsv[k];
; #pragma unroll
;             for (int di = 0; di < 3; ++di)
; #pragma unroll
;               for (int dj = 0; dj < 3; ++dj) a += win[dj][rr + di][k] * w[di * 3 + dj][k];
;             o[k] = gelu_as(a) * uv[k];
;           }
;           u32x2 ow; ow.x = cvt_pk_bf16(o[0], o[1]); ow.y = cvt_pk_bf16(o[2], o[3]);
;           *(u32x2*)(G + (size_t)((r0 + rr) * 64 + jb + q) * DFF + c0) = ow;
	v_lshlrev_b32_e32 v72, 16, v88
	v_and_b32_e32 v73, 0xffff0000, v88
	v_lshlrev_b32_e32 v74, 16, v89
	v_and_b32_e32 v75, 0xffff0000, v89
	v_lshlrev_b32_e32 v76, 16, v90
	v_and_b32_e32 v77, 0xffff0000, v90
	v_lshlrev_b32_e32 v78, 16, v91
	v_and_b32_e32 v79, 0xffff0000, v91
	v_lshlrev_b32_e32 v80, 16, v92
	v_and_b32_e32 v81, 0xffff0000, v92
	v_lshlrev_b32_e32 v82, 16, v93
	v_and_b32_e32 v83, 0xffff0000, v93
	v_lshlrev_b32_e32 v84, 16, v94
	v_and_b32_e32 v85, 0xffff0000, v94
	v_lshlrev_b32_e32 v86, 16, v95
	v_and_b32_e32 v87, 0xffff0000, v95
	v_pk_mul_f32 v[72:73], v[72:73], v[200:201]
	v_pk_mul_f32 v[74:75], v[74:75], v[200:201]
	v_pk_mul_f32 v[84:85], v[84:85], v[202:203]
	v_pk_mul_f32 v[86:87], v[86:87], v[202:203]
	v_lshlrev_b32_e32 v124, 16, v112
	v_and_b32_e32 v125, 0xffff0000, v112
	v_lshlrev_b32_e32 v126, 16, v113
	v_and_b32_e32 v127, 0xffff0000, v113
	v_lshlrev_b32_e32 v128, 16, v114
	v_and_b32_e32 v129, 0xffff0000, v114
	v_lshlrev_b32_e32 v130, 16, v115
	v_and_b32_e32 v131, 0xffff0000, v115
	v_pk_fma_f32 v[148:149], v[40:41], v[0:1], v[36:37]
	v_pk_fma_f32 v[150:151], v[42:43], v[2:3], v[38:39]
	v_pk_fma_f32 v[152:153], v[44:45], v[0:1], v[36:37]
	v_pk_fma_f32 v[154:155], v[46:47], v[2:3], v[38:39]
	v_pk_fma_f32 v[148:149], v[56:57], v[4:5], v[148:149]
	v_pk_fma_f32 v[150:151], v[58:59], v[6:7], v[150:151]
	v_pk_fma_f32 v[152:153], v[60:61], v[4:5], v[152:153]
	v_pk_fma_f32 v[154:155], v[62:63], v[6:7], v[154:155]
	v_pk_fma_f32 v[148:149], v[72:73], v[8:9], v[148:149]
	v_pk_fma_f32 v[150:151], v[74:75], v[10:11], v[150:151]
	v_pk_fma_f32 v[152:153], v[76:77], v[8:9], v[152:153]
	v_pk_fma_f32 v[154:155], v[78:79], v[10:11], v[154:155]
	v_pk_fma_f32 v[148:149], v[44:45], v[12:13], v[148:149]
	v_pk_fma_f32 v[150:151], v[46:47], v[14:15], v[150:151]
	v_pk_fma_f32 v[152:153], v[48:49], v[12:13], v[152:153]
	v_pk_fma_f32 v[154:155], v[50:51], v[14:15], v[154:155]
	v_pk_fma_f32 v[148:149], v[60:61], v[16:17], v[148:149]
	v_pk_fma_f32 v[150:151], v[62:63], v[18:19], v[150:151]
	v_pk_fma_f32 v[152:153], v[64:65], v[16:17], v[152:153]
	v_pk_fma_f32 v[154:155], v[66:67], v[18:19], v[154:155]
	v_pk_fma_f32 v[148:149], v[76:77], v[20:21], v[148:149]
	v_pk_fma_f32 v[150:151], v[78:79], v[22:23], v[150:151]
	v_pk_fma_f32 v[152:153], v[80:81], v[20:21], v[152:153]
	v_pk_fma_f32 v[154:155], v[82:83], v[22:23], v[154:155]
	v_pk_fma_f32 v[148:149], v[48:49], v[24:25], v[148:149]
	v_pk_fma_f32 v[150:151], v[50:51], v[26:27], v[150:151]
	v_pk_fma_f32 v[152:153], v[52:53], v[24:25], v[152:153]
	v_pk_fma_f32 v[154:155], v[54:55], v[26:27], v[154:155]
	v_pk_fma_f32 v[148:149], v[64:65], v[28:29], v[148:149]
	v_pk_fma_f32 v[150:151], v[66:67], v[30:31], v[150:151]
	v_pk_fma_f32 v[152:153], v[68:69], v[28:29], v[152:153]
	v_pk_fma_f32 v[154:155], v[70:71], v[30:31], v[154:155]
	v_pk_fma_f32 v[148:149], v[80:81], v[32:33], v[148:149]
	v_pk_fma_f32 v[150:151], v[82:83], v[34:35], v[150:151]
	v_pk_fma_f32 v[152:153], v[84:85], v[32:33], v[152:153]
	v_pk_fma_f32 v[154:155], v[86:87], v[34:35], v[154:155]
	v_and_b32_e32 v156, 0x7fffffff, v148
	v_and_b32_e32 v157, 0x7fffffff, v149
	v_and_b32_e32 v158, 0x7fffffff, v150
	v_and_b32_e32 v159, 0x7fffffff, v151
	v_and_b32_e32 v160, 0x7fffffff, v152
	v_and_b32_e32 v161, 0x7fffffff, v153
	v_and_b32_e32 v162, 0x7fffffff, v154
	v_and_b32_e32 v163, 0x7fffffff, v155
	v_pk_fma_f32 v[164:165], v[156:157], v[184:185], v[186:187]
	v_pk_fma_f32 v[166:167], v[158:159], v[184:185], v[186:187]
	v_pk_fma_f32 v[168:169], v[160:161], v[184:185], v[186:187]
	v_pk_fma_f32 v[170:171], v[162:163], v[184:185], v[186:187]
	v_rcp_f32_e32 v164, v164
	v_rcp_f32_e32 v165, v165
	v_rcp_f32_e32 v166, v166
	v_rcp_f32_e32 v167, v167
	v_rcp_f32_e32 v168, v168
	v_rcp_f32_e32 v169, v169
	v_rcp_f32_e32 v170, v170
	v_rcp_f32_e32 v171, v171
	v_pk_fma_f32 v[172:173], v[164:165], v[188:189], v[190:191]
	v_pk_fma_f32 v[174:175], v[166:167], v[188:189], v[190:191]
	v_pk_fma_f32 v[176:177], v[168:169], v[188:189], v[190:191]
	v_pk_fma_f32 v[178:179], v[170:171], v[188:189], v[190:191]
	v_pk_fma_f32 v[172:173], v[172:173], v[164:165], v[192:193]
	v_pk_fma_f32 v[174:175], v[174:175], v[166:167], v[192:193]
	v_pk_fma_f32 v[176:177], v[176:177], v[168:169], v[192:193]
	v_pk_fma_f32 v[178:179], v[178:179], v[170:171], v[192:193]
	v_pk_fma_f32 v[172:173], v[172:173], v[164:165], v[194:195]
	v_pk_fma_f32 v[174:175], v[174:175], v[166:167], v[194:195]
	v_pk_fma_f32 v[176:177], v[176:177], v[168:169], v[194:195]
	v_pk_fma_f32 v[178:179], v[178:179], v[170:171], v[194:195]
	v_pk_fma_f32 v[172:173], v[172:173], v[164:165], v[196:197]
	v_pk_fma_f32 v[174:175], v[174:175], v[166:167], v[196:197]
	v_pk_fma_f32 v[176:177], v[176:177], v[168:169], v[196:197]
	v_pk_fma_f32 v[178:179], v[178:179], v[170:171], v[196:197]
	v_pk_mul_f32 v[172:173], v[172:173], v[164:165]
	v_pk_mul_f32 v[174:175], v[174:175], v[166:167]
	v_pk_mul_f32 v[176:177], v[176:177], v[168:169]
	v_pk_mul_f32 v[178:179], v[178:179], v[170:171]
	v_pk_mul_f32 v[164:165], v[148:149], v[148:149]
	v_pk_mul_f32 v[166:167], v[150:151], v[150:151]
	v_pk_mul_f32 v[168:169], v[152:153], v[152:153]
	v_pk_mul_f32 v[170:171], v[154:155], v[154:155]
	v_pk_mul_f32 v[164:165], v[164:165], v[198:199]
	v_pk_mul_f32 v[166:167], v[166:167], v[198:199]
	v_pk_mul_f32 v[168:169], v[168:169], v[198:199]
	v_pk_mul_f32 v[170:171], v[170:171], v[198:199]
	v_exp_f32_e32 v164, v164
	v_exp_f32_e32 v165, v165
	v_exp_f32_e32 v166, v166
	v_exp_f32_e32 v167, v167
	v_exp_f32_e32 v168, v168
	v_exp_f32_e32 v169, v169
	v_exp_f32_e32 v170, v170
	v_exp_f32_e32 v171, v171
	v_pk_mul_f32 v[172:173], v[172:173], v[164:165]
	v_pk_mul_f32 v[174:175], v[174:175], v[166:167]
; __device__ __forceinline__ unsigned cvt_pk_bf16(float lo, float hi) { unsigned r; asm volatile("v_cvt_pk_bf16_f32 %0, %1, %2" : "=v"(r) : "v"(lo), "v"(hi)); return r; }
; __device__ __forceinline__ void phase_conv(KP p, int l, int tid) {
;     ...
;       for (int q = 0; q < CB; ++q) { const int col = jb + q + 1; const int cl = col > 63 ? 63 : col;
; #pragma unroll
;         for (int di = 0; di < RB + 2; ++di) an[q][di] = *(const u32x2*)(rowp[di] + (size_t)cl * DFF);
; #pragma unroll
;         for (int rr = 0; rr < RB; ++rr) ur[q][rr] = *(const u32x2*)(U + (size_t)((r0 + rr) * 64 + jb + q) * DFF + c0); }
;     ...
;             o[k] = gelu_as(a) * uv[k];
;           }
;           u32x2 ow; ow.x = cvt_pk_bf16(o[0], o[1]); ow.y = cvt_pk_bf16(o[2], o[3]);
;           *(u32x2*)(G + (size_t)((r0 + rr) * 64 + jb + q) * DFF + c0) = ow;
	v_pk_mul_f32 v[176:177], v[176:177], v[168:169]
	v_pk_mul_f32 v[178:179], v[178:179], v[170:171]
	v_pk_mul_f32 v[172:173], v[156:157], v[172:173]
	v_pk_mul_f32 v[174:175], v[158:159], v[174:175]
	v_pk_mul_f32 v[176:177], v[160:161], v[176:177]
	v_pk_mul_f32 v[178:179], v[162:163], v[178:179]
	v_max_f32_e32 v164, 0, v148
	v_max_f32_e32 v165, 0, v149
	v_max_f32_e32 v166, 0, v150
	v_max_f32_e32 v167, 0, v151
	v_max_f32_e32 v168, 0, v152
	v_max_f32_e32 v169, 0, v153
	v_max_f32_e32 v170, 0, v154
	v_max_f32_e32 v171, 0, v155
	v_pk_add_f32 v[164:165], v[164:165], v[172:173] neg_lo:[0,1] neg_hi:[0,1]
	v_pk_add_f32 v[166:167], v[166:167], v[174:175] neg_lo:[0,1] neg_hi:[0,1]
	v_pk_add_f32 v[168:169], v[168:169], v[176:177] neg_lo:[0,1] neg_hi:[0,1]
	v_pk_add_f32 v[170:171], v[170:171], v[178:179] neg_lo:[0,1] neg_hi:[0,1]
	v_pk_mul_f32 v[164:165], v[164:165], v[124:125]
	v_pk_mul_f32 v[166:167], v[166:167], v[126:127]
	v_pk_mul_f32 v[168:169], v[168:169], v[128:129]
	v_pk_mul_f32 v[170:171], v[170:171], v[130:131]
	v_cvt_pk_bf16_f32 v156, v164, v165
	v_cvt_pk_bf16_f32 v157, v166, v167
	v_cvt_pk_bf16_f32 v158, v168, v169
	v_cvt_pk_bf16_f32 v159, v170, v171
	global_store_dwordx2 v216, v[156:157], s[10:11]
	global_store_dwordx2 v217, v[158:159], s[10:11]
	v_add_u32_e32 v210, 0x2c00, v210
	v_add_u32_e32 v211, 0x2c00, v210
	v_add_u32_e32 v212, v206, v211
	global_load_dwordx2 v[88:89], v212, s[6:7]
	v_add_u32_e32 v213, v207, v211
	global_load_dwordx2 v[90:91], v213, s[6:7]
	v_add_u32_e32 v214, v208, v211
	global_load_dwordx2 v[92:93], v214, s[6:7]
	v_add_u32_e32 v215, v209, v211
	global_load_dwordx2 v[94:95], v215, s[6:7]
	v_add_u32_e32 v216, v207, v210
	global_load_dwordx2 v[112:113], v216, s[8:9] nt
	v_add_u32_e32 v217, v208, v210
	global_load_dwordx2 v[114:115], v217, s[8:9] nt
	s_waitcnt vmcnt(14)
	v_lshlrev_b32_e32 v40, 16, v96
	v_and_b32_e32 v41, 0xffff0000, v96
	v_lshlrev_b32_e32 v42, 16, v97
	v_and_b32_e32 v43, 0xffff0000, v97
	v_lshlrev_b32_e32 v44, 16, v98
	v_and_b32_e32 v45, 0xffff0000, v98
	v_lshlrev_b32_e32 v46, 16, v99
	v_and_b32_e32 v47, 0xffff0000, v99
	v_lshlrev_b32_e32 v48, 16, v100
	v_and_b32_e32 v49, 0xffff0000, v100
	v_lshlrev_b32_e32 v50, 16, v101
	v_and_b32_e32 v51, 0xffff0000, v101
	v_lshlrev_b32_e32 v52, 16, v102
	v_and_b32_e32 v53, 0xffff0000, v102
	v_lshlrev_b32_e32 v54, 16, v103
	v_and_b32_e32 v55, 0xffff0000, v103
	v_pk_mul_f32 v[40:41], v[40:41], v[200:201]
	v_pk_mul_f32 v[42:43], v[42:43], v[200:201]
	v_pk_mul_f32 v[52:53], v[52:53], v[202:203]
	v_pk_mul_f32 v[54:55], v[54:55], v[202:203]
	v_lshlrev_b32_e32 v124, 16, v116
	v_and_b32_e32 v125, 0xffff0000, v116
	v_lshlrev_b32_e32 v126, 16, v117
	v_and_b32_e32 v127, 0xffff0000, v117
	v_lshlrev_b32_e32 v128, 16, v118
	v_and_b32_e32 v129, 0xffff0000, v118
	v_lshlrev_b32_e32 v130, 16, v119
	v_and_b32_e32 v131, 0xffff0000, v119
	v_pk_fma_f32 v[148:149], v[56:57], v[0:1], v[36:37]
	v_pk_fma_f32 v[150:151], v[58:59], v[2:3], v[38:39]
	v_pk_fma_f32 v[152:153], v[60:61], v[0:1], v[36:37]
	v_pk_fma_f32 v[154:155], v[62:63], v[2:3], v[38:39]
	v_pk_fma_f32 v[148:149], v[72:73], v[4:5], v[148:149]
	v_pk_fma_f32 v[150:151], v[74:75], v[6:7], v[150:151]
	v_pk_fma_f32 v[152:153], v[76:77], v[4:5], v[152:153]
	v_pk_fma_f32 v[154:155], v[78:79], v[6:7], v[154:155]
	v_pk_fma_f32 v[148:149], v[40:41], v[8:9], v[148:149]
	v_pk_fma_f32 v[150:151], v[42:43], v[10:11], v[150:151]
	v_pk_fma_f32 v[152:153], v[44:45], v[8:9], v[152:153]
	v_pk_fma_f32 v[154:155], v[46:47], v[10:11], v[154:155]
	v_pk_fma_f32 v[148:149], v[60:61], v[12:13], v[148:149]
	v_pk_fma_f32 v[150:151], v[62:63], v[14:15], v[150:151]
	v_pk_fma_f32 v[152:153], v[64:65], v[12:13], v[152:153]
	v_pk_fma_f32 v[154:155], v[66:67], v[14:15], v[154:155]
	v_pk_fma_f32 v[148:149], v[76:77], v[16:17], v[148:149]
	v_pk_fma_f32 v[150:151], v[78:79], v[18:19], v[150:151]
	v_pk_fma_f32 v[152:153], v[80:81], v[16:17], v[152:153]
	v_pk_fma_f32 v[154:155], v[82:83], v[18:19], v[154:155]
	v_pk_fma_f32 v[148:149], v[44:45], v[20:21], v[148:149]
	v_pk_fma_f32 v[150:151], v[46:47], v[22:23], v[150:151]
	v_pk_fma_f32 v[152:153], v[48:49], v[20:21], v[152:153]
	v_pk_fma_f32 v[154:155], v[50:51], v[22:23], v[154:155]
	v_pk_fma_f32 v[148:149], v[64:65], v[24:25], v[148:149]
	v_pk_fma_f32 v[150:151], v[66:67], v[26:27], v[150:151]
	v_pk_fma_f32 v[152:153], v[68:69], v[24:25], v[152:153]
	v_pk_fma_f32 v[154:155], v[70:71], v[26:27], v[154:155]
	v_pk_fma_f32 v[148:149], v[80:81], v[28:29], v[148:149]
	v_pk_fma_f32 v[150:151], v[82:83], v[30:31], v[150:151]
	v_pk_fma_f32 v[152:153], v[84:85], v[28:29], v[152:153]
	v_pk_fma_f32 v[154:155], v[86:87], v[30:31], v[154:155]
	v_pk_fma_f32 v[148:149], v[48:49], v[32:33], v[148:149]
	v_pk_fma_f32 v[150:151], v[50:51], v[34:35], v[150:151]
	v_pk_fma_f32 v[152:153], v[52:53], v[32:33], v[152:153]
	v_pk_fma_f32 v[154:155], v[54:55], v[34:35], v[154:155]
	v_and_b32_e32 v156, 0x7fffffff, v148
	v_and_b32_e32 v157, 0x7fffffff, v149
	v_and_b32_e32 v158, 0x7fffffff, v150
	v_and_b32_e32 v159, 0x7fffffff, v151
	v_and_b32_e32 v160, 0x7fffffff, v152
	v_and_b32_e32 v161, 0x7fffffff, v153
	v_and_b32_e32 v162, 0x7fffffff, v154
	v_and_b32_e32 v163, 0x7fffffff, v155
	v_pk_fma_f32 v[164:165], v[156:157], v[184:185], v[186:187]
	v_pk_fma_f32 v[166:167], v[158:159], v[184:185], v[186:187]
	v_pk_fma_f32 v[168:169], v[160:161], v[184:185], v[186:187]
	v_pk_fma_f32 v[170:171], v[162:163], v[184:185], v[186:187]
	v_rcp_f32_e32 v164, v164
	v_rcp_f32_e32 v165, v165
	v_rcp_f32_e32 v166, v166
	v_rcp_f32_e32 v167, v167
	v_rcp_f32_e32 v168, v168
	v_rcp_f32_e32 v169, v169
	v_rcp_f32_e32 v170, v170
	v_rcp_f32_e32 v171, v171
; __device__ __forceinline__ unsigned cvt_pk_bf16(float lo, float hi) { unsigned r; asm volatile("v_cvt_pk_bf16_f32 %0, %1, %2" : "=v"(r) : "v"(lo), "v"(hi)); return r; }
; __device__ __forceinline__ void phase_conv(KP p, int l, int tid) {
;     ...
;       for (int q = 0; q < CB; ++q) { const int col = jb + q + 1; const int cl = col > 63 ? 63 : col;
; #pragma unroll
;         for (int di = 0; di < RB + 2; ++di) an[q][di] = *(const u32x2*)(rowp[di] + (size_t)cl * DFF);
; #pragma unroll
;         for (int rr = 0; rr < RB; ++rr) ur[q][rr] = *(const u32x2*)(U + (size_t)((r0 + rr) * 64 + jb + q) * DFF + c0); }
;     ...
;           for (int k = 0; k < 4; ++k) {
;             float a = bsv[k];
; #pragma unroll
;             for (int di = 0; di < 3; ++di)
; #pragma unroll
;               for (int dj = 0; dj < 3; ++dj) a += win[dj][rr + di][k] * w[di * 3 + dj][k];
;             o[k] = gelu_as(a) * uv[k];
;           }
;           u32x2 ow; ow.x = cvt_pk_bf16(o[0], o[1]); ow.y = cvt_pk_bf16(o[2], o[3]);
;           *(u32x2*)(G + (size_t)((r0 + rr) * 64 + jb + q) * DFF + c0) = ow;
	v_pk_fma_f32 v[172:173], v[164:165], v[188:189], v[190:191]
	v_pk_fma_f32 v[174:175], v[166:167], v[188:189], v[190:191]
	v_pk_fma_f32 v[176:177], v[168:169], v[188:189], v[190:191]
	v_pk_fma_f32 v[178:179], v[170:171], v[188:189], v[190:191]
	v_pk_fma_f32 v[172:173], v[172:173], v[164:165], v[192:193]
	v_pk_fma_f32 v[174:175], v[174:175], v[166:167], v[192:193]
	v_pk_fma_f32 v[176:177], v[176:177], v[168:169], v[192:193]
	v_pk_fma_f32 v[178:179], v[178:179], v[170:171], v[192:193]
	v_pk_fma_f32 v[172:173], v[172:173], v[164:165], v[194:195]
	v_pk_fma_f32 v[174:175], v[174:175], v[166:167], v[194:195]
	v_pk_fma_f32 v[176:177], v[176:177], v[168:169], v[194:195]
	v_pk_fma_f32 v[178:179], v[178:179], v[170:171], v[194:195]
	v_pk_fma_f32 v[172:173], v[172:173], v[164:165], v[196:197]
	v_pk_fma_f32 v[174:175], v[174:175], v[166:167], v[196:197]
	v_pk_fma_f32 v[176:177], v[176:177], v[168:169], v[196:197]
	v_pk_fma_f32 v[178:179], v[178:179], v[170:171], v[196:197]
	v_pk_mul_f32 v[172:173], v[172:173], v[164:165]
	v_pk_mul_f32 v[174:175], v[174:175], v[166:167]
	v_pk_mul_f32 v[176:177], v[176:177], v[168:169]
	v_pk_mul_f32 v[178:179], v[178:179], v[170:171]
	v_pk_mul_f32 v[164:165], v[148:149], v[148:149]
	v_pk_mul_f32 v[166:167], v[150:151], v[150:151]
	v_pk_mul_f32 v[168:169], v[152:153], v[152:153]
	v_pk_mul_f32 v[170:171], v[154:155], v[154:155]
	v_pk_mul_f32 v[164:165], v[164:165], v[198:199]
	v_pk_mul_f32 v[166:167], v[166:167], v[198:199]
	v_pk_mul_f32 v[168:169], v[168:169], v[198:199]
	v_pk_mul_f32 v[170:171], v[170:171], v[198:199]
	v_exp_f32_e32 v164, v164
	v_exp_f32_e32 v165, v165
	v_exp_f32_e32 v166, v166
	v_exp_f32_e32 v167, v167
	v_exp_f32_e32 v168, v168
	v_exp_f32_e32 v169, v169
	v_exp_f32_e32 v170, v170
	v_exp_f32_e32 v171, v171
	v_pk_mul_f32 v[172:173], v[172:173], v[164:165]
	v_pk_mul_f32 v[174:175], v[174:175], v[166:167]
	v_pk_mul_f32 v[176:177], v[176:177], v[168:169]
	v_pk_mul_f32 v[178:179], v[178:179], v[170:171]
	v_pk_mul_f32 v[172:173], v[156:157], v[172:173]
	v_pk_mul_f32 v[174:175], v[158:159], v[174:175]
	v_pk_mul_f32 v[176:177], v[160:161], v[176:177]
	v_pk_mul_f32 v[178:179], v[162:163], v[178:179]
	v_max_f32_e32 v164, 0, v148
	v_max_f32_e32 v165, 0, v149
	v_max_f32_e32 v166, 0, v150
	v_max_f32_e32 v167, 0, v151
	v_max_f32_e32 v168, 0, v152
	v_max_f32_e32 v169, 0, v153
	v_max_f32_e32 v170, 0, v154
	v_max_f32_e32 v171, 0, v155
	v_pk_add_f32 v[164:165], v[164:165], v[172:173] neg_lo:[0,1] neg_hi:[0,1]
	v_pk_add_f32 v[166:167], v[166:167], v[174:175] neg_lo:[0,1] neg_hi:[0,1]
	v_pk_add_f32 v[168:169], v[168:169], v[176:177] neg_lo:[0,1] neg_hi:[0,1]
	v_pk_add_f32 v[170:171], v[170:171], v[178:179] neg_lo:[0,1] neg_hi:[0,1]
	v_pk_mul_f32 v[164:165], v[164:165], v[124:125]
	v_pk_mul_f32 v[166:167], v[166:167], v[126:127]
	v_pk_mul_f32 v[168:169], v[168:169], v[128:129]
	v_pk_mul_f32 v[170:171], v[170:171], v[130:131]
	v_cvt_pk_bf16_f32 v156, v164, v165
	v_cvt_pk_bf16_f32 v157, v166, v167
	v_cvt_pk_bf16_f32 v158, v168, v169
	v_cvt_pk_bf16_f32 v159, v170, v171
	global_store_dwordx2 v218, v[156:157], s[10:11]
	global_store_dwordx2 v219, v[158:159], s[10:11]
	v_add_u32_e32 v210, 0x2c00, v210
	v_add_u32_e32 v211, 0x2c00, v210
	v_add_u32_e32 v212, v206, v211
	global_load_dwordx2 v[96:97], v212, s[6:7]
	v_add_u32_e32 v213, v207, v211
	global_load_dwordx2 v[98:99], v213, s[6:7]
	v_add_u32_e32 v214, v208, v211
	global_load_dwordx2 v[100:101], v214, s[6:7]
	v_add_u32_e32 v215, v209, v211
	global_load_dwordx2 v[102:103], v215, s[6:7]
	v_add_u32_e32 v218, v207, v210
	global_load_dwordx2 v[116:117], v218, s[8:9] nt
	v_add_u32_e32 v219, v208, v210
	global_load_dwordx2 v[118:119], v219, s[8:9] nt
	s_waitcnt vmcnt(16)
	v_lshlrev_b32_e32 v56, 16, v104
	v_and_b32_e32 v57, 0xffff0000, v104
	v_lshlrev_b32_e32 v58, 16, v105
	v_and_b32_e32 v59, 0xffff0000, v105
	v_lshlrev_b32_e32 v60, 16, v106
	v_and_b32_e32 v61, 0xffff0000, v106
	v_lshlrev_b32_e32 v62, 16, v107
	v_and_b32_e32 v63, 0xffff0000, v107
	v_lshlrev_b32_e32 v64, 16, v108
	v_and_b32_e32 v65, 0xffff0000, v108
	v_lshlrev_b32_e32 v66, 16, v109
	v_and_b32_e32 v67, 0xffff0000, v109
	v_lshlrev_b32_e32 v68, 16, v110
	v_and_b32_e32 v69, 0xffff0000, v110
	v_lshlrev_b32_e32 v70, 16, v111
	v_and_b32_e32 v71, 0xffff0000, v111
	v_pk_mul_f32 v[56:57], v[56:57], v[200:201]
	v_pk_mul_f32 v[58:59], v[58:59], v[200:201]
	v_pk_mul_f32 v[68:69], v[68:69], v[202:203]
	v_pk_mul_f32 v[70:71], v[70:71], v[202:203]
	v_lshlrev_b32_e32 v124, 16, v120
	v_and_b32_e32 v125, 0xffff0000, v120
	v_lshlrev_b32_e32 v126, 16, v121
	v_and_b32_e32 v127, 0xffff0000, v121
	v_lshlrev_b32_e32 v128, 16, v122
	v_and_b32_e32 v129, 0xffff0000, v122
	v_lshlrev_b32_e32 v130, 16, v123
	v_and_b32_e32 v131, 0xffff0000, v123
	v_pk_fma_f32 v[148:149], v[72:73], v[0:1], v[36:37]
	v_pk_fma_f32 v[150:151], v[74:75], v[2:3], v[38:39]
	v_pk_fma_f32 v[152:153], v[76:77], v[0:1], v[36:37]
	v_pk_fma_f32 v[154:155], v[78:79], v[2:3], v[38:39]
	v_pk_fma_f32 v[148:149], v[40:41], v[4:5], v[148:149]
	v_pk_fma_f32 v[150:151], v[42:43], v[6:7], v[150:151]
	v_pk_fma_f32 v[152:153], v[44:45], v[4:5], v[152:153]
	v_pk_fma_f32 v[154:155], v[46:47], v[6:7], v[154:155]
	v_pk_fma_f32 v[148:149], v[56:57], v[8:9], v[148:149]
	v_pk_fma_f32 v[150:151], v[58:59], v[10:11], v[150:151]
	v_pk_fma_f32 v[152:153], v[60:61], v[8:9], v[152:153]
	v_pk_fma_f32 v[154:155], v[62:63], v[10:11], v[154:155]
	v_pk_fma_f32 v[148:149], v[76:77], v[12:13], v[148:149]
	v_pk_fma_f32 v[150:151], v[78:79], v[14:15], v[150:151]
	v_pk_fma_f32 v[152:153], v[80:81], v[12:13], v[152:153]
	v_pk_fma_f32 v[154:155], v[82:83], v[14:15], v[154:155]
	v_pk_fma_f32 v[148:149], v[44:45], v[16:17], v[148:149]
; __device__ __forceinline__ unsigned cvt_pk_bf16(float lo, float hi) { unsigned r; asm volatile("v_cvt_pk_bf16_f32 %0, %1, %2" : "=v"(r) : "v"(lo), "v"(hi)); return r; }
; __device__ __forceinline__ void phase_conv(KP p, int l, int tid) {
;     ...
;       for (int q = 0; q < CB; ++q) { const int col = jb + q + 1; const int cl = col > 63 ? 63 : col;
; #pragma unroll
;         for (int di = 0; di < RB + 2; ++di) an[q][di] = *(const u32x2*)(rowp[di] + (size_t)cl * DFF);
; #pragma unroll
;         for (int rr = 0; rr < RB; ++rr) ur[q][rr] = *(const u32x2*)(U + (size_t)((r0 + rr) * 64 + jb + q) * DFF + c0); }
;     ...
;           for (int k = 0; k < 4; ++k) {
;             float a = bsv[k];
; #pragma unroll
;             for (int di = 0; di < 3; ++di)
; #pragma unroll
;               for (int dj = 0; dj < 3; ++dj) a += win[dj][rr + di][k] * w[di * 3 + dj][k];
;             o[k] = gelu_as(a) * uv[k];
;           }
;           u32x2 ow; ow.x = cvt_pk_bf16(o[0], o[1]); ow.y = cvt_pk_bf16(o[2], o[3]);
;           *(u32x2*)(G + (size_t)((r0 + rr) * 64 + jb + q) * DFF + c0) = ow;
	v_pk_fma_f32 v[150:151], v[46:47], v[18:19], v[150:151]
	v_pk_fma_f32 v[152:153], v[48:49], v[16:17], v[152:153]
	v_pk_fma_f32 v[154:155], v[50:51], v[18:19], v[154:155]
	v_pk_fma_f32 v[148:149], v[60:61], v[20:21], v[148:149]
	v_pk_fma_f32 v[150:151], v[62:63], v[22:23], v[150:151]
	v_pk_fma_f32 v[152:153], v[64:65], v[20:21], v[152:153]
	v_pk_fma_f32 v[154:155], v[66:67], v[22:23], v[154:155]
	v_pk_fma_f32 v[148:149], v[80:81], v[24:25], v[148:149]
	v_pk_fma_f32 v[150:151], v[82:83], v[26:27], v[150:151]
	v_pk_fma_f32 v[152:153], v[84:85], v[24:25], v[152:153]
	v_pk_fma_f32 v[154:155], v[86:87], v[26:27], v[154:155]
	v_pk_fma_f32 v[148:149], v[48:49], v[28:29], v[148:149]
	v_pk_fma_f32 v[150:151], v[50:51], v[30:31], v[150:151]
	v_pk_fma_f32 v[152:153], v[52:53], v[28:29], v[152:153]
	v_pk_fma_f32 v[154:155], v[54:55], v[30:31], v[154:155]
	v_pk_fma_f32 v[148:149], v[64:65], v[32:33], v[148:149]
	v_pk_fma_f32 v[150:151], v[66:67], v[34:35], v[150:151]
	v_pk_fma_f32 v[152:153], v[68:69], v[32:33], v[152:153]
	v_pk_fma_f32 v[154:155], v[70:71], v[34:35], v[154:155]
	v_and_b32_e32 v156, 0x7fffffff, v148
	v_and_b32_e32 v157, 0x7fffffff, v149
	v_and_b32_e32 v158, 0x7fffffff, v150
	v_and_b32_e32 v159, 0x7fffffff, v151
	v_and_b32_e32 v160, 0x7fffffff, v152
	v_and_b32_e32 v161, 0x7fffffff, v153
	v_and_b32_e32 v162, 0x7fffffff, v154
	v_and_b32_e32 v163, 0x7fffffff, v155
	v_pk_fma_f32 v[164:165], v[156:157], v[184:185], v[186:187]
	v_pk_fma_f32 v[166:167], v[158:159], v[184:185], v[186:187]
	v_pk_fma_f32 v[168:169], v[160:161], v[184:185], v[186:187]
	v_pk_fma_f32 v[170:171], v[162:163], v[184:185], v[186:187]
	v_rcp_f32_e32 v164, v164
	v_rcp_f32_e32 v165, v165
	v_rcp_f32_e32 v166, v166
	v_rcp_f32_e32 v167, v167
	v_rcp_f32_e32 v168, v168
	v_rcp_f32_e32 v169, v169
	v_rcp_f32_e32 v170, v170
	v_rcp_f32_e32 v171, v171
	v_pk_fma_f32 v[172:173], v[164:165], v[188:189], v[190:191]
	v_pk_fma_f32 v[174:175], v[166:167], v[188:189], v[190:191]
	v_pk_fma_f32 v[176:177], v[168:169], v[188:189], v[190:191]
	v_pk_fma_f32 v[178:179], v[170:171], v[188:189], v[190:191]
	v_pk_fma_f32 v[172:173], v[172:173], v[164:165], v[192:193]
	v_pk_fma_f32 v[174:175], v[174:175], v[166:167], v[192:193]
	v_pk_fma_f32 v[176:177], v[176:177], v[168:169], v[192:193]
	v_pk_fma_f32 v[178:179], v[178:179], v[170:171], v[192:193]
	v_pk_fma_f32 v[172:173], v[172:173], v[164:165], v[194:195]
	v_pk_fma_f32 v[174:175], v[174:175], v[166:167], v[194:195]
	v_pk_fma_f32 v[176:177], v[176:177], v[168:169], v[194:195]
	v_pk_fma_f32 v[178:179], v[178:179], v[170:171], v[194:195]
	v_pk_fma_f32 v[172:173], v[172:173], v[164:165], v[196:197]
	v_pk_fma_f32 v[174:175], v[174:175], v[166:167], v[196:197]
	v_pk_fma_f32 v[176:177], v[176:177], v[168:169], v[196:197]
	v_pk_fma_f32 v[178:179], v[178:179], v[170:171], v[196:197]
	v_pk_mul_f32 v[172:173], v[172:173], v[164:165]
	v_pk_mul_f32 v[174:175], v[174:175], v[166:167]
	v_pk_mul_f32 v[176:177], v[176:177], v[168:169]
	v_pk_mul_f32 v[178:179], v[178:179], v[170:171]
	v_pk_mul_f32 v[164:165], v[148:149], v[148:149]
	v_pk_mul_f32 v[166:167], v[150:151], v[150:151]
	v_pk_mul_f32 v[168:169], v[152:153], v[152:153]
	v_pk_mul_f32 v[170:171], v[154:155], v[154:155]
	v_pk_mul_f32 v[164:165], v[164:165], v[198:199]
	v_pk_mul_f32 v[166:167], v[166:167], v[198:199]
	v_pk_mul_f32 v[168:169], v[168:169], v[198:199]
	v_pk_mul_f32 v[170:171], v[170:171], v[198:199]
	v_exp_f32_e32 v164, v164
	v_exp_f32_e32 v165, v165
	v_exp_f32_e32 v166, v166
	v_exp_f32_e32 v167, v167
	v_exp_f32_e32 v168, v168
	v_exp_f32_e32 v169, v169
	v_exp_f32_e32 v170, v170
	v_exp_f32_e32 v171, v171
	v_pk_mul_f32 v[172:173], v[172:173], v[164:165]
	v_pk_mul_f32 v[174:175], v[174:175], v[166:167]
	v_pk_mul_f32 v[176:177], v[176:177], v[168:169]
	v_pk_mul_f32 v[178:179], v[178:179], v[170:171]
	v_pk_mul_f32 v[172:173], v[156:157], v[172:173]
	v_pk_mul_f32 v[174:175], v[158:159], v[174:175]
	v_pk_mul_f32 v[176:177], v[160:161], v[176:177]
	v_pk_mul_f32 v[178:179], v[162:163], v[178:179]
	v_max_f32_e32 v164, 0, v148
	v_max_f32_e32 v165, 0, v149
	v_max_f32_e32 v166, 0, v150
	v_max_f32_e32 v167, 0, v151
	v_max_f32_e32 v168, 0, v152
	v_max_f32_e32 v169, 0, v153
	v_max_f32_e32 v170, 0, v154
	v_max_f32_e32 v171, 0, v155
	v_pk_add_f32 v[164:165], v[164:165], v[172:173] neg_lo:[0,1] neg_hi:[0,1]
	v_pk_add_f32 v[166:167], v[166:167], v[174:175] neg_lo:[0,1] neg_hi:[0,1]
	v_pk_add_f32 v[168:169], v[168:169], v[176:177] neg_lo:[0,1] neg_hi:[0,1]
	v_pk_add_f32 v[170:171], v[170:171], v[178:179] neg_lo:[0,1] neg_hi:[0,1]
	v_pk_mul_f32 v[164:165], v[164:165], v[124:125]
	v_pk_mul_f32 v[166:167], v[166:167], v[126:127]
	v_pk_mul_f32 v[168:169], v[168:169], v[128:129]
	v_pk_mul_f32 v[170:171], v[170:171], v[130:131]
	v_cvt_pk_bf16_f32 v156, v164, v165
	v_cvt_pk_bf16_f32 v157, v166, v167
	v_cvt_pk_bf16_f32 v158, v168, v169
	v_cvt_pk_bf16_f32 v159, v170, v171
	global_store_dwordx2 v220, v[156:157], s[10:11]
	global_store_dwordx2 v221, v[158:159], s[10:11]
	v_add_u32_e32 v210, 0x2c00, v210
	v_add_u32_e32 v211, 0x2c00, v210
	v_add_u32_e32 v212, v206, v211
	global_load_dwordx2 v[104:105], v212, s[6:7]
	v_add_u32_e32 v213, v207, v211
	global_load_dwordx2 v[106:107], v213, s[6:7]
	v_add_u32_e32 v214, v208, v211
	global_load_dwordx2 v[108:109], v214, s[6:7]
	v_add_u32_e32 v215, v209, v211
	global_load_dwordx2 v[110:111], v215, s[6:7]
	v_add_u32_e32 v220, v207, v210
	global_load_dwordx2 v[120:121], v220, s[8:9] nt
	v_add_u32_e32 v221, v208, v210
	global_load_dwordx2 v[122:123], v221, s[8:9] nt
	s_waitcnt vmcnt(16)
; __device__ __forceinline__ unsigned cvt_pk_bf16(float lo, float hi) { unsigned r; asm volatile("v_cvt_pk_bf16_f32 %0, %1, %2" : "=v"(r) : "v"(lo), "v"(hi)); return r; }
; __device__ __forceinline__ float gelu_as(float v) {
;   const float av = fabsf(v); const float t = __builtin_amdgcn_rcpf(av * 0.2316418882f + 1.0f);
;   float q = t * 0.5307027145f + (-0.7265760135f); q = q * t + 0.7107068705f; q = q * t + (-0.142248368f); q = q * t + 0.127414796f; q = q * t;
;   const float e = __builtin_amdgcn_exp2f((v * v) * (-0.72134752044f));
;   const float m = v * (q * e);
;   return v < 0.f ? m : v - m;
; __device__ __forceinline__ void phase_conv(KP p, int l, int tid) {
;     ...
;       for (int q = 0; q < CB; ++q) { const int col = jb + q + 1; const int cl = col > 63 ? 63 : col;
; #pragma unroll
;         for (int di = 0; di < RB + 2; ++di) an[q][di] = *(const u32x2*)(rowp[di] + (size_t)cl * DFF);
; #pragma unroll
;         for (int rr = 0; rr < RB; ++rr) ur[q][rr] = *(const u32x2*)(U + (size_t)((r0 + rr) * 64 + jb + q) * DFF + c0); }
;       __builtin_amdgcn_sched_barrier(0);
; #pragma unroll
;       for (int q = 0; q < CB; ++q) {
;         const int col = jb + q + 1;
; #pragma unroll
;         for (int di = 0; di < RB + 2; ++di) { const bool ok = rv[di] && (col < 64); unpack4(an[q][di], win[2][di]);
; #pragma unroll
;           for (int k = 0; k < 4; ++k) win[2][di][k] = ok ? win[2][di][k] : 0.f; }
; #pragma unroll
;         for (int rr = 0; rr < RB; ++rr) {
;           float uv[4]; unpack4(ur[q][rr], uv);
;           float o[4];
; #pragma unroll
;           for (int k = 0; k < 4; ++k) {
;             float a = bsv[k];
; #pragma unroll
;             for (int di = 0; di < 3; ++di)
; #pragma unroll
;               for (int dj = 0; dj < 3; ++dj) a += win[dj][rr + di][k] * w[di * 3 + dj][k];
;             o[k] = gelu_as(a) * uv[k];
;           }
;           u32x2 ow; ow.x = cvt_pk_bf16(o[0], o[1]); ow.y = cvt_pk_bf16(o[2], o[3]);
;           *(u32x2*)(G + (size_t)((r0 + rr) * 64 + jb + q) * DFF + c0) = ow;
;         }
	v_lshlrev_b32_e32 v72, 16, v88
	v_and_b32_e32 v73, 0xffff0000, v88
	v_lshlrev_b32_e32 v74, 16, v89
	v_and_b32_e32 v75, 0xffff0000, v89
	v_lshlrev_b32_e32 v76, 16, v90
	v_and_b32_e32 v77, 0xffff0000, v90
	v_lshlrev_b32_e32 v78, 16, v91
	v_and_b32_e32 v79, 0xffff0000, v91
	v_lshlrev_b32_e32 v80, 16, v92
	v_and_b32_e32 v81, 0xffff0000, v92
	v_lshlrev_b32_e32 v82, 16, v93
	v_and_b32_e32 v83, 0xffff0000, v93
	v_lshlrev_b32_e32 v84, 16, v94
	v_and_b32_e32 v85, 0xffff0000, v94
	v_lshlrev_b32_e32 v86, 16, v95
	v_and_b32_e32 v87, 0xffff0000, v95
	v_pk_mul_f32 v[72:73], v[72:73], v[200:201]
	v_pk_mul_f32 v[74:75], v[74:75], v[200:201]
	v_pk_mul_f32 v[84:85], v[84:85], v[202:203]
	v_pk_mul_f32 v[86:87], v[86:87], v[202:203]
	v_lshlrev_b32_e32 v124, 16, v112
	v_and_b32_e32 v125, 0xffff0000, v112
	v_lshlrev_b32_e32 v126, 16, v113
	v_and_b32_e32 v127, 0xffff0000, v113
	v_lshlrev_b32_e32 v128, 16, v114
	v_and_b32_e32 v129, 0xffff0000, v114
	v_lshlrev_b32_e32 v130, 16, v115
	v_and_b32_e32 v131, 0xffff0000, v115
	v_pk_fma_f32 v[148:149], v[40:41], v[0:1], v[36:37]
	v_pk_fma_f32 v[150:151], v[42:43], v[2:3], v[38:39]
	v_pk_fma_f32 v[152:153], v[44:45], v[0:1], v[36:37]
	v_pk_fma_f32 v[154:155], v[46:47], v[2:3], v[38:39]
	v_pk_fma_f32 v[148:149], v[56:57], v[4:5], v[148:149]
	v_pk_fma_f32 v[150:151], v[58:59], v[6:7], v[150:151]
	v_pk_fma_f32 v[152:153], v[60:61], v[4:5], v[152:153]
	v_pk_fma_f32 v[154:155], v[62:63], v[6:7], v[154:155]
	v_pk_fma_f32 v[148:149], v[72:73], v[8:9], v[148:149]
	v_pk_fma_f32 v[150:151], v[74:75], v[10:11], v[150:151]
	v_pk_fma_f32 v[152:153], v[76:77], v[8:9], v[152:153]
	v_pk_fma_f32 v[154:155], v[78:79], v[10:11], v[154:155]
	v_pk_fma_f32 v[148:149], v[44:45], v[12:13], v[148:149]
	v_pk_fma_f32 v[150:151], v[46:47], v[14:15], v[150:151]
	v_pk_fma_f32 v[152:153], v[48:49], v[12:13], v[152:153]
	v_pk_fma_f32 v[154:155], v[50:51], v[14:15], v[154:155]
	v_pk_fma_f32 v[148:149], v[60:61], v[16:17], v[148:149]
	v_pk_fma_f32 v[150:151], v[62:63], v[18:19], v[150:151]
	v_pk_fma_f32 v[152:153], v[64:65], v[16:17], v[152:153]
	v_pk_fma_f32 v[154:155], v[66:67], v[18:19], v[154:155]
	v_pk_fma_f32 v[148:149], v[76:77], v[20:21], v[148:149]
	v_pk_fma_f32 v[150:151], v[78:79], v[22:23], v[150:151]
	v_pk_fma_f32 v[152:153], v[80:81], v[20:21], v[152:153]
	v_pk_fma_f32 v[154:155], v[82:83], v[22:23], v[154:155]
	v_pk_fma_f32 v[148:149], v[48:49], v[24:25], v[148:149]
	v_pk_fma_f32 v[150:151], v[50:51], v[26:27], v[150:151]
	v_pk_fma_f32 v[152:153], v[52:53], v[24:25], v[152:153]
	v_pk_fma_f32 v[154:155], v[54:55], v[26:27], v[154:155]
	v_pk_fma_f32 v[148:149], v[64:65], v[28:29], v[148:149]
	v_pk_fma_f32 v[150:151], v[66:67], v[30:31], v[150:151]
	v_pk_fma_f32 v[152:153], v[68:69], v[28:29], v[152:153]
	v_pk_fma_f32 v[154:155], v[70:71], v[30:31], v[154:155]
	v_pk_fma_f32 v[148:149], v[80:81], v[32:33], v[148:149]
	v_pk_fma_f32 v[150:151], v[82:83], v[34:35], v[150:151]
	v_pk_fma_f32 v[152:153], v[84:85], v[32:33], v[152:153]
	v_pk_fma_f32 v[154:155], v[86:87], v[34:35], v[154:155]
	v_and_b32_e32 v156, 0x7fffffff, v148
	v_and_b32_e32 v157, 0x7fffffff, v149
	v_and_b32_e32 v158, 0x7fffffff, v150
	v_and_b32_e32 v159, 0x7fffffff, v151
	v_and_b32_e32 v160, 0x7fffffff, v152
	v_and_b32_e32 v161, 0x7fffffff, v153
	v_and_b32_e32 v162, 0x7fffffff, v154
	v_and_b32_e32 v163, 0x7fffffff, v155
	v_pk_fma_f32 v[164:165], v[156:157], v[184:185], v[186:187]
	v_pk_fma_f32 v[166:167], v[158:159], v[184:185], v[186:187]
	v_pk_fma_f32 v[168:169], v[160:161], v[184:185], v[186:187]
	v_pk_fma_f32 v[170:171], v[162:163], v[184:185], v[186:187]
	v_rcp_f32_e32 v164, v164
	v_rcp_f32_e32 v165, v165
	v_rcp_f32_e32 v166, v166
	v_rcp_f32_e32 v167, v167
	v_rcp_f32_e32 v168, v168
	v_rcp_f32_e32 v169, v169
	v_rcp_f32_e32 v170, v170
	v_rcp_f32_e32 v171, v171
	v_pk_fma_f32 v[172:173], v[164:165], v[188:189], v[190:191]
	v_pk_fma_f32 v[174:175], v[166:167], v[188:189], v[190:191]
	v_pk_fma_f32 v[176:177], v[168:169], v[188:189], v[190:191]
	v_pk_fma_f32 v[178:179], v[170:171], v[188:189], v[190:191]
	v_pk_fma_f32 v[172:173], v[172:173], v[164:165], v[192:193]
	v_pk_fma_f32 v[174:175], v[174:175], v[166:167], v[192:193]
	v_pk_fma_f32 v[176:177], v[176:177], v[168:169], v[192:193]
	v_pk_fma_f32 v[178:179], v[178:179], v[170:171], v[192:193]
	v_pk_fma_f32 v[172:173], v[172:173], v[164:165], v[194:195]
	v_pk_fma_f32 v[174:175], v[174:175], v[166:167], v[194:195]
	v_pk_fma_f32 v[176:177], v[176:177], v[168:169], v[194:195]
	v_pk_fma_f32 v[178:179], v[178:179], v[170:171], v[194:195]
	v_pk_fma_f32 v[172:173], v[172:173], v[164:165], v[196:197]
	v_pk_fma_f32 v[174:175], v[174:175], v[166:167], v[196:197]
	v_pk_fma_f32 v[176:177], v[176:177], v[168:169], v[196:197]
	v_pk_fma_f32 v[178:179], v[178:179], v[170:171], v[196:197]
	v_pk_mul_f32 v[172:173], v[172:173], v[164:165]
	v_pk_mul_f32 v[174:175], v[174:175], v[166:167]
	v_pk_mul_f32 v[176:177], v[176:177], v[168:169]
	v_pk_mul_f32 v[178:179], v[178:179], v[170:171]
	v_pk_mul_f32 v[164:165], v[148:149], v[148:149]
	v_pk_mul_f32 v[166:167], v[150:151], v[150:151]
	v_pk_mul_f32 v[168:169], v[152:153], v[152:153]
	v_pk_mul_f32 v[170:171], v[154:155], v[154:155]
	v_pk_mul_f32 v[164:165], v[164:165], v[198:199]
	v_pk_mul_f32 v[166:167], v[166:167], v[198:199]
	v_pk_mul_f32 v[168:169], v[168:169], v[198:199]
	v_pk_mul_f32 v[170:171], v[170:171], v[198:199]
	v_exp_f32_e32 v164, v164
	v_exp_f32_e32 v165, v165
	v_exp_f32_e32 v166, v166
	v_exp_f32_e32 v167, v167
	v_exp_f32_e32 v168, v168
	v_exp_f32_e32 v169, v169
	v_exp_f32_e32 v170, v170
	v_exp_f32_e32 v171, v171
	v_pk_mul_f32 v[172:173], v[172:173], v[164:165]
	v_pk_mul_f32 v[174:175], v[174:175], v[166:167]
; __device__ __forceinline__ unsigned cvt_pk_bf16(float lo, float hi) { unsigned r; asm volatile("v_cvt_pk_bf16_f32 %0, %1, %2" : "=v"(r) : "v"(lo), "v"(hi)); return r; }
; __device__ __forceinline__ float gelu_as(float v) {
;   const float av = fabsf(v); const float t = __builtin_amdgcn_rcpf(av * 0.2316418882f + 1.0f);
;   float q = t * 0.5307027145f + (-0.7265760135f); q = q * t + 0.7107068705f; q = q * t + (-0.142248368f); q = q * t + 0.127414796f; q = q * t;
;   const float e = __builtin_amdgcn_exp2f((v * v) * (-0.72134752044f));
;   const float m = v * (q * e);
;   return v < 0.f ? m : v - m;
; __device__ __forceinline__ void phase_conv(KP p, int l, int tid) {
;     ...
;       for (int q = 0; q < CB; ++q) { const int col = jb + q + 1; const int cl = col > 63 ? 63 : col;
; #pragma unroll
;         for (int di = 0; di < RB + 2; ++di) an[q][di] = *(const u32x2*)(rowp[di] + (size_t)cl * DFF);
; #pragma unroll
;         for (int rr = 0; rr < RB; ++rr) ur[q][rr] = *(const u32x2*)(U + (size_t)((r0 + rr) * 64 + jb + q) * DFF + c0); }
;       __builtin_amdgcn_sched_barrier(0);
; #pragma unroll
;       for (int q = 0; q < CB; ++q) {
;         const int col = jb + q + 1;
; #pragma unroll
;         for (int di = 0; di < RB + 2; ++di) { const bool ok = rv[di] && (col < 64); unpack4(an[q][di], win[2][di]);
; #pragma unroll
;           for (int k = 0; k < 4; ++k) win[2][di][k] = ok ? win[2][di][k] : 0.f; }
; #pragma unroll
;         for (int rr = 0; rr < RB; ++rr) {
;           float uv[4]; unpack4(ur[q][rr], uv);
;           float o[4];
; #pragma unroll
;           for (int k = 0; k < 4; ++k) {
;             float a = bsv[k];
; #pragma unroll
;             for (int di = 0; di < 3; ++di)
; #pragma unroll
;               for (int dj = 0; dj < 3; ++dj) a += win[dj][rr + di][k] * w[di * 3 + dj][k];
;             o[k] = gelu_as(a) * uv[k];
;           }
;           u32x2 ow; ow.x = cvt_pk_bf16(o[0], o[1]); ow.y = cvt_pk_bf16(o[2], o[3]);
;           *(u32x2*)(G + (size_t)((r0 + rr) * 64 + jb + q) * DFF + c0) = ow;
;         }
	v_pk_mul_f32 v[176:177], v[176:177], v[168:169]
	v_pk_mul_f32 v[178:179], v[178:179], v[170:171]
	v_pk_mul_f32 v[172:173], v[156:157], v[172:173]
	v_pk_mul_f32 v[174:175], v[158:159], v[174:175]
	v_pk_mul_f32 v[176:177], v[160:161], v[176:177]
	v_pk_mul_f32 v[178:179], v[162:163], v[178:179]
	v_max_f32_e32 v164, 0, v148
	v_max_f32_e32 v165, 0, v149
	v_max_f32_e32 v166, 0, v150
	v_max_f32_e32 v167, 0, v151
	v_max_f32_e32 v168, 0, v152
	v_max_f32_e32 v169, 0, v153
	v_max_f32_e32 v170, 0, v154
	v_max_f32_e32 v171, 0, v155
	v_pk_add_f32 v[164:165], v[164:165], v[172:173] neg_lo:[0,1] neg_hi:[0,1]
	v_pk_add_f32 v[166:167], v[166:167], v[174:175] neg_lo:[0,1] neg_hi:[0,1]
	v_pk_add_f32 v[168:169], v[168:169], v[176:177] neg_lo:[0,1] neg_hi:[0,1]
	v_pk_add_f32 v[170:171], v[170:171], v[178:179] neg_lo:[0,1] neg_hi:[0,1]
	v_pk_mul_f32 v[164:165], v[164:165], v[124:125]
	v_pk_mul_f32 v[166:167], v[166:167], v[126:127]
	v_pk_mul_f32 v[168:169], v[168:169], v[128:129]
	v_pk_mul_f32 v[170:171], v[170:171], v[130:131]
	v_cvt_pk_bf16_f32 v156, v164, v165
	v_cvt_pk_bf16_f32 v157, v166, v167
	v_cvt_pk_bf16_f32 v158, v168, v169
	v_cvt_pk_bf16_f32 v159, v170, v171
	global_store_dwordx2 v216, v[156:157], s[10:11]
	global_store_dwordx2 v217, v[158:159], s[10:11]
	v_add_u32_e32 v210, 0x2c00, v210
	v_add_u32_e32 v211, 0x2c00, v210
	v_add_u32_e32 v212, v206, v211
	global_load_dwordx2 v[88:89], v212, s[6:7]
	v_add_u32_e32 v213, v207, v211
	global_load_dwordx2 v[90:91], v213, s[6:7]
	v_add_u32_e32 v214, v208, v211
	global_load_dwordx2 v[92:93], v214, s[6:7]
	v_add_u32_e32 v215, v209, v211
	global_load_dwordx2 v[94:95], v215, s[6:7]
	v_add_u32_e32 v216, v207, v210
	global_load_dwordx2 v[112:113], v216, s[8:9] nt
	v_add_u32_e32 v217, v208, v210
	global_load_dwordx2 v[114:115], v217, s[8:9] nt
	s_waitcnt vmcnt(16)
	v_lshlrev_b32_e32 v40, 16, v96
	v_and_b32_e32 v41, 0xffff0000, v96
	v_lshlrev_b32_e32 v42, 16, v97
	v_and_b32_e32 v43, 0xffff0000, v97
	v_lshlrev_b32_e32 v44, 16, v98
	v_and_b32_e32 v45, 0xffff0000, v98
	v_lshlrev_b32_e32 v46, 16, v99
	v_and_b32_e32 v47, 0xffff0000, v99
	v_lshlrev_b32_e32 v48, 16, v100
	v_and_b32_e32 v49, 0xffff0000, v100
	v_lshlrev_b32_e32 v50, 16, v101
	v_and_b32_e32 v51, 0xffff0000, v101
	v_lshlrev_b32_e32 v52, 16, v102
	v_and_b32_e32 v53, 0xffff0000, v102
	v_lshlrev_b32_e32 v54, 16, v103
	v_and_b32_e32 v55, 0xffff0000, v103
	v_pk_mul_f32 v[40:41], v[40:41], v[200:201]
	v_pk_mul_f32 v[42:43], v[42:43], v[200:201]
	v_pk_mul_f32 v[52:53], v[52:53], v[202:203]
	v_pk_mul_f32 v[54:55], v[54:55], v[202:203]
	v_lshlrev_b32_e32 v124, 16, v116
	v_and_b32_e32 v125, 0xffff0000, v116
	v_lshlrev_b32_e32 v126, 16, v117
	v_and_b32_e32 v127, 0xffff0000, v117
	v_lshlrev_b32_e32 v128, 16, v118
	v_and_b32_e32 v129, 0xffff0000, v118
	v_lshlrev_b32_e32 v130, 16, v119
	v_and_b32_e32 v131, 0xffff0000, v119
	v_pk_fma_f32 v[148:149], v[56:57], v[0:1], v[36:37]
	v_pk_fma_f32 v[150:151], v[58:59], v[2:3], v[38:39]
	v_pk_fma_f32 v[152:153], v[60:61], v[0:1], v[36:37]
	v_pk_fma_f32 v[154:155], v[62:63], v[2:3], v[38:39]
	v_pk_fma_f32 v[148:149], v[72:73], v[4:5], v[148:149]
	v_pk_fma_f32 v[150:151], v[74:75], v[6:7], v[150:151]
	v_pk_fma_f32 v[152:153], v[76:77], v[4:5], v[152:153]
	v_pk_fma_f32 v[154:155], v[78:79], v[6:7], v[154:155]
	v_pk_fma_f32 v[148:149], v[40:41], v[8:9], v[148:149]
	v_pk_fma_f32 v[150:151], v[42:43], v[10:11], v[150:151]
	v_pk_fma_f32 v[152:153], v[44:45], v[8:9], v[152:153]
	v_pk_fma_f32 v[154:155], v[46:47], v[10:11], v[154:155]
	v_pk_fma_f32 v[148:149], v[60:61], v[12:13], v[148:149]
	v_pk_fma_f32 v[150:151], v[62:63], v[14:15], v[150:151]
	v_pk_fma_f32 v[152:153], v[64:65], v[12:13], v[152:153]
	v_pk_fma_f32 v[154:155], v[66:67], v[14:15], v[154:155]
	v_pk_fma_f32 v[148:149], v[76:77], v[16:17], v[148:149]
	v_pk_fma_f32 v[150:151], v[78:79], v[18:19], v[150:151]
	v_pk_fma_f32 v[152:153], v[80:81], v[16:17], v[152:153]
	v_pk_fma_f32 v[154:155], v[82:83], v[18:19], v[154:155]
	v_pk_fma_f32 v[148:149], v[44:45], v[20:21], v[148:149]
	v_pk_fma_f32 v[150:151], v[46:47], v[22:23], v[150:151]
	v_pk_fma_f32 v[152:153], v[48:49], v[20:21], v[152:153]
	v_pk_fma_f32 v[154:155], v[50:51], v[22:23], v[154:155]
	v_pk_fma_f32 v[148:149], v[64:65], v[24:25], v[148:149]
	v_pk_fma_f32 v[150:151], v[66:67], v[26:27], v[150:151]
	v_pk_fma_f32 v[152:153], v[68:69], v[24:25], v[152:153]
	v_pk_fma_f32 v[154:155], v[70:71], v[26:27], v[154:155]
	v_pk_fma_f32 v[148:149], v[80:81], v[28:29], v[148:149]
	v_pk_fma_f32 v[150:151], v[82:83], v[30:31], v[150:151]
	v_pk_fma_f32 v[152:153], v[84:85], v[28:29], v[152:153]
	v_pk_fma_f32 v[154:155], v[86:87], v[30:31], v[154:155]
	v_pk_fma_f32 v[148:149], v[48:49], v[32:33], v[148:149]
	v_pk_fma_f32 v[150:151], v[50:51], v[34:35], v[150:151]
	v_pk_fma_f32 v[152:153], v[52:53], v[32:33], v[152:153]
	v_pk_fma_f32 v[154:155], v[54:55], v[34:35], v[154:155]
	v_and_b32_e32 v156, 0x7fffffff, v148
	v_and_b32_e32 v157, 0x7fffffff, v149
	v_and_b32_e32 v158, 0x7fffffff, v150
	v_and_b32_e32 v159, 0x7fffffff, v151
	v_and_b32_e32 v160, 0x7fffffff, v152
	v_and_b32_e32 v161, 0x7fffffff, v153
	v_and_b32_e32 v162, 0x7fffffff, v154
	v_and_b32_e32 v163, 0x7fffffff, v155
	v_pk_fma_f32 v[164:165], v[156:157], v[184:185], v[186:187]
	v_pk_fma_f32 v[166:167], v[158:159], v[184:185], v[186:187]
	v_pk_fma_f32 v[168:169], v[160:161], v[184:185], v[186:187]
	v_pk_fma_f32 v[170:171], v[162:163], v[184:185], v[186:187]
	v_rcp_f32_e32 v164, v164
	v_rcp_f32_e32 v165, v165
	v_rcp_f32_e32 v166, v166
	v_rcp_f32_e32 v167, v167
	v_rcp_f32_e32 v168, v168
	v_rcp_f32_e32 v169, v169
	v_rcp_f32_e32 v170, v170
	v_rcp_f32_e32 v171, v171
; __device__ __forceinline__ unsigned cvt_pk_bf16(float lo, float hi) { unsigned r; asm volatile("v_cvt_pk_bf16_f32 %0, %1, %2" : "=v"(r) : "v"(lo), "v"(hi)); return r; }
; __device__ __forceinline__ float gelu_as(float v) {
;   const float av = fabsf(v); const float t = __builtin_amdgcn_rcpf(av * 0.2316418882f + 1.0f);
;   float q = t * 0.5307027145f + (-0.7265760135f); q = q * t + 0.7107068705f; q = q * t + (-0.142248368f); q = q * t + 0.127414796f; q = q * t;
;   const float e = __builtin_amdgcn_exp2f((v * v) * (-0.72134752044f));
;   const float m = v * (q * e);
;   return v < 0.f ? m : v - m;
; __device__ __forceinline__ void phase_conv(KP p, int l, int tid) {
;     ...
;       for (int q = 0; q < CB; ++q) { const int col = jb + q + 1; const int cl = col > 63 ? 63 : col;
; #pragma unroll
;         for (int di = 0; di < RB + 2; ++di) an[q][di] = *(const u32x2*)(rowp[di] + (size_t)cl * DFF);
; #pragma unroll
;         for (int rr = 0; rr < RB; ++rr) ur[q][rr] = *(const u32x2*)(U + (size_t)((r0 + rr) * 64 + jb + q) * DFF + c0); }
;       __builtin_amdgcn_sched_barrier(0);
; #pragma unroll
;       for (int q = 0; q < CB; ++q) {
;         const int col = jb + q + 1;
; #pragma unroll
;         for (int di = 0; di < RB + 2; ++di) { const bool ok = rv[di] && (col < 64); unpack4(an[q][di], win[2][di]);
; #pragma unroll
;           for (int k = 0; k < 4; ++k) win[2][di][k] = ok ? win[2][di][k] : 0.f; }
; #pragma unroll
;         for (int rr = 0; rr < RB; ++rr) {
;           float uv[4]; unpack4(ur[q][rr], uv);
;           float o[4];
; #pragma unroll
;           for (int k = 0; k < 4; ++k) {
;             float a = bsv[k];
; #pragma unroll
;             for (int di = 0; di < 3; ++di)
; #pragma unroll
;               for (int dj = 0; dj < 3; ++dj) a += win[dj][rr + di][k] * w[di * 3 + dj][k];
;             o[k] = gelu_as(a) * uv[k];
;           }
;           u32x2 ow; ow.x = cvt_pk_bf16(o[0], o[1]); ow.y = cvt_pk_bf16(o[2], o[3]);
;           *(u32x2*)(G + (size_t)((r0 + rr) * 64 + jb + q) * DFF + c0) = ow;
;         }
	v_pk_fma_f32 v[172:173], v[164:165], v[188:189], v[190:191]
	v_pk_fma_f32 v[174:175], v[166:167], v[188:189], v[190:191]
	v_pk_fma_f32 v[176:177], v[168:169], v[188:189], v[190:191]
	v_pk_fma_f32 v[178:179], v[170:171], v[188:189], v[190:191]
	v_pk_fma_f32 v[172:173], v[172:173], v[164:165], v[192:193]
	v_pk_fma_f32 v[174:175], v[174:175], v[166:167], v[192:193]
	v_pk_fma_f32 v[176:177], v[176:177], v[168:169], v[192:193]
	v_pk_fma_f32 v[178:179], v[178:179], v[170:171], v[192:193]
	v_pk_fma_f32 v[172:173], v[172:173], v[164:165], v[194:195]
	v_pk_fma_f32 v[174:175], v[174:175], v[166:167], v[194:195]
	v_pk_fma_f32 v[176:177], v[176:177], v[168:169], v[194:195]
	v_pk_fma_f32 v[178:179], v[178:179], v[170:171], v[194:195]
	v_pk_fma_f32 v[172:173], v[172:173], v[164:165], v[196:197]
	v_pk_fma_f32 v[174:175], v[174:175], v[166:167], v[196:197]
	v_pk_fma_f32 v[176:177], v[176:177], v[168:169], v[196:197]
	v_pk_fma_f32 v[178:179], v[178:179], v[170:171], v[196:197]
	v_pk_mul_f32 v[172:173], v[172:173], v[164:165]
	v_pk_mul_f32 v[174:175], v[174:175], v[166:167]
	v_pk_mul_f32 v[176:177], v[176:177], v[168:169]
	v_pk_mul_f32 v[178:179], v[178:179], v[170:171]
	v_pk_mul_f32 v[164:165], v[148:149], v[148:149]
	v_pk_mul_f32 v[166:167], v[150:151], v[150:151]
	v_pk_mul_f32 v[168:169], v[152:153], v[152:153]
	v_pk_mul_f32 v[170:171], v[154:155], v[154:155]
	v_pk_mul_f32 v[164:165], v[164:165], v[198:199]
	v_pk_mul_f32 v[166:167], v[166:167], v[198:199]
	v_pk_mul_f32 v[168:169], v[168:169], v[198:199]
	v_pk_mul_f32 v[170:171], v[170:171], v[198:199]
	v_exp_f32_e32 v164, v164
	v_exp_f32_e32 v165, v165
	v_exp_f32_e32 v166, v166
	v_exp_f32_e32 v167, v167
	v_exp_f32_e32 v168, v168
	v_exp_f32_e32 v169, v169
	v_exp_f32_e32 v170, v170
	v_exp_f32_e32 v171, v171
	v_pk_mul_f32 v[172:173], v[172:173], v[164:165]
	v_pk_mul_f32 v[174:175], v[174:175], v[166:167]
	v_pk_mul_f32 v[176:177], v[176:177], v[168:169]
	v_pk_mul_f32 v[178:179], v[178:179], v[170:171]
	v_pk_mul_f32 v[172:173], v[156:157], v[172:173]
	v_pk_mul_f32 v[174:175], v[158:159], v[174:175]
	v_pk_mul_f32 v[176:177], v[160:161], v[176:177]
	v_pk_mul_f32 v[178:179], v[162:163], v[178:179]
	v_max_f32_e32 v164, 0, v148
	v_max_f32_e32 v165, 0, v149
	v_max_f32_e32 v166, 0, v150
	v_max_f32_e32 v167, 0, v151
	v_max_f32_e32 v168, 0, v152
	v_max_f32_e32 v169, 0, v153
	v_max_f32_e32 v170, 0, v154
	v_max_f32_e32 v171, 0, v155
	v_pk_add_f32 v[164:165], v[164:165], v[172:173] neg_lo:[0,1] neg_hi:[0,1]
	v_pk_add_f32 v[166:167], v[166:167], v[174:175] neg_lo:[0,1] neg_hi:[0,1]
	v_pk_add_f32 v[168:169], v[168:169], v[176:177] neg_lo:[0,1] neg_hi:[0,1]
	v_pk_add_f32 v[170:171], v[170:171], v[178:179] neg_lo:[0,1] neg_hi:[0,1]
	v_pk_mul_f32 v[164:165], v[164:165], v[124:125]
	v_pk_mul_f32 v[166:167], v[166:167], v[126:127]
	v_pk_mul_f32 v[168:169], v[168:169], v[128:129]
	v_pk_mul_f32 v[170:171], v[170:171], v[130:131]
	v_cvt_pk_bf16_f32 v156, v164, v165
	v_cvt_pk_bf16_f32 v157, v166, v167
	v_cvt_pk_bf16_f32 v158, v168, v169
	v_cvt_pk_bf16_f32 v159, v170, v171
	global_store_dwordx2 v218, v[156:157], s[10:11]
	global_store_dwordx2 v219, v[158:159], s[10:11]
	v_add_u32_e32 v210, 0x2c00, v210
	v_add_u32_e32 v211, 0x2c00, v210
	v_add_u32_e32 v212, v206, v211
	global_load_dwordx2 v[96:97], v212, s[6:7]
	v_add_u32_e32 v213, v207, v211
	global_load_dwordx2 v[98:99], v213, s[6:7]
	v_add_u32_e32 v214, v208, v211
	global_load_dwordx2 v[100:101], v214, s[6:7]
	v_add_u32_e32 v215, v209, v211
	global_load_dwordx2 v[102:103], v215, s[6:7]
	v_add_u32_e32 v218, v207, v210
	global_load_dwordx2 v[116:117], v218, s[8:9] nt
	v_add_u32_e32 v219, v208, v210
	global_load_dwordx2 v[118:119], v219, s[8:9] nt
	s_waitcnt vmcnt(16)
	v_lshlrev_b32_e32 v56, 16, v104
	v_and_b32_e32 v57, 0xffff0000, v104
	v_lshlrev_b32_e32 v58, 16, v105
	v_and_b32_e32 v59, 0xffff0000, v105
	v_lshlrev_b32_e32 v60, 16, v106
	v_and_b32_e32 v61, 0xffff0000, v106
	v_lshlrev_b32_e32 v62, 16, v107
	v_and_b32_e32 v63, 0xffff0000, v107
	v_lshlrev_b32_e32 v64, 16, v108
	v_and_b32_e32 v65, 0xffff0000, v108
	v_lshlrev_b32_e32 v66, 16, v109
	v_and_b32_e32 v67, 0xffff0000, v109
	v_lshlrev_b32_e32 v68, 16, v110
	v_and_b32_e32 v69, 0xffff0000, v110
	v_lshlrev_b32_e32 v70, 16, v111
	v_and_b32_e32 v71, 0xffff0000, v111
	v_pk_mul_f32 v[56:57], v[56:57], v[200:201]
	v_pk_mul_f32 v[58:59], v[58:59], v[200:201]
	v_pk_mul_f32 v[68:69], v[68:69], v[202:203]
	v_pk_mul_f32 v[70:71], v[70:71], v[202:203]
	v_lshlrev_b32_e32 v124, 16, v120
	v_and_b32_e32 v125, 0xffff0000, v120
	v_lshlrev_b32_e32 v126, 16, v121
	v_and_b32_e32 v127, 0xffff0000, v121
	v_lshlrev_b32_e32 v128, 16, v122
	v_and_b32_e32 v129, 0xffff0000, v122
	v_lshlrev_b32_e32 v130, 16, v123
	v_and_b32_e32 v131, 0xffff0000, v123
	v_pk_fma_f32 v[148:149], v[72:73], v[0:1], v[36:37]
	v_pk_fma_f32 v[150:151], v[74:75], v[2:3], v[38:39]
	v_pk_fma_f32 v[152:153], v[76:77], v[0:1], v[36:37]
	v_pk_fma_f32 v[154:155], v[78:79], v[2:3], v[38:39]
	v_pk_fma_f32 v[148:149], v[40:41], v[4:5], v[148:149]
	v_pk_fma_f32 v[150:151], v[42:43], v[6:7], v[150:151]
	v_pk_fma_f32 v[152:153], v[44:45], v[4:5], v[152:153]
	v_pk_fma_f32 v[154:155], v[46:47], v[6:7], v[154:155]
	v_pk_fma_f32 v[148:149], v[56:57], v[8:9], v[148:149]
	v_pk_fma_f32 v[150:151], v[58:59], v[10:11], v[150:151]
	v_pk_fma_f32 v[152:153], v[60:61], v[8:9], v[152:153]
	v_pk_fma_f32 v[154:155], v[62:63], v[10:11], v[154:155]
	v_pk_fma_f32 v[148:149], v[76:77], v[12:13], v[148:149]
	v_pk_fma_f32 v[150:151], v[78:79], v[14:15], v[150:151]
	v_pk_fma_f32 v[152:153], v[80:81], v[12:13], v[152:153]
	v_pk_fma_f32 v[154:155], v[82:83], v[14:15], v[154:155]
	v_pk_fma_f32 v[148:149], v[44:45], v[16:17], v[148:149]
; __device__ __forceinline__ unsigned cvt_pk_bf16(float lo, float hi) { unsigned r; asm volatile("v_cvt_pk_bf16_f32 %0, %1, %2" : "=v"(r) : "v"(lo), "v"(hi)); return r; }
; __device__ __forceinline__ float gelu_as(float v) {
;   const float av = fabsf(v); const float t = __builtin_amdgcn_rcpf(av * 0.2316418882f + 1.0f);
;   float q = t * 0.5307027145f + (-0.7265760135f); q = q * t + 0.7107068705f; q = q * t + (-0.142248368f); q = q * t + 0.127414796f; q = q * t;
;   const float e = __builtin_amdgcn_exp2f((v * v) * (-0.72134752044f));
;   const float m = v * (q * e);
;   return v < 0.f ? m : v - m;
; __device__ __forceinline__ void phase_conv(KP p, int l, int tid) {
;     ...
;       for (int q = 0; q < CB; ++q) { const int col = jb + q + 1; const int cl = col > 63 ? 63 : col;
; #pragma unroll
;         for (int di = 0; di < RB + 2; ++di) an[q][di] = *(const u32x2*)(rowp[di] + (size_t)cl * DFF);
; #pragma unroll
;         for (int rr = 0; rr < RB; ++rr) ur[q][rr] = *(const u32x2*)(U + (size_t)((r0 + rr) * 64 + jb + q) * DFF + c0); }
;       __builtin_amdgcn_sched_barrier(0);
; #pragma unroll
;       for (int q = 0; q < CB; ++q) {
;         const int col = jb + q + 1;
; #pragma unroll
;         for (int di = 0; di < RB + 2; ++di) { const bool ok = rv[di] && (col < 64); unpack4(an[q][di], win[2][di]);
; #pragma unroll
;           for (int k = 0; k < 4; ++k) win[2][di][k] = ok ? win[2][di][k] : 0.f; }
; #pragma unroll
;         for (int rr = 0; rr < RB; ++rr) {
;           float uv[4]; unpack4(ur[q][rr], uv);
;           float o[4];
; #pragma unroll
;           for (int k = 0; k < 4; ++k) {
;             float a = bsv[k];
; #pragma unroll
;             for (int di = 0; di < 3; ++di)
; #pragma unroll
;               for (int dj = 0; dj < 3; ++dj) a += win[dj][rr + di][k] * w[di * 3 + dj][k];
;             o[k] = gelu_as(a) * uv[k];
;           }
;           u32x2 ow; ow.x = cvt_pk_bf16(o[0], o[1]); ow.y = cvt_pk_bf16(o[2], o[3]);
;           *(u32x2*)(G + (size_t)((r0 + rr) * 64 + jb + q) * DFF + c0) = ow;
;         }
	v_pk_fma_f32 v[150:151], v[46:47], v[18:19], v[150:151]
	v_pk_fma_f32 v[152:153], v[48:49], v[16:17], v[152:153]
	v_pk_fma_f32 v[154:155], v[50:51], v[18:19], v[154:155]
	v_pk_fma_f32 v[148:149], v[60:61], v[20:21], v[148:149]
	v_pk_fma_f32 v[150:151], v[62:63], v[22:23], v[150:151]
	v_pk_fma_f32 v[152:153], v[64:65], v[20:21], v[152:153]
	v_pk_fma_f32 v[154:155], v[66:67], v[22:23], v[154:155]
	v_pk_fma_f32 v[148:149], v[80:81], v[24:25], v[148:149]
	v_pk_fma_f32 v[150:151], v[82:83], v[26:27], v[150:151]
	v_pk_fma_f32 v[152:153], v[84:85], v[24:25], v[152:153]
	v_pk_fma_f32 v[154:155], v[86:87], v[26:27], v[154:155]
	v_pk_fma_f32 v[148:149], v[48:49], v[28:29], v[148:149]
	v_pk_fma_f32 v[150:151], v[50:51], v[30:31], v[150:151]
	v_pk_fma_f32 v[152:153], v[52:53], v[28:29], v[152:153]
	v_pk_fma_f32 v[154:155], v[54:55], v[30:31], v[154:155]
	v_pk_fma_f32 v[148:149], v[64:65], v[32:33], v[148:149]
	v_pk_fma_f32 v[150:151], v[66:67], v[34:35], v[150:151]
	v_pk_fma_f32 v[152:153], v[68:69], v[32:33], v[152:153]
	v_pk_fma_f32 v[154:155], v[70:71], v[34:35], v[154:155]
	v_and_b32_e32 v156, 0x7fffffff, v148
	v_and_b32_e32 v157, 0x7fffffff, v149
	v_and_b32_e32 v158, 0x7fffffff, v150
	v_and_b32_e32 v159, 0x7fffffff, v151
	v_and_b32_e32 v160, 0x7fffffff, v152
	v_and_b32_e32 v161, 0x7fffffff, v153
	v_and_b32_e32 v162, 0x7fffffff, v154
	v_and_b32_e32 v163, 0x7fffffff, v155
	v_pk_fma_f32 v[164:165], v[156:157], v[184:185], v[186:187]
	v_pk_fma_f32 v[166:167], v[158:159], v[184:185], v[186:187]
	v_pk_fma_f32 v[168:169], v[160:161], v[184:185], v[186:187]
	v_pk_fma_f32 v[170:171], v[162:163], v[184:185], v[186:187]
	v_rcp_f32_e32 v164, v164
	v_rcp_f32_e32 v165, v165
	v_rcp_f32_e32 v166, v166
	v_rcp_f32_e32 v167, v167
	v_rcp_f32_e32 v168, v168
	v_rcp_f32_e32 v169, v169
	v_rcp_f32_e32 v170, v170
	v_rcp_f32_e32 v171, v171
	v_pk_fma_f32 v[172:173], v[164:165], v[188:189], v[190:191]
	v_pk_fma_f32 v[174:175], v[166:167], v[188:189], v[190:191]
	v_pk_fma_f32 v[176:177], v[168:169], v[188:189], v[190:191]
	v_pk_fma_f32 v[178:179], v[170:171], v[188:189], v[190:191]
	v_pk_fma_f32 v[172:173], v[172:173], v[164:165], v[192:193]
	v_pk_fma_f32 v[174:175], v[174:175], v[166:167], v[192:193]
	v_pk_fma_f32 v[176:177], v[176:177], v[168:169], v[192:193]
	v_pk_fma_f32 v[178:179], v[178:179], v[170:171], v[192:193]
	v_pk_fma_f32 v[172:173], v[172:173], v[164:165], v[194:195]
	v_pk_fma_f32 v[174:175], v[174:175], v[166:167], v[194:195]
	v_pk_fma_f32 v[176:177], v[176:177], v[168:169], v[194:195]
	v_pk_fma_f32 v[178:179], v[178:179], v[170:171], v[194:195]
	v_pk_fma_f32 v[172:173], v[172:173], v[164:165], v[196:197]
	v_pk_fma_f32 v[174:175], v[174:175], v[166:167], v[196:197]
	v_pk_fma_f32 v[176:177], v[176:177], v[168:169], v[196:197]
	v_pk_fma_f32 v[178:179], v[178:179], v[170:171], v[196:197]
	v_pk_mul_f32 v[172:173], v[172:173], v[164:165]
	v_pk_mul_f32 v[174:175], v[174:175], v[166:167]
	v_pk_mul_f32 v[176:177], v[176:177], v[168:169]
	v_pk_mul_f32 v[178:179], v[178:179], v[170:171]
	v_pk_mul_f32 v[164:165], v[148:149], v[148:149]
	v_pk_mul_f32 v[166:167], v[150:151], v[150:151]
	v_pk_mul_f32 v[168:169], v[152:153], v[152:153]
	v_pk_mul_f32 v[170:171], v[154:155], v[154:155]
	v_pk_mul_f32 v[164:165], v[164:165], v[198:199]
	v_pk_mul_f32 v[166:167], v[166:167], v[198:199]
	v_pk_mul_f32 v[168:169], v[168:169], v[198:199]
	v_pk_mul_f32 v[170:171], v[170:171], v[198:199]
	v_exp_f32_e32 v164, v164
	v_exp_f32_e32 v165, v165
	v_exp_f32_e32 v166, v166
	v_exp_f32_e32 v167, v167
	v_exp_f32_e32 v168, v168
	v_exp_f32_e32 v169, v169
	v_exp_f32_e32 v170, v170
	v_exp_f32_e32 v171, v171
	v_pk_mul_f32 v[172:173], v[172:173], v[164:165]
	v_pk_mul_f32 v[174:175], v[174:175], v[166:167]
	v_pk_mul_f32 v[176:177], v[176:177], v[168:169]
	v_pk_mul_f32 v[178:179], v[178:179], v[170:171]
	v_pk_mul_f32 v[172:173], v[156:157], v[172:173]
	v_pk_mul_f32 v[174:175], v[158:159], v[174:175]
	v_pk_mul_f32 v[176:177], v[160:161], v[176:177]
	v_pk_mul_f32 v[178:179], v[162:163], v[178:179]
	v_max_f32_e32 v164, 0, v148
	v_max_f32_e32 v165, 0, v149
	v_max_f32_e32 v166, 0, v150
	v_max_f32_e32 v167, 0, v151
	v_max_f32_e32 v168, 0, v152
	v_max_f32_e32 v169, 0, v153
	v_max_f32_e32 v170, 0, v154
	v_max_f32_e32 v171, 0, v155
	v_pk_add_f32 v[164:165], v[164:165], v[172:173] neg_lo:[0,1] neg_hi:[0,1]
	v_pk_add_f32 v[166:167], v[166:167], v[174:175] neg_lo:[0,1] neg_hi:[0,1]
	v_pk_add_f32 v[168:169], v[168:169], v[176:177] neg_lo:[0,1] neg_hi:[0,1]
	v_pk_add_f32 v[170:171], v[170:171], v[178:179] neg_lo:[0,1] neg_hi:[0,1]
	v_pk_mul_f32 v[164:165], v[164:165], v[124:125]
	v_pk_mul_f32 v[166:167], v[166:167], v[126:127]
	v_pk_mul_f32 v[168:169], v[168:169], v[128:129]
	v_pk_mul_f32 v[170:171], v[170:171], v[130:131]
	v_cvt_pk_bf16_f32 v156, v164, v165
	v_cvt_pk_bf16_f32 v157, v166, v167
	v_cvt_pk_bf16_f32 v158, v168, v169
	v_cvt_pk_bf16_f32 v159, v170, v171
	global_store_dwordx2 v220, v[156:157], s[10:11]
	global_store_dwordx2 v221, v[158:159], s[10:11]
	v_add_u32_e32 v210, 0x2c00, v210
	v_add_u32_e32 v211, 0x2c00, v210
	v_add_u32_e32 v212, v206, v211
	global_load_dwordx2 v[104:105], v212, s[6:7]
	v_add_u32_e32 v213, v207, v211
	global_load_dwordx2 v[106:107], v213, s[6:7]
	v_add_u32_e32 v214, v208, v211
	global_load_dwordx2 v[108:109], v214, s[6:7]
	v_add_u32_e32 v215, v209, v211
	global_load_dwordx2 v[110:111], v215, s[6:7]
	v_add_u32_e32 v220, v207, v210
	global_load_dwordx2 v[120:121], v220, s[8:9] nt
	v_add_u32_e32 v221, v208, v210
	global_load_dwordx2 v[122:123], v221, s[8:9] nt
	s_waitcnt vmcnt(16)
; __device__ __forceinline__ unsigned cvt_pk_bf16(float lo, float hi) { unsigned r; asm volatile("v_cvt_pk_bf16_f32 %0, %1, %2" : "=v"(r) : "v"(lo), "v"(hi)); return r; }
; __device__ __forceinline__ float gelu_as(float v) {
;   const float av = fabsf(v); const float t = __builtin_amdgcn_rcpf(av * 0.2316418882f + 1.0f);
;   float q = t * 0.5307027145f + (-0.7265760135f); q = q * t + 0.7107068705f; q = q * t + (-0.142248368f); q = q * t + 0.127414796f; q = q * t;
;   const float e = __builtin_amdgcn_exp2f((v * v) * (-0.72134752044f));
;   const float m = v * (q * e);
;   return v < 0.f ? m : v - m;
; __device__ __forceinline__ void phase_conv(KP p, int l, int tid) {
;     ...
;       for (int q = 0; q < CB; ++q) { const int col = jb + q + 1; const int cl = col > 63 ? 63 : col;
; #pragma unroll
;         for (int di = 0; di < RB + 2; ++di) an[q][di] = *(const u32x2*)(rowp[di] + (size_t)cl * DFF);
; #pragma unroll
;         for (int rr = 0; rr < RB; ++rr) ur[q][rr] = *(const u32x2*)(U + (size_t)((r0 + rr) * 64 + jb + q) * DFF + c0); }
;       __builtin_amdgcn_sched_barrier(0);
; #pragma unroll
;       for (int q = 0; q < CB; ++q) {
;         const int col = jb + q + 1;
; #pragma unroll
;         for (int di = 0; di < RB + 2; ++di) { const bool ok = rv[di] && (col < 64); unpack4(an[q][di], win[2][di]);
; #pragma unroll
;           for (int k = 0; k < 4; ++k) win[2][di][k] = ok ? win[2][di][k] : 0.f; }
; #pragma unroll
;         for (int rr = 0; rr < RB; ++rr) {
;           float uv[4]; unpack4(ur[q][rr], uv);
;           float o[4];
; #pragma unroll
;           for (int k = 0; k < 4; ++k) {
;             float a = bsv[k];
; #pragma unroll
;             for (int di = 0; di < 3; ++di)
; #pragma unroll
;               for (int dj = 0; dj < 3; ++dj) a += win[dj][rr + di][k] * w[di * 3 + dj][k];
;             o[k] = gelu_as(a) * uv[k];
;           }
;           u32x2 ow; ow.x = cvt_pk_bf16(o[0], o[1]); ow.y = cvt_pk_bf16(o[2], o[3]);
;           *(u32x2*)(G + (size_t)((r0 + rr) * 64 + jb + q) * DFF + c0) = ow;
;         }
	v_lshlrev_b32_e32 v72, 16, v88
	v_and_b32_e32 v73, 0xffff0000, v88
	v_lshlrev_b32_e32 v74, 16, v89
	v_and_b32_e32 v75, 0xffff0000, v89
	v_lshlrev_b32_e32 v76, 16, v90
	v_and_b32_e32 v77, 0xffff0000, v90
	v_lshlrev_b32_e32 v78, 16, v91
	v_and_b32_e32 v79, 0xffff0000, v91
	v_lshlrev_b32_e32 v80, 16, v92
	v_and_b32_e32 v81, 0xffff0000, v92
	v_lshlrev_b32_e32 v82, 16, v93
	v_and_b32_e32 v83, 0xffff0000, v93
	v_lshlrev_b32_e32 v84, 16, v94
	v_and_b32_e32 v85, 0xffff0000, v94
	v_lshlrev_b32_e32 v86, 16, v95
	v_and_b32_e32 v87, 0xffff0000, v95
	v_pk_mul_f32 v[72:73], v[72:73], v[200:201]
	v_pk_mul_f32 v[74:75], v[74:75], v[200:201]
	v_pk_mul_f32 v[84:85], v[84:85], v[202:203]
	v_pk_mul_f32 v[86:87], v[86:87], v[202:203]
	v_lshlrev_b32_e32 v124, 16, v112
	v_and_b32_e32 v125, 0xffff0000, v112
	v_lshlrev_b32_e32 v126, 16, v113
	v_and_b32_e32 v127, 0xffff0000, v113
	v_lshlrev_b32_e32 v128, 16, v114
	v_and_b32_e32 v129, 0xffff0000, v114
	v_lshlrev_b32_e32 v130, 16, v115
	v_and_b32_e32 v131, 0xffff0000, v115
	v_pk_fma_f32 v[148:149], v[40:41], v[0:1], v[36:37]
	v_pk_fma_f32 v[150:151], v[42:43], v[2:3], v[38:39]
	v_pk_fma_f32 v[152:153], v[44:45], v[0:1], v[36:37]
	v_pk_fma_f32 v[154:155], v[46:47], v[2:3], v[38:39]
	v_pk_fma_f32 v[148:149], v[56:57], v[4:5], v[148:149]
	v_pk_fma_f32 v[150:151], v[58:59], v[6:7], v[150:151]
	v_pk_fma_f32 v[152:153], v[60:61], v[4:5], v[152:153]
	v_pk_fma_f32 v[154:155], v[62:63], v[6:7], v[154:155]
	v_pk_fma_f32 v[148:149], v[72:73], v[8:9], v[148:149]
	v_pk_fma_f32 v[150:151], v[74:75], v[10:11], v[150:151]
	v_pk_fma_f32 v[152:153], v[76:77], v[8:9], v[152:153]
	v_pk_fma_f32 v[154:155], v[78:79], v[10:11], v[154:155]
	v_pk_fma_f32 v[148:149], v[44:45], v[12:13], v[148:149]
	v_pk_fma_f32 v[150:151], v[46:47], v[14:15], v[150:151]
	v_pk_fma_f32 v[152:153], v[48:49], v[12:13], v[152:153]
	v_pk_fma_f32 v[154:155], v[50:51], v[14:15], v[154:155]
	v_pk_fma_f32 v[148:149], v[60:61], v[16:17], v[148:149]
	v_pk_fma_f32 v[150:151], v[62:63], v[18:19], v[150:151]
	v_pk_fma_f32 v[152:153], v[64:65], v[16:17], v[152:153]
	v_pk_fma_f32 v[154:155], v[66:67], v[18:19], v[154:155]
	v_pk_fma_f32 v[148:149], v[76:77], v[20:21], v[148:149]
	v_pk_fma_f32 v[150:151], v[78:79], v[22:23], v[150:151]
	v_pk_fma_f32 v[152:153], v[80:81], v[20:21], v[152:153]
	v_pk_fma_f32 v[154:155], v[82:83], v[22:23], v[154:155]
	v_pk_fma_f32 v[148:149], v[48:49], v[24:25], v[148:149]
	v_pk_fma_f32 v[150:151], v[50:51], v[26:27], v[150:151]
	v_pk_fma_f32 v[152:153], v[52:53], v[24:25], v[152:153]
	v_pk_fma_f32 v[154:155], v[54:55], v[26:27], v[154:155]
	v_pk_fma_f32 v[148:149], v[64:65], v[28:29], v[148:149]
	v_pk_fma_f32 v[150:151], v[66:67], v[30:31], v[150:151]
	v_pk_fma_f32 v[152:153], v[68:69], v[28:29], v[152:153]
	v_pk_fma_f32 v[154:155], v[70:71], v[30:31], v[154:155]
	v_pk_fma_f32 v[148:149], v[80:81], v[32:33], v[148:149]
	v_pk_fma_f32 v[150:151], v[82:83], v[34:35], v[150:151]
	v_pk_fma_f32 v[152:153], v[84:85], v[32:33], v[152:153]
	v_pk_fma_f32 v[154:155], v[86:87], v[34:35], v[154:155]
	v_and_b32_e32 v156, 0x7fffffff, v148
	v_and_b32_e32 v157, 0x7fffffff, v149
	v_and_b32_e32 v158, 0x7fffffff, v150
	v_and_b32_e32 v159, 0x7fffffff, v151
	v_and_b32_e32 v160, 0x7fffffff, v152
	v_and_b32_e32 v161, 0x7fffffff, v153
	v_and_b32_e32 v162, 0x7fffffff, v154
	v_and_b32_e32 v163, 0x7fffffff, v155
	v_pk_fma_f32 v[164:165], v[156:157], v[184:185], v[186:187]
	v_pk_fma_f32 v[166:167], v[158:159], v[184:185], v[186:187]
	v_pk_fma_f32 v[168:169], v[160:161], v[184:185], v[186:187]
	v_pk_fma_f32 v[170:171], v[162:163], v[184:185], v[186:187]
	v_rcp_f32_e32 v164, v164
	v_rcp_f32_e32 v165, v165
	v_rcp_f32_e32 v166, v166
	v_rcp_f32_e32 v167, v167
	v_rcp_f32_e32 v168, v168
	v_rcp_f32_e32 v169, v169
	v_rcp_f32_e32 v170, v170
	v_rcp_f32_e32 v171, v171
	v_pk_fma_f32 v[172:173], v[164:165], v[188:189], v[190:191]
	v_pk_fma_f32 v[174:175], v[166:167], v[188:189], v[190:191]
	v_pk_fma_f32 v[176:177], v[168:169], v[188:189], v[190:191]
	v_pk_fma_f32 v[178:179], v[170:171], v[188:189], v[190:191]
	v_pk_fma_f32 v[172:173], v[172:173], v[164:165], v[192:193]
	v_pk_fma_f32 v[174:175], v[174:175], v[166:167], v[192:193]
	v_pk_fma_f32 v[176:177], v[176:177], v[168:169], v[192:193]
	v_pk_fma_f32 v[178:179], v[178:179], v[170:171], v[192:193]
	v_pk_fma_f32 v[172:173], v[172:173], v[164:165], v[194:195]
	v_pk_fma_f32 v[174:175], v[174:175], v[166:167], v[194:195]
	v_pk_fma_f32 v[176:177], v[176:177], v[168:169], v[194:195]
	v_pk_fma_f32 v[178:179], v[178:179], v[170:171], v[194:195]
	v_pk_fma_f32 v[172:173], v[172:173], v[164:165], v[196:197]
	v_pk_fma_f32 v[174:175], v[174:175], v[166:167], v[196:197]
	v_pk_fma_f32 v[176:177], v[176:177], v[168:169], v[196:197]
	v_pk_fma_f32 v[178:179], v[178:179], v[170:171], v[196:197]
	v_pk_mul_f32 v[172:173], v[172:173], v[164:165]
	v_pk_mul_f32 v[174:175], v[174:175], v[166:167]
	v_pk_mul_f32 v[176:177], v[176:177], v[168:169]
	v_pk_mul_f32 v[178:179], v[178:179], v[170:171]
	v_pk_mul_f32 v[164:165], v[148:149], v[148:149]
	v_pk_mul_f32 v[166:167], v[150:151], v[150:151]
	v_pk_mul_f32 v[168:169], v[152:153], v[152:153]
	v_pk_mul_f32 v[170:171], v[154:155], v[154:155]
	v_pk_mul_f32 v[164:165], v[164:165], v[198:199]
	v_pk_mul_f32 v[166:167], v[166:167], v[198:199]
	v_pk_mul_f32 v[168:169], v[168:169], v[198:199]
	v_pk_mul_f32 v[170:171], v[170:171], v[198:199]
	v_exp_f32_e32 v164, v164
	v_exp_f32_e32 v165, v165
	v_exp_f32_e32 v166, v166
	v_exp_f32_e32 v167, v167
	v_exp_f32_e32 v168, v168
	v_exp_f32_e32 v169, v169
	v_exp_f32_e32 v170, v170
	v_exp_f32_e32 v171, v171
	v_pk_mul_f32 v[172:173], v[172:173], v[164:165]
	v_pk_mul_f32 v[174:175], v[174:175], v[166:167]
; __device__ __forceinline__ unsigned cvt_pk_bf16(float lo, float hi) { unsigned r; asm volatile("v_cvt_pk_bf16_f32 %0, %1, %2" : "=v"(r) : "v"(lo), "v"(hi)); return r; }
; __device__ __forceinline__ float gelu_as(float v) {
;   const float av = fabsf(v); const float t = __builtin_amdgcn_rcpf(av * 0.2316418882f + 1.0f);
;   float q = t * 0.5307027145f + (-0.7265760135f); q = q * t + 0.7107068705f; q = q * t + (-0.142248368f); q = q * t + 0.127414796f; q = q * t;
;   const float e = __builtin_amdgcn_exp2f((v * v) * (-0.72134752044f));
;   const float m = v * (q * e);
;   return v < 0.f ? m : v - m;
; __device__ __forceinline__ void phase_conv(KP p, int l, int tid) {
;     ...
;       for (int q = 0; q < CB; ++q) { const int col = jb + q + 1; const int cl = col > 63 ? 63 : col;
; #pragma unroll
;         for (int di = 0; di < RB + 2; ++di) an[q][di] = *(const u32x2*)(rowp[di] + (size_t)cl * DFF);
; #pragma unroll
;         for (int rr = 0; rr < RB; ++rr) ur[q][rr] = *(const u32x2*)(U + (size_t)((r0 + rr) * 64 + jb + q) * DFF + c0); }
;       __builtin_amdgcn_sched_barrier(0);
; #pragma unroll
;       for (int q = 0; q < CB; ++q) {
;         const int col = jb + q + 1;
; #pragma unroll
;         for (int di = 0; di < RB + 2; ++di) { const bool ok = rv[di] && (col < 64); unpack4(an[q][di], win[2][di]);
; #pragma unroll
;           for (int k = 0; k < 4; ++k) win[2][di][k] = ok ? win[2][di][k] : 0.f; }
; #pragma unroll
;         for (int rr = 0; rr < RB; ++rr) {
;           float uv[4]; unpack4(ur[q][rr], uv);
;           float o[4];
; #pragma unroll
;           for (int k = 0; k < 4; ++k) {
;             float a = bsv[k];
; #pragma unroll
;             for (int di = 0; di < 3; ++di)
; #pragma unroll
;               for (int dj = 0; dj < 3; ++dj) a += win[dj][rr + di][k] * w[di * 3 + dj][k];
;             o[k] = gelu_as(a) * uv[k];
;           }
;           u32x2 ow; ow.x = cvt_pk_bf16(o[0], o[1]); ow.y = cvt_pk_bf16(o[2], o[3]);
;           *(u32x2*)(G + (size_t)((r0 + rr) * 64 + jb + q) * DFF + c0) = ow;
;         }
	v_pk_mul_f32 v[176:177], v[176:177], v[168:169]
	v_pk_mul_f32 v[178:179], v[178:179], v[170:171]
	v_pk_mul_f32 v[172:173], v[156:157], v[172:173]
	v_pk_mul_f32 v[174:175], v[158:159], v[174:175]
	v_pk_mul_f32 v[176:177], v[160:161], v[176:177]
	v_pk_mul_f32 v[178:179], v[162:163], v[178:179]
	v_max_f32_e32 v164, 0, v148
	v_max_f32_e32 v165, 0, v149
	v_max_f32_e32 v166, 0, v150
	v_max_f32_e32 v167, 0, v151
	v_max_f32_e32 v168, 0, v152
	v_max_f32_e32 v169, 0, v153
	v_max_f32_e32 v170, 0, v154
	v_max_f32_e32 v171, 0, v155
	v_pk_add_f32 v[164:165], v[164:165], v[172:173] neg_lo:[0,1] neg_hi:[0,1]
	v_pk_add_f32 v[166:167], v[166:167], v[174:175] neg_lo:[0,1] neg_hi:[0,1]
	v_pk_add_f32 v[168:169], v[168:169], v[176:177] neg_lo:[0,1] neg_hi:[0,1]
	v_pk_add_f32 v[170:171], v[170:171], v[178:179] neg_lo:[0,1] neg_hi:[0,1]
	v_pk_mul_f32 v[164:165], v[164:165], v[124:125]
	v_pk_mul_f32 v[166:167], v[166:167], v[126:127]
	v_pk_mul_f32 v[168:169], v[168:169], v[128:129]
	v_pk_mul_f32 v[170:171], v[170:171], v[130:131]
	v_cvt_pk_bf16_f32 v156, v164, v165
	v_cvt_pk_bf16_f32 v157, v166, v167
	v_cvt_pk_bf16_f32 v158, v168, v169
	v_cvt_pk_bf16_f32 v159, v170, v171
	global_store_dwordx2 v216, v[156:157], s[10:11]
	global_store_dwordx2 v217, v[158:159], s[10:11]
	v_add_u32_e32 v210, 0x2c00, v210
	v_add_u32_e32 v211, 0x2c00, v210
	v_add_u32_e32 v212, v206, v211
	global_load_dwordx2 v[88:89], v212, s[6:7]
	v_add_u32_e32 v213, v207, v211
	global_load_dwordx2 v[90:91], v213, s[6:7]
	v_add_u32_e32 v214, v208, v211
	global_load_dwordx2 v[92:93], v214, s[6:7]
	v_add_u32_e32 v215, v209, v211
	global_load_dwordx2 v[94:95], v215, s[6:7]
	v_add_u32_e32 v216, v207, v210
	global_load_dwordx2 v[112:113], v216, s[8:9] nt
	v_add_u32_e32 v217, v208, v210
	global_load_dwordx2 v[114:115], v217, s[8:9] nt
	s_waitcnt vmcnt(16)
	v_lshlrev_b32_e32 v40, 16, v96
	v_and_b32_e32 v41, 0xffff0000, v96
	v_lshlrev_b32_e32 v42, 16, v97
	v_and_b32_e32 v43, 0xffff0000, v97
	v_lshlrev_b32_e32 v44, 16, v98
	v_and_b32_e32 v45, 0xffff0000, v98
	v_lshlrev_b32_e32 v46, 16, v99
	v_and_b32_e32 v47, 0xffff0000, v99
	v_lshlrev_b32_e32 v48, 16, v100
	v_and_b32_e32 v49, 0xffff0000, v100
	v_lshlrev_b32_e32 v50, 16, v101
	v_and_b32_e32 v51, 0xffff0000, v101
	v_lshlrev_b32_e32 v52, 16, v102
	v_and_b32_e32 v53, 0xffff0000, v102
	v_lshlrev_b32_e32 v54, 16, v103
	v_and_b32_e32 v55, 0xffff0000, v103
	v_pk_mul_f32 v[40:41], v[40:41], v[200:201]
	v_pk_mul_f32 v[42:43], v[42:43], v[200:201]
	v_pk_mul_f32 v[52:53], v[52:53], v[202:203]
	v_pk_mul_f32 v[54:55], v[54:55], v[202:203]
	v_lshlrev_b32_e32 v124, 16, v116
	v_and_b32_e32 v125, 0xffff0000, v116
	v_lshlrev_b32_e32 v126, 16, v117
	v_and_b32_e32 v127, 0xffff0000, v117
	v_lshlrev_b32_e32 v128, 16, v118
	v_and_b32_e32 v129, 0xffff0000, v118
	v_lshlrev_b32_e32 v130, 16, v119
	v_and_b32_e32 v131, 0xffff0000, v119
	v_pk_fma_f32 v[148:149], v[56:57], v[0:1], v[36:37]
	v_pk_fma_f32 v[150:151], v[58:59], v[2:3], v[38:39]
	v_pk_fma_f32 v[152:153], v[60:61], v[0:1], v[36:37]
	v_pk_fma_f32 v[154:155], v[62:63], v[2:3], v[38:39]
	v_pk_fma_f32 v[148:149], v[72:73], v[4:5], v[148:149]
	v_pk_fma_f32 v[150:151], v[74:75], v[6:7], v[150:151]
	v_pk_fma_f32 v[152:153], v[76:77], v[4:5], v[152:153]
	v_pk_fma_f32 v[154:155], v[78:79], v[6:7], v[154:155]
	v_pk_fma_f32 v[148:149], v[40:41], v[8:9], v[148:149]
	v_pk_fma_f32 v[150:151], v[42:43], v[10:11], v[150:151]
	v_pk_fma_f32 v[152:153], v[44:45], v[8:9], v[152:153]
	v_pk_fma_f32 v[154:155], v[46:47], v[10:11], v[154:155]
	v_pk_fma_f32 v[148:149], v[60:61], v[12:13], v[148:149]
	v_pk_fma_f32 v[150:151], v[62:63], v[14:15], v[150:151]
	v_pk_fma_f32 v[152:153], v[64:65], v[12:13], v[152:153]
	v_pk_fma_f32 v[154:155], v[66:67], v[14:15], v[154:155]
	v_pk_fma_f32 v[148:149], v[76:77], v[16:17], v[148:149]
	v_pk_fma_f32 v[150:151], v[78:79], v[18:19], v[150:151]
	v_pk_fma_f32 v[152:153], v[80:81], v[16:17], v[152:153]
	v_pk_fma_f32 v[154:155], v[82:83], v[18:19], v[154:155]
	v_pk_fma_f32 v[148:149], v[44:45], v[20:21], v[148:149]
	v_pk_fma_f32 v[150:151], v[46:47], v[22:23], v[150:151]
	v_pk_fma_f32 v[152:153], v[48:49], v[20:21], v[152:153]
	v_pk_fma_f32 v[154:155], v[50:51], v[22:23], v[154:155]
	v_pk_fma_f32 v[148:149], v[64:65], v[24:25], v[148:149]
	v_pk_fma_f32 v[150:151], v[66:67], v[26:27], v[150:151]
	v_pk_fma_f32 v[152:153], v[68:69], v[24:25], v[152:153]
	v_pk_fma_f32 v[154:155], v[70:71], v[26:27], v[154:155]
	v_pk_fma_f32 v[148:149], v[80:81], v[28:29], v[148:149]
	v_pk_fma_f32 v[150:151], v[82:83], v[30:31], v[150:151]
	v_pk_fma_f32 v[152:153], v[84:85], v[28:29], v[152:153]
	v_pk_fma_f32 v[154:155], v[86:87], v[30:31], v[154:155]
	v_pk_fma_f32 v[148:149], v[48:49], v[32:33], v[148:149]
	v_pk_fma_f32 v[150:151], v[50:51], v[34:35], v[150:151]
	v_pk_fma_f32 v[152:153], v[52:53], v[32:33], v[152:153]
	v_pk_fma_f32 v[154:155], v[54:55], v[34:35], v[154:155]
	v_and_b32_e32 v156, 0x7fffffff, v148
	v_and_b32_e32 v157, 0x7fffffff, v149
	v_and_b32_e32 v158, 0x7fffffff, v150
	v_and_b32_e32 v159, 0x7fffffff, v151
	v_and_b32_e32 v160, 0x7fffffff, v152
	v_and_b32_e32 v161, 0x7fffffff, v153
	v_and_b32_e32 v162, 0x7fffffff, v154
	v_and_b32_e32 v163, 0x7fffffff, v155
	v_pk_fma_f32 v[164:165], v[156:157], v[184:185], v[186:187]
	v_pk_fma_f32 v[166:167], v[158:159], v[184:185], v[186:187]
	v_pk_fma_f32 v[168:169], v[160:161], v[184:185], v[186:187]
	v_pk_fma_f32 v[170:171], v[162:163], v[184:185], v[186:187]
	v_rcp_f32_e32 v164, v164
	v_rcp_f32_e32 v165, v165
	v_rcp_f32_e32 v166, v166
	v_rcp_f32_e32 v167, v167
	v_rcp_f32_e32 v168, v168
	v_rcp_f32_e32 v169, v169
	v_rcp_f32_e32 v170, v170
	v_rcp_f32_e32 v171, v171
; __device__ __forceinline__ unsigned cvt_pk_bf16(float lo, float hi) { unsigned r; asm volatile("v_cvt_pk_bf16_f32 %0, %1, %2" : "=v"(r) : "v"(lo), "v"(hi)); return r; }
; __device__ __forceinline__ float gelu_as(float v) {
;   const float av = fabsf(v); const float t = __builtin_amdgcn_rcpf(av * 0.2316418882f + 1.0f);
;   float q = t * 0.5307027145f + (-0.7265760135f); q = q * t + 0.7107068705f; q = q * t + (-0.142248368f); q = q * t + 0.127414796f; q = q * t;
;   const float e = __builtin_amdgcn_exp2f((v * v) * (-0.72134752044f));
;   const float m = v * (q * e);
;   return v < 0.f ? m : v - m;
; __device__ __forceinline__ void phase_conv(KP p, int l, int tid) {
;     ...
;       for (int q = 0; q < CB; ++q) { const int col = jb + q + 1; const int cl = col > 63 ? 63 : col;
; #pragma unroll
;         for (int di = 0; di < RB + 2; ++di) an[q][di] = *(const u32x2*)(rowp[di] + (size_t)cl * DFF);
; #pragma unroll
;         for (int rr = 0; rr < RB; ++rr) ur[q][rr] = *(const u32x2*)(U + (size_t)((r0 + rr) * 64 + jb + q) * DFF + c0); }
;       __builtin_amdgcn_sched_barrier(0);
; #pragma unroll
;       for (int q = 0; q < CB; ++q) {
;         const int col = jb + q + 1;
; #pragma unroll
;         for (int di = 0; di < RB + 2; ++di) { const bool ok = rv[di] && (col < 64); unpack4(an[q][di], win[2][di]);
; #pragma unroll
;           for (int k = 0; k < 4; ++k) win[2][di][k] = ok ? win[2][di][k] : 0.f; }
; #pragma unroll
;         for (int rr = 0; rr < RB; ++rr) {
;           float uv[4]; unpack4(ur[q][rr], uv);
;           float o[4];
; #pragma unroll
;           for (int k = 0; k < 4; ++k) {
;             float a = bsv[k];
; #pragma unroll
;             for (int di = 0; di < 3; ++di)
; #pragma unroll
;               for (int dj = 0; dj < 3; ++dj) a += win[dj][rr + di][k] * w[di * 3 + dj][k];
;             o[k] = gelu_as(a) * uv[k];
;           }
;           u32x2 ow; ow.x = cvt_pk_bf16(o[0], o[1]); ow.y = cvt_pk_bf16(o[2], o[3]);
;           *(u32x2*)(G + (size_t)((r0 + rr) * 64 + jb + q) * DFF + c0) = ow;
;         }
	v_pk_fma_f32 v[172:173], v[164:165], v[188:189], v[190:191]
	v_pk_fma_f32 v[174:175], v[166:167], v[188:189], v[190:191]
	v_pk_fma_f32 v[176:177], v[168:169], v[188:189], v[190:191]
	v_pk_fma_f32 v[178:179], v[170:171], v[188:189], v[190:191]
	v_pk_fma_f32 v[172:173], v[172:173], v[164:165], v[192:193]
	v_pk_fma_f32 v[174:175], v[174:175], v[166:167], v[192:193]
	v_pk_fma_f32 v[176:177], v[176:177], v[168:169], v[192:193]
	v_pk_fma_f32 v[178:179], v[178:179], v[170:171], v[192:193]
	v_pk_fma_f32 v[172:173], v[172:173], v[164:165], v[194:195]
	v_pk_fma_f32 v[174:175], v[174:175], v[166:167], v[194:195]
	v_pk_fma_f32 v[176:177], v[176:177], v[168:169], v[194:195]
	v_pk_fma_f32 v[178:179], v[178:179], v[170:171], v[194:195]
	v_pk_fma_f32 v[172:173], v[172:173], v[164:165], v[196:197]
	v_pk_fma_f32 v[174:175], v[174:175], v[166:167], v[196:197]
	v_pk_fma_f32 v[176:177], v[176:177], v[168:169], v[196:197]
	v_pk_fma_f32 v[178:179], v[178:179], v[170:171], v[196:197]
	v_pk_mul_f32 v[172:173], v[172:173], v[164:165]
	v_pk_mul_f32 v[174:175], v[174:175], v[166:167]
	v_pk_mul_f32 v[176:177], v[176:177], v[168:169]
	v_pk_mul_f32 v[178:179], v[178:179], v[170:171]
	v_pk_mul_f32 v[164:165], v[148:149], v[148:149]
	v_pk_mul_f32 v[166:167], v[150:151], v[150:151]
	v_pk_mul_f32 v[168:169], v[152:153], v[152:153]
	v_pk_mul_f32 v[170:171], v[154:155], v[154:155]
	v_pk_mul_f32 v[164:165], v[164:165], v[198:199]
	v_pk_mul_f32 v[166:167], v[166:167], v[198:199]
	v_pk_mul_f32 v[168:169], v[168:169], v[198:199]
	v_pk_mul_f32 v[170:171], v[170:171], v[198:199]
	v_exp_f32_e32 v164, v164
	v_exp_f32_e32 v165, v165
	v_exp_f32_e32 v166, v166
	v_exp_f32_e32 v167, v167
	v_exp_f32_e32 v168, v168
	v_exp_f32_e32 v169, v169
	v_exp_f32_e32 v170, v170
	v_exp_f32_e32 v171, v171
	v_pk_mul_f32 v[172:173], v[172:173], v[164:165]
	v_pk_mul_f32 v[174:175], v[174:175], v[166:167]
	v_pk_mul_f32 v[176:177], v[176:177], v[168:169]
	v_pk_mul_f32 v[178:179], v[178:179], v[170:171]
	v_pk_mul_f32 v[172:173], v[156:157], v[172:173]
	v_pk_mul_f32 v[174:175], v[158:159], v[174:175]
	v_pk_mul_f32 v[176:177], v[160:161], v[176:177]
	v_pk_mul_f32 v[178:179], v[162:163], v[178:179]
	v_max_f32_e32 v164, 0, v148
	v_max_f32_e32 v165, 0, v149
	v_max_f32_e32 v166, 0, v150
	v_max_f32_e32 v167, 0, v151
	v_max_f32_e32 v168, 0, v152
	v_max_f32_e32 v169, 0, v153
	v_max_f32_e32 v170, 0, v154
	v_max_f32_e32 v171, 0, v155
	v_pk_add_f32 v[164:165], v[164:165], v[172:173] neg_lo:[0,1] neg_hi:[0,1]
	v_pk_add_f32 v[166:167], v[166:167], v[174:175] neg_lo:[0,1] neg_hi:[0,1]
	v_pk_add_f32 v[168:169], v[168:169], v[176:177] neg_lo:[0,1] neg_hi:[0,1]
	v_pk_add_f32 v[170:171], v[170:171], v[178:179] neg_lo:[0,1] neg_hi:[0,1]
	v_pk_mul_f32 v[164:165], v[164:165], v[124:125]
	v_pk_mul_f32 v[166:167], v[166:167], v[126:127]
	v_pk_mul_f32 v[168:169], v[168:169], v[128:129]
	v_pk_mul_f32 v[170:171], v[170:171], v[130:131]
	v_cvt_pk_bf16_f32 v156, v164, v165
	v_cvt_pk_bf16_f32 v157, v166, v167
	v_cvt_pk_bf16_f32 v158, v168, v169
	v_cvt_pk_bf16_f32 v159, v170, v171
	global_store_dwordx2 v218, v[156:157], s[10:11]
	global_store_dwordx2 v219, v[158:159], s[10:11]
	v_add_u32_e32 v210, 0x2c00, v210
	v_add_u32_e32 v211, 0x2c00, v210
	v_add_u32_e32 v212, v206, v211
	global_load_dwordx2 v[96:97], v212, s[6:7]
	v_add_u32_e32 v213, v207, v211
	global_load_dwordx2 v[98:99], v213, s[6:7]
	v_add_u32_e32 v214, v208, v211
	global_load_dwordx2 v[100:101], v214, s[6:7]
	v_add_u32_e32 v215, v209, v211
	global_load_dwordx2 v[102:103], v215, s[6:7]
	v_add_u32_e32 v218, v207, v210
	global_load_dwordx2 v[116:117], v218, s[8:9] nt
	v_add_u32_e32 v219, v208, v210
	global_load_dwordx2 v[118:119], v219, s[8:9] nt
	s_waitcnt vmcnt(16)
	v_lshlrev_b32_e32 v56, 16, v104
	v_and_b32_e32 v57, 0xffff0000, v104
	v_lshlrev_b32_e32 v58, 16, v105
	v_and_b32_e32 v59, 0xffff0000, v105
	v_lshlrev_b32_e32 v60, 16, v106
	v_and_b32_e32 v61, 0xffff0000, v106
	v_lshlrev_b32_e32 v62, 16, v107
	v_and_b32_e32 v63, 0xffff0000, v107
	v_lshlrev_b32_e32 v64, 16, v108
	v_and_b32_e32 v65, 0xffff0000, v108
	v_lshlrev_b32_e32 v66, 16, v109
	v_and_b32_e32 v67, 0xffff0000, v109
	v_lshlrev_b32_e32 v68, 16, v110
	v_and_b32_e32 v69, 0xffff0000, v110
	v_lshlrev_b32_e32 v70, 16, v111
	v_and_b32_e32 v71, 0xffff0000, v111
	v_pk_mul_f32 v[56:57], v[56:57], v[200:201]
	v_pk_mul_f32 v[58:59], v[58:59], v[200:201]
	v_pk_mul_f32 v[68:69], v[68:69], v[202:203]
	v_pk_mul_f32 v[70:71], v[70:71], v[202:203]
	v_lshlrev_b32_e32 v124, 16, v120
	v_and_b32_e32 v125, 0xffff0000, v120
	v_lshlrev_b32_e32 v126, 16, v121
	v_and_b32_e32 v127, 0xffff0000, v121
	v_lshlrev_b32_e32 v128, 16, v122
	v_and_b32_e32 v129, 0xffff0000, v122
	v_lshlrev_b32_e32 v130, 16, v123
	v_and_b32_e32 v131, 0xffff0000, v123
	v_pk_fma_f32 v[148:149], v[72:73], v[0:1], v[36:37]
	v_pk_fma_f32 v[150:151], v[74:75], v[2:3], v[38:39]
	v_pk_fma_f32 v[152:153], v[76:77], v[0:1], v[36:37]
	v_pk_fma_f32 v[154:155], v[78:79], v[2:3], v[38:39]
	v_pk_fma_f32 v[148:149], v[40:41], v[4:5], v[148:149]
	v_pk_fma_f32 v[150:151], v[42:43], v[6:7], v[150:151]
	v_pk_fma_f32 v[152:153], v[44:45], v[4:5], v[152:153]
	v_pk_fma_f32 v[154:155], v[46:47], v[6:7], v[154:155]
	v_pk_fma_f32 v[148:149], v[56:57], v[8:9], v[148:149]
	v_pk_fma_f32 v[150:151], v[58:59], v[10:11], v[150:151]
	v_pk_fma_f32 v[152:153], v[60:61], v[8:9], v[152:153]
	v_pk_fma_f32 v[154:155], v[62:63], v[10:11], v[154:155]
	v_pk_fma_f32 v[148:149], v[76:77], v[12:13], v[148:149]
	v_pk_fma_f32 v[150:151], v[78:79], v[14:15], v[150:151]
	v_pk_fma_f32 v[152:153], v[80:81], v[12:13], v[152:153]
	v_pk_fma_f32 v[154:155], v[82:83], v[14:15], v[154:155]
	v_pk_fma_f32 v[148:149], v[44:45], v[16:17], v[148:149]
; __device__ __forceinline__ unsigned cvt_pk_bf16(float lo, float hi) { unsigned r; asm volatile("v_cvt_pk_bf16_f32 %0, %1, %2" : "=v"(r) : "v"(lo), "v"(hi)); return r; }
; __device__ __forceinline__ float gelu_as(float v) {
;   const float av = fabsf(v); const float t = __builtin_amdgcn_rcpf(av * 0.2316418882f + 1.0f);
;   float q = t * 0.5307027145f + (-0.7265760135f); q = q * t + 0.7107068705f; q = q * t + (-0.142248368f); q = q * t + 0.127414796f; q = q * t;
;   const float e = __builtin_amdgcn_exp2f((v * v) * (-0.72134752044f));
;   const float m = v * (q * e);
;   return v < 0.f ? m : v - m;
; __device__ __forceinline__ void phase_conv(KP p, int l, int tid) {
;     ...
;       for (int q = 0; q < CB; ++q) { const int col = jb + q + 1; const int cl = col > 63 ? 63 : col;
; #pragma unroll
;         for (int di = 0; di < RB + 2; ++di) an[q][di] = *(const u32x2*)(rowp[di] + (size_t)cl * DFF);
; #pragma unroll
;         for (int rr = 0; rr < RB; ++rr) ur[q][rr] = *(const u32x2*)(U + (size_t)((r0 + rr) * 64 + jb + q) * DFF + c0); }
;       __builtin_amdgcn_sched_barrier(0);
; #pragma unroll
;       for (int q = 0; q < CB; ++q) {
;         const int col = jb + q + 1;
; #pragma unroll
;         for (int di = 0; di < RB + 2; ++di) { const bool ok = rv[di] && (col < 64); unpack4(an[q][di], win[2][di]);
; #pragma unroll
;           for (int k = 0; k < 4; ++k) win[2][di][k] = ok ? win[2][di][k] : 0.f; }
; #pragma unroll
;         for (int rr = 0; rr < RB; ++rr) {
;           float uv[4]; unpack4(ur[q][rr], uv);
;           float o[4];
; #pragma unroll
;           for (int k = 0; k < 4; ++k) {
;             float a = bsv[k];
; #pragma unroll
;             for (int di = 0; di < 3; ++di)
; #pragma unroll
;               for (int dj = 0; dj < 3; ++dj) a += win[dj][rr + di][k] * w[di * 3 + dj][k];
;             o[k] = gelu_as(a) * uv[k];
;           }
;           u32x2 ow; ow.x = cvt_pk_bf16(o[0], o[1]); ow.y = cvt_pk_bf16(o[2], o[3]);
;           *(u32x2*)(G + (size_t)((r0 + rr) * 64 + jb + q) * DFF + c0) = ow;
;         }
	v_pk_fma_f32 v[150:151], v[46:47], v[18:19], v[150:151]
	v_pk_fma_f32 v[152:153], v[48:49], v[16:17], v[152:153]
	v_pk_fma_f32 v[154:155], v[50:51], v[18:19], v[154:155]
	v_pk_fma_f32 v[148:149], v[60:61], v[20:21], v[148:149]
	v_pk_fma_f32 v[150:151], v[62:63], v[22:23], v[150:151]
	v_pk_fma_f32 v[152:153], v[64:65], v[20:21], v[152:153]
	v_pk_fma_f32 v[154:155], v[66:67], v[22:23], v[154:155]
	v_pk_fma_f32 v[148:149], v[80:81], v[24:25], v[148:149]
	v_pk_fma_f32 v[150:151], v[82:83], v[26:27], v[150:151]
	v_pk_fma_f32 v[152:153], v[84:85], v[24:25], v[152:153]
	v_pk_fma_f32 v[154:155], v[86:87], v[26:27], v[154:155]
	v_pk_fma_f32 v[148:149], v[48:49], v[28:29], v[148:149]
	v_pk_fma_f32 v[150:151], v[50:51], v[30:31], v[150:151]
	v_pk_fma_f32 v[152:153], v[52:53], v[28:29], v[152:153]
	v_pk_fma_f32 v[154:155], v[54:55], v[30:31], v[154:155]
	v_pk_fma_f32 v[148:149], v[64:65], v[32:33], v[148:149]
	v_pk_fma_f32 v[150:151], v[66:67], v[34:35], v[150:151]
	v_pk_fma_f32 v[152:153], v[68:69], v[32:33], v[152:153]
	v_pk_fma_f32 v[154:155], v[70:71], v[34:35], v[154:155]
	v_and_b32_e32 v156, 0x7fffffff, v148
	v_and_b32_e32 v157, 0x7fffffff, v149
	v_and_b32_e32 v158, 0x7fffffff, v150
	v_and_b32_e32 v159, 0x7fffffff, v151
	v_and_b32_e32 v160, 0x7fffffff, v152
	v_and_b32_e32 v161, 0x7fffffff, v153
	v_and_b32_e32 v162, 0x7fffffff, v154
	v_and_b32_e32 v163, 0x7fffffff, v155
	v_pk_fma_f32 v[164:165], v[156:157], v[184:185], v[186:187]
	v_pk_fma_f32 v[166:167], v[158:159], v[184:185], v[186:187]
	v_pk_fma_f32 v[168:169], v[160:161], v[184:185], v[186:187]
	v_pk_fma_f32 v[170:171], v[162:163], v[184:185], v[186:187]
	v_rcp_f32_e32 v164, v164
	v_rcp_f32_e32 v165, v165
	v_rcp_f32_e32 v166, v166
	v_rcp_f32_e32 v167, v167
	v_rcp_f32_e32 v168, v168
	v_rcp_f32_e32 v169, v169
	v_rcp_f32_e32 v170, v170
	v_rcp_f32_e32 v171, v171
	v_pk_fma_f32 v[172:173], v[164:165], v[188:189], v[190:191]
	v_pk_fma_f32 v[174:175], v[166:167], v[188:189], v[190:191]
	v_pk_fma_f32 v[176:177], v[168:169], v[188:189], v[190:191]
	v_pk_fma_f32 v[178:179], v[170:171], v[188:189], v[190:191]
	v_pk_fma_f32 v[172:173], v[172:173], v[164:165], v[192:193]
	v_pk_fma_f32 v[174:175], v[174:175], v[166:167], v[192:193]
	v_pk_fma_f32 v[176:177], v[176:177], v[168:169], v[192:193]
	v_pk_fma_f32 v[178:179], v[178:179], v[170:171], v[192:193]
	v_pk_fma_f32 v[172:173], v[172:173], v[164:165], v[194:195]
	v_pk_fma_f32 v[174:175], v[174:175], v[166:167], v[194:195]
	v_pk_fma_f32 v[176:177], v[176:177], v[168:169], v[194:195]
	v_pk_fma_f32 v[178:179], v[178:179], v[170:171], v[194:195]
	v_pk_fma_f32 v[172:173], v[172:173], v[164:165], v[196:197]
	v_pk_fma_f32 v[174:175], v[174:175], v[166:167], v[196:197]
	v_pk_fma_f32 v[176:177], v[176:177], v[168:169], v[196:197]
	v_pk_fma_f32 v[178:179], v[178:179], v[170:171], v[196:197]
	v_pk_mul_f32 v[172:173], v[172:173], v[164:165]
	v_pk_mul_f32 v[174:175], v[174:175], v[166:167]
	v_pk_mul_f32 v[176:177], v[176:177], v[168:169]
	v_pk_mul_f32 v[178:179], v[178:179], v[170:171]
	v_pk_mul_f32 v[164:165], v[148:149], v[148:149]
	v_pk_mul_f32 v[166:167], v[150:151], v[150:151]
	v_pk_mul_f32 v[168:169], v[152:153], v[152:153]
	v_pk_mul_f32 v[170:171], v[154:155], v[154:155]
	v_pk_mul_f32 v[164:165], v[164:165], v[198:199]
	v_pk_mul_f32 v[166:167], v[166:167], v[198:199]
	v_pk_mul_f32 v[168:169], v[168:169], v[198:199]
	v_pk_mul_f32 v[170:171], v[170:171], v[198:199]
	v_exp_f32_e32 v164, v164
	v_exp_f32_e32 v165, v165
	v_exp_f32_e32 v166, v166
	v_exp_f32_e32 v167, v167
	v_exp_f32_e32 v168, v168
	v_exp_f32_e32 v169, v169
	v_exp_f32_e32 v170, v170
	v_exp_f32_e32 v171, v171
	v_pk_mul_f32 v[172:173], v[172:173], v[164:165]
	v_pk_mul_f32 v[174:175], v[174:175], v[166:167]
	v_pk_mul_f32 v[176:177], v[176:177], v[168:169]
	v_pk_mul_f32 v[178:179], v[178:179], v[170:171]
	v_pk_mul_f32 v[172:173], v[156:157], v[172:173]
	v_pk_mul_f32 v[174:175], v[158:159], v[174:175]
	v_pk_mul_f32 v[176:177], v[160:161], v[176:177]
	v_pk_mul_f32 v[178:179], v[162:163], v[178:179]
	v_max_f32_e32 v164, 0, v148
	v_max_f32_e32 v165, 0, v149
	v_max_f32_e32 v166, 0, v150
	v_max_f32_e32 v167, 0, v151
	v_max_f32_e32 v168, 0, v152
	v_max_f32_e32 v169, 0, v153
	v_max_f32_e32 v170, 0, v154
	v_max_f32_e32 v171, 0, v155
	v_pk_add_f32 v[164:165], v[164:165], v[172:173] neg_lo:[0,1] neg_hi:[0,1]
	v_pk_add_f32 v[166:167], v[166:167], v[174:175] neg_lo:[0,1] neg_hi:[0,1]
	v_pk_add_f32 v[168:169], v[168:169], v[176:177] neg_lo:[0,1] neg_hi:[0,1]
	v_pk_add_f32 v[170:171], v[170:171], v[178:179] neg_lo:[0,1] neg_hi:[0,1]
	v_pk_mul_f32 v[164:165], v[164:165], v[124:125]
	v_pk_mul_f32 v[166:167], v[166:167], v[126:127]
	v_pk_mul_f32 v[168:169], v[168:169], v[128:129]
	v_pk_mul_f32 v[170:171], v[170:171], v[130:131]
	v_cvt_pk_bf16_f32 v156, v164, v165
	v_cvt_pk_bf16_f32 v157, v166, v167
	v_cvt_pk_bf16_f32 v158, v168, v169
	v_cvt_pk_bf16_f32 v159, v170, v171
	global_store_dwordx2 v220, v[156:157], s[10:11]
	global_store_dwordx2 v221, v[158:159], s[10:11]
	v_add_u32_e32 v210, 0x2c00, v210
	v_add_u32_e32 v211, 0x2c00, v210
	v_add_u32_e32 v212, v206, v211
	global_load_dwordx2 v[104:105], v212, s[6:7]
	v_add_u32_e32 v213, v207, v211
	global_load_dwordx2 v[106:107], v213, s[6:7]
	v_add_u32_e32 v214, v208, v211
	global_load_dwordx2 v[108:109], v214, s[6:7]
	v_add_u32_e32 v215, v209, v211
	global_load_dwordx2 v[110:111], v215, s[6:7]
	v_add_u32_e32 v220, v207, v210
	global_load_dwordx2 v[120:121], v220, s[8:9] nt
	v_add_u32_e32 v221, v208, v210
	global_load_dwordx2 v[122:123], v221, s[8:9] nt
	s_waitcnt vmcnt(16)
; __device__ __forceinline__ unsigned cvt_pk_bf16(float lo, float hi) { unsigned r; asm volatile("v_cvt_pk_bf16_f32 %0, %1, %2" : "=v"(r) : "v"(lo), "v"(hi)); return r; }
; __device__ __forceinline__ float gelu_as(float v) {
;   const float av = fabsf(v); const float t = __builtin_amdgcn_rcpf(av * 0.2316418882f + 1.0f);
;   float q = t * 0.5307027145f + (-0.7265760135f); q = q * t + 0.7107068705f; q = q * t + (-0.142248368f); q = q * t + 0.127414796f; q = q * t;
;   const float e = __builtin_amdgcn_exp2f((v * v) * (-0.72134752044f));
;   const float m = v * (q * e);
;   return v < 0.f ? m : v - m;
; __device__ __forceinline__ void phase_conv(KP p, int l, int tid) {
;     ...
;       for (int q = 0; q < CB; ++q) { const int col = jb + q + 1; const int cl = col > 63 ? 63 : col;
; #pragma unroll
;         for (int di = 0; di < RB + 2; ++di) an[q][di] = *(const u32x2*)(rowp[di] + (size_t)cl * DFF);
; #pragma unroll
;         for (int rr = 0; rr < RB; ++rr) ur[q][rr] = *(const u32x2*)(U + (size_t)((r0 + rr) * 64 + jb + q) * DFF + c0); }
;       __builtin_amdgcn_sched_barrier(0);
; #pragma unroll
;       for (int q = 0; q < CB; ++q) {
;         const int col = jb + q + 1;
; #pragma unroll
;         for (int di = 0; di < RB + 2; ++di) { const bool ok = rv[di] && (col < 64); unpack4(an[q][di], win[2][di]);
; #pragma unroll
;           for (int k = 0; k < 4; ++k) win[2][di][k] = ok ? win[2][di][k] : 0.f; }
; #pragma unroll
;         for (int rr = 0; rr < RB; ++rr) {
;           float uv[4]; unpack4(ur[q][rr], uv);
;           float o[4];
; #pragma unroll
;           for (int k = 0; k < 4; ++k) {
;             float a = bsv[k];
; #pragma unroll
;             for (int di = 0; di < 3; ++di)
; #pragma unroll
;               for (int dj = 0; dj < 3; ++dj) a += win[dj][rr + di][k] * w[di * 3 + dj][k];
;             o[k] = gelu_as(a) * uv[k];
;           }
;           u32x2 ow; ow.x = cvt_pk_bf16(o[0], o[1]); ow.y = cvt_pk_bf16(o[2], o[3]);
;           *(u32x2*)(G + (size_t)((r0 + rr) * 64 + jb + q) * DFF + c0) = ow;
;         }
	v_lshlrev_b32_e32 v72, 16, v88
	v_and_b32_e32 v73, 0xffff0000, v88
	v_lshlrev_b32_e32 v74, 16, v89
	v_and_b32_e32 v75, 0xffff0000, v89
	v_lshlrev_b32_e32 v76, 16, v90
	v_and_b32_e32 v77, 0xffff0000, v90
	v_lshlrev_b32_e32 v78, 16, v91
	v_and_b32_e32 v79, 0xffff0000, v91
	v_lshlrev_b32_e32 v80, 16, v92
	v_and_b32_e32 v81, 0xffff0000, v92
	v_lshlrev_b32_e32 v82, 16, v93
	v_and_b32_e32 v83, 0xffff0000, v93
	v_lshlrev_b32_e32 v84, 16, v94
	v_and_b32_e32 v85, 0xffff0000, v94
	v_lshlrev_b32_e32 v86, 16, v95
	v_and_b32_e32 v87, 0xffff0000, v95
	v_pk_mul_f32 v[72:73], v[72:73], v[200:201]
	v_pk_mul_f32 v[74:75], v[74:75], v[200:201]
	v_pk_mul_f32 v[84:85], v[84:85], v[202:203]
	v_pk_mul_f32 v[86:87], v[86:87], v[202:203]
	v_lshlrev_b32_e32 v124, 16, v112
	v_and_b32_e32 v125, 0xffff0000, v112
	v_lshlrev_b32_e32 v126, 16, v113
	v_and_b32_e32 v127, 0xffff0000, v113
	v_lshlrev_b32_e32 v128, 16, v114
	v_and_b32_e32 v129, 0xffff0000, v114
	v_lshlrev_b32_e32 v130, 16, v115
	v_and_b32_e32 v131, 0xffff0000, v115
	v_pk_fma_f32 v[148:149], v[40:41], v[0:1], v[36:37]
	v_pk_fma_f32 v[150:151], v[42:43], v[2:3], v[38:39]
	v_pk_fma_f32 v[152:153], v[44:45], v[0:1], v[36:37]
	v_pk_fma_f32 v[154:155], v[46:47], v[2:3], v[38:39]
	v_pk_fma_f32 v[148:149], v[56:57], v[4:5], v[148:149]
	v_pk_fma_f32 v[150:151], v[58:59], v[6:7], v[150:151]
	v_pk_fma_f32 v[152:153], v[60:61], v[4:5], v[152:153]
	v_pk_fma_f32 v[154:155], v[62:63], v[6:7], v[154:155]
	v_pk_fma_f32 v[148:149], v[72:73], v[8:9], v[148:149]
	v_pk_fma_f32 v[150:151], v[74:75], v[10:11], v[150:151]
	v_pk_fma_f32 v[152:153], v[76:77], v[8:9], v[152:153]
	v_pk_fma_f32 v[154:155], v[78:79], v[10:11], v[154:155]
	v_pk_fma_f32 v[148:149], v[44:45], v[12:13], v[148:149]
	v_pk_fma_f32 v[150:151], v[46:47], v[14:15], v[150:151]
	v_pk_fma_f32 v[152:153], v[48:49], v[12:13], v[152:153]
	v_pk_fma_f32 v[154:155], v[50:51], v[14:15], v[154:155]
	v_pk_fma_f32 v[148:149], v[60:61], v[16:17], v[148:149]
	v_pk_fma_f32 v[150:151], v[62:63], v[18:19], v[150:151]
	v_pk_fma_f32 v[152:153], v[64:65], v[16:17], v[152:153]
	v_pk_fma_f32 v[154:155], v[66:67], v[18:19], v[154:155]
	v_pk_fma_f32 v[148:149], v[76:77], v[20:21], v[148:149]
	v_pk_fma_f32 v[150:151], v[78:79], v[22:23], v[150:151]
	v_pk_fma_f32 v[152:153], v[80:81], v[20:21], v[152:153]
	v_pk_fma_f32 v[154:155], v[82:83], v[22:23], v[154:155]
	v_pk_fma_f32 v[148:149], v[48:49], v[24:25], v[148:149]
	v_pk_fma_f32 v[150:151], v[50:51], v[26:27], v[150:151]
	v_pk_fma_f32 v[152:153], v[52:53], v[24:25], v[152:153]
	v_pk_fma_f32 v[154:155], v[54:55], v[26:27], v[154:155]
	v_pk_fma_f32 v[148:149], v[64:65], v[28:29], v[148:149]
	v_pk_fma_f32 v[150:151], v[66:67], v[30:31], v[150:151]
	v_pk_fma_f32 v[152:153], v[68:69], v[28:29], v[152:153]
	v_pk_fma_f32 v[154:155], v[70:71], v[30:31], v[154:155]
	v_pk_fma_f32 v[148:149], v[80:81], v[32:33], v[148:149]
	v_pk_fma_f32 v[150:151], v[82:83], v[34:35], v[150:151]
	v_pk_fma_f32 v[152:153], v[84:85], v[32:33], v[152:153]
	v_pk_fma_f32 v[154:155], v[86:87], v[34:35], v[154:155]
	v_and_b32_e32 v156, 0x7fffffff, v148
	v_and_b32_e32 v157, 0x7fffffff, v149
	v_and_b32_e32 v158, 0x7fffffff, v150
	v_and_b32_e32 v159, 0x7fffffff, v151
	v_and_b32_e32 v160, 0x7fffffff, v152
	v_and_b32_e32 v161, 0x7fffffff, v153
	v_and_b32_e32 v162, 0x7fffffff, v154
	v_and_b32_e32 v163, 0x7fffffff, v155
	v_pk_fma_f32 v[164:165], v[156:157], v[184:185], v[186:187]
	v_pk_fma_f32 v[166:167], v[158:159], v[184:185], v[186:187]
	v_pk_fma_f32 v[168:169], v[160:161], v[184:185], v[186:187]
	v_pk_fma_f32 v[170:171], v[162:163], v[184:185], v[186:187]
	v_rcp_f32_e32 v164, v164
	v_rcp_f32_e32 v165, v165
	v_rcp_f32_e32 v166, v166
	v_rcp_f32_e32 v167, v167
	v_rcp_f32_e32 v168, v168
	v_rcp_f32_e32 v169, v169
	v_rcp_f32_e32 v170, v170
	v_rcp_f32_e32 v171, v171
	v_pk_fma_f32 v[172:173], v[164:165], v[188:189], v[190:191]
	v_pk_fma_f32 v[174:175], v[166:167], v[188:189], v[190:191]
	v_pk_fma_f32 v[176:177], v[168:169], v[188:189], v[190:191]
	v_pk_fma_f32 v[178:179], v[170:171], v[188:189], v[190:191]
	v_pk_fma_f32 v[172:173], v[172:173], v[164:165], v[192:193]
	v_pk_fma_f32 v[174:175], v[174:175], v[166:167], v[192:193]
	v_pk_fma_f32 v[176:177], v[176:177], v[168:169], v[192:193]
	v_pk_fma_f32 v[178:179], v[178:179], v[170:171], v[192:193]
	v_pk_fma_f32 v[172:173], v[172:173], v[164:165], v[194:195]
	v_pk_fma_f32 v[174:175], v[174:175], v[166:167], v[194:195]
	v_pk_fma_f32 v[176:177], v[176:177], v[168:169], v[194:195]
	v_pk_fma_f32 v[178:179], v[178:179], v[170:171], v[194:195]
	v_pk_fma_f32 v[172:173], v[172:173], v[164:165], v[196:197]
	v_pk_fma_f32 v[174:175], v[174:175], v[166:167], v[196:197]
	v_pk_fma_f32 v[176:177], v[176:177], v[168:169], v[196:197]
	v_pk_fma_f32 v[178:179], v[178:179], v[170:171], v[196:197]
	v_pk_mul_f32 v[172:173], v[172:173], v[164:165]
	v_pk_mul_f32 v[174:175], v[174:175], v[166:167]
	v_pk_mul_f32 v[176:177], v[176:177], v[168:169]
	v_pk_mul_f32 v[178:179], v[178:179], v[170:171]
	v_pk_mul_f32 v[164:165], v[148:149], v[148:149]
	v_pk_mul_f32 v[166:167], v[150:151], v[150:151]
	v_pk_mul_f32 v[168:169], v[152:153], v[152:153]
	v_pk_mul_f32 v[170:171], v[154:155], v[154:155]
	v_pk_mul_f32 v[164:165], v[164:165], v[198:199]
	v_pk_mul_f32 v[166:167], v[166:167], v[198:199]
	v_pk_mul_f32 v[168:169], v[168:169], v[198:199]
	v_pk_mul_f32 v[170:171], v[170:171], v[198:199]
	v_exp_f32_e32 v164, v164
	v_exp_f32_e32 v165, v165
	v_exp_f32_e32 v166, v166
	v_exp_f32_e32 v167, v167
	v_exp_f32_e32 v168, v168
	v_exp_f32_e32 v169, v169
	v_exp_f32_e32 v170, v170
	v_exp_f32_e32 v171, v171
	v_pk_mul_f32 v[172:173], v[172:173], v[164:165]
	v_pk_mul_f32 v[174:175], v[174:175], v[166:167]
; __device__ __forceinline__ unsigned cvt_pk_bf16(float lo, float hi) { unsigned r; asm volatile("v_cvt_pk_bf16_f32 %0, %1, %2" : "=v"(r) : "v"(lo), "v"(hi)); return r; }
; __device__ __forceinline__ float gelu_as(float v) {
;   const float av = fabsf(v); const float t = __builtin_amdgcn_rcpf(av * 0.2316418882f + 1.0f);
;   float q = t * 0.5307027145f + (-0.7265760135f); q = q * t + 0.7107068705f; q = q * t + (-0.142248368f); q = q * t + 0.127414796f; q = q * t;
;   const float e = __builtin_amdgcn_exp2f((v * v) * (-0.72134752044f));
;   const float m = v * (q * e);
;   return v < 0.f ? m : v - m;
; __device__ __forceinline__ void phase_conv(KP p, int l, int tid) {
;     ...
;       for (int q = 0; q < CB; ++q) { const int col = jb + q + 1; const int cl = col > 63 ? 63 : col;
; #pragma unroll
;         for (int di = 0; di < RB + 2; ++di) an[q][di] = *(const u32x2*)(rowp[di] + (size_t)cl * DFF);
; #pragma unroll
;         for (int rr = 0; rr < RB; ++rr) ur[q][rr] = *(const u32x2*)(U + (size_t)((r0 + rr) * 64 + jb + q) * DFF + c0); }
;       __builtin_amdgcn_sched_barrier(0);
; #pragma unroll
;       for (int q = 0; q < CB; ++q) {
;         const int col = jb + q + 1;
; #pragma unroll
;         for (int di = 0; di < RB + 2; ++di) { const bool ok = rv[di] && (col < 64); unpack4(an[q][di], win[2][di]);
; #pragma unroll
;           for (int k = 0; k < 4; ++k) win[2][di][k] = ok ? win[2][di][k] : 0.f; }
; #pragma unroll
;         for (int rr = 0; rr < RB; ++rr) {
;           float uv[4]; unpack4(ur[q][rr], uv);
;           float o[4];
; #pragma unroll
;           for (int k = 0; k < 4; ++k) {
;             float a = bsv[k];
; #pragma unroll
;             for (int di = 0; di < 3; ++di)
; #pragma unroll
;               for (int dj = 0; dj < 3; ++dj) a += win[dj][rr + di][k] * w[di * 3 + dj][k];
;             o[k] = gelu_as(a) * uv[k];
;           }
;           u32x2 ow; ow.x = cvt_pk_bf16(o[0], o[1]); ow.y = cvt_pk_bf16(o[2], o[3]);
;           *(u32x2*)(G + (size_t)((r0 + rr) * 64 + jb + q) * DFF + c0) = ow;
;         }
	v_pk_mul_f32 v[176:177], v[176:177], v[168:169]
	v_pk_mul_f32 v[178:179], v[178:179], v[170:171]
	v_pk_mul_f32 v[172:173], v[156:157], v[172:173]
	v_pk_mul_f32 v[174:175], v[158:159], v[174:175]
	v_pk_mul_f32 v[176:177], v[160:161], v[176:177]
	v_pk_mul_f32 v[178:179], v[162:163], v[178:179]
	v_max_f32_e32 v164, 0, v148
	v_max_f32_e32 v165, 0, v149
	v_max_f32_e32 v166, 0, v150
	v_max_f32_e32 v167, 0, v151
	v_max_f32_e32 v168, 0, v152
	v_max_f32_e32 v169, 0, v153
	v_max_f32_e32 v170, 0, v154
	v_max_f32_e32 v171, 0, v155
	v_pk_add_f32 v[164:165], v[164:165], v[172:173] neg_lo:[0,1] neg_hi:[0,1]
	v_pk_add_f32 v[166:167], v[166:167], v[174:175] neg_lo:[0,1] neg_hi:[0,1]
	v_pk_add_f32 v[168:169], v[168:169], v[176:177] neg_lo:[0,1] neg_hi:[0,1]
	v_pk_add_f32 v[170:171], v[170:171], v[178:179] neg_lo:[0,1] neg_hi:[0,1]
	v_pk_mul_f32 v[164:165], v[164:165], v[124:125]
	v_pk_mul_f32 v[166:167], v[166:167], v[126:127]
	v_pk_mul_f32 v[168:169], v[168:169], v[128:129]
	v_pk_mul_f32 v[170:171], v[170:171], v[130:131]
	v_cvt_pk_bf16_f32 v156, v164, v165
	v_cvt_pk_bf16_f32 v157, v166, v167
	v_cvt_pk_bf16_f32 v158, v168, v169
	v_cvt_pk_bf16_f32 v159, v170, v171
	global_store_dwordx2 v216, v[156:157], s[10:11]
	global_store_dwordx2 v217, v[158:159], s[10:11]
	v_add_u32_e32 v210, 0x2c00, v210
	v_add_u32_e32 v211, 0x2c00, v210
	v_add_u32_e32 v212, v206, v211
	global_load_dwordx2 v[88:89], v212, s[6:7]
	v_add_u32_e32 v213, v207, v211
	global_load_dwordx2 v[90:91], v213, s[6:7]
	v_add_u32_e32 v214, v208, v211
	global_load_dwordx2 v[92:93], v214, s[6:7]
	v_add_u32_e32 v215, v209, v211
	global_load_dwordx2 v[94:95], v215, s[6:7]
	v_add_u32_e32 v216, v207, v210
	global_load_dwordx2 v[112:113], v216, s[8:9] nt
	v_add_u32_e32 v217, v208, v210
	global_load_dwordx2 v[114:115], v217, s[8:9] nt
	s_waitcnt vmcnt(16)
	v_lshlrev_b32_e32 v40, 16, v96
	v_and_b32_e32 v41, 0xffff0000, v96
	v_lshlrev_b32_e32 v42, 16, v97
	v_and_b32_e32 v43, 0xffff0000, v97
	v_lshlrev_b32_e32 v44, 16, v98
	v_and_b32_e32 v45, 0xffff0000, v98
	v_lshlrev_b32_e32 v46, 16, v99
	v_and_b32_e32 v47, 0xffff0000, v99
	v_lshlrev_b32_e32 v48, 16, v100
	v_and_b32_e32 v49, 0xffff0000, v100
	v_lshlrev_b32_e32 v50, 16, v101
	v_and_b32_e32 v51, 0xffff0000, v101
	v_lshlrev_b32_e32 v52, 16, v102
	v_and_b32_e32 v53, 0xffff0000, v102
	v_lshlrev_b32_e32 v54, 16, v103
	v_and_b32_e32 v55, 0xffff0000, v103
	v_pk_mul_f32 v[40:41], v[40:41], v[200:201]
	v_pk_mul_f32 v[42:43], v[42:43], v[200:201]
	v_pk_mul_f32 v[52:53], v[52:53], v[202:203]
	v_pk_mul_f32 v[54:55], v[54:55], v[202:203]
	v_lshlrev_b32_e32 v124, 16, v116
	v_and_b32_e32 v125, 0xffff0000, v116
	v_lshlrev_b32_e32 v126, 16, v117
	v_and_b32_e32 v127, 0xffff0000, v117
	v_lshlrev_b32_e32 v128, 16, v118
	v_and_b32_e32 v129, 0xffff0000, v118
	v_lshlrev_b32_e32 v130, 16, v119
	v_and_b32_e32 v131, 0xffff0000, v119
	v_pk_fma_f32 v[148:149], v[56:57], v[0:1], v[36:37]
	v_pk_fma_f32 v[150:151], v[58:59], v[2:3], v[38:39]
	v_pk_fma_f32 v[152:153], v[60:61], v[0:1], v[36:37]
	v_pk_fma_f32 v[154:155], v[62:63], v[2:3], v[38:39]
	v_pk_fma_f32 v[148:149], v[72:73], v[4:5], v[148:149]
	v_pk_fma_f32 v[150:151], v[74:75], v[6:7], v[150:151]
	v_pk_fma_f32 v[152:153], v[76:77], v[4:5], v[152:153]
	v_pk_fma_f32 v[154:155], v[78:79], v[6:7], v[154:155]
	v_pk_fma_f32 v[148:149], v[40:41], v[8:9], v[148:149]
	v_pk_fma_f32 v[150:151], v[42:43], v[10:11], v[150:151]
	v_pk_fma_f32 v[152:153], v[44:45], v[8:9], v[152:153]
	v_pk_fma_f32 v[154:155], v[46:47], v[10:11], v[154:155]
	v_pk_fma_f32 v[148:149], v[60:61], v[12:13], v[148:149]
	v_pk_fma_f32 v[150:151], v[62:63], v[14:15], v[150:151]
	v_pk_fma_f32 v[152:153], v[64:65], v[12:13], v[152:153]
	v_pk_fma_f32 v[154:155], v[66:67], v[14:15], v[154:155]
	v_pk_fma_f32 v[148:149], v[76:77], v[16:17], v[148:149]
	v_pk_fma_f32 v[150:151], v[78:79], v[18:19], v[150:151]
	v_pk_fma_f32 v[152:153], v[80:81], v[16:17], v[152:153]
	v_pk_fma_f32 v[154:155], v[82:83], v[18:19], v[154:155]
	v_pk_fma_f32 v[148:149], v[44:45], v[20:21], v[148:149]
	v_pk_fma_f32 v[150:151], v[46:47], v[22:23], v[150:151]
	v_pk_fma_f32 v[152:153], v[48:49], v[20:21], v[152:153]
	v_pk_fma_f32 v[154:155], v[50:51], v[22:23], v[154:155]
	v_pk_fma_f32 v[148:149], v[64:65], v[24:25], v[148:149]
	v_pk_fma_f32 v[150:151], v[66:67], v[26:27], v[150:151]
	v_pk_fma_f32 v[152:153], v[68:69], v[24:25], v[152:153]
	v_pk_fma_f32 v[154:155], v[70:71], v[26:27], v[154:155]
	v_pk_fma_f32 v[148:149], v[80:81], v[28:29], v[148:149]
	v_pk_fma_f32 v[150:151], v[82:83], v[30:31], v[150:151]
	v_pk_fma_f32 v[152:153], v[84:85], v[28:29], v[152:153]
	v_pk_fma_f32 v[154:155], v[86:87], v[30:31], v[154:155]
	v_pk_fma_f32 v[148:149], v[48:49], v[32:33], v[148:149]
	v_pk_fma_f32 v[150:151], v[50:51], v[34:35], v[150:151]
	v_pk_fma_f32 v[152:153], v[52:53], v[32:33], v[152:153]
	v_pk_fma_f32 v[154:155], v[54:55], v[34:35], v[154:155]
	v_and_b32_e32 v156, 0x7fffffff, v148
	v_and_b32_e32 v157, 0x7fffffff, v149
	v_and_b32_e32 v158, 0x7fffffff, v150
	v_and_b32_e32 v159, 0x7fffffff, v151
	v_and_b32_e32 v160, 0x7fffffff, v152
	v_and_b32_e32 v161, 0x7fffffff, v153
	v_and_b32_e32 v162, 0x7fffffff, v154
	v_and_b32_e32 v163, 0x7fffffff, v155
	v_pk_fma_f32 v[164:165], v[156:157], v[184:185], v[186:187]
	v_pk_fma_f32 v[166:167], v[158:159], v[184:185], v[186:187]
	v_pk_fma_f32 v[168:169], v[160:161], v[184:185], v[186:187]
	v_pk_fma_f32 v[170:171], v[162:163], v[184:185], v[186:187]
	v_rcp_f32_e32 v164, v164
	v_rcp_f32_e32 v165, v165
	v_rcp_f32_e32 v166, v166
	v_rcp_f32_e32 v167, v167
	v_rcp_f32_e32 v168, v168
	v_rcp_f32_e32 v169, v169
	v_rcp_f32_e32 v170, v170
	v_rcp_f32_e32 v171, v171
; __device__ __forceinline__ unsigned cvt_pk_bf16(float lo, float hi) { unsigned r; asm volatile("v_cvt_pk_bf16_f32 %0, %1, %2" : "=v"(r) : "v"(lo), "v"(hi)); return r; }
; __device__ __forceinline__ float gelu_as(float v) {
;   const float av = fabsf(v); const float t = __builtin_amdgcn_rcpf(av * 0.2316418882f + 1.0f);
;   float q = t * 0.5307027145f + (-0.7265760135f); q = q * t + 0.7107068705f; q = q * t + (-0.142248368f); q = q * t + 0.127414796f; q = q * t;
;   const float e = __builtin_amdgcn_exp2f((v * v) * (-0.72134752044f));
;   const float m = v * (q * e);
;   return v < 0.f ? m : v - m;
; __device__ __forceinline__ void phase_conv(KP p, int l, int tid) {
;     ...
;       for (int q = 0; q < CB; ++q) { const int col = jb + q + 1; const int cl = col > 63 ? 63 : col;
; #pragma unroll
;         for (int di = 0; di < RB + 2; ++di) an[q][di] = *(const u32x2*)(rowp[di] + (size_t)cl * DFF);
; #pragma unroll
;         for (int rr = 0; rr < RB; ++rr) ur[q][rr] = *(const u32x2*)(U + (size_t)((r0 + rr) * 64 + jb + q) * DFF + c0); }
;       __builtin_amdgcn_sched_barrier(0);
; #pragma unroll
;       for (int q = 0; q < CB; ++q) {
;         const int col = jb + q + 1;
; #pragma unroll
;         for (int di = 0; di < RB + 2; ++di) { const bool ok = rv[di] && (col < 64); unpack4(an[q][di], win[2][di]);
; #pragma unroll
;           for (int k = 0; k < 4; ++k) win[2][di][k] = ok ? win[2][di][k] : 0.f; }
; #pragma unroll
;         for (int rr = 0; rr < RB; ++rr) {
;           float uv[4]; unpack4(ur[q][rr], uv);
;           float o[4];
; #pragma unroll
;           for (int k = 0; k < 4; ++k) {
;             float a = bsv[k];
; #pragma unroll
;             for (int di = 0; di < 3; ++di)
; #pragma unroll
;               for (int dj = 0; dj < 3; ++dj) a += win[dj][rr + di][k] * w[di * 3 + dj][k];
;             o[k] = gelu_as(a) * uv[k];
;           }
;           u32x2 ow; ow.x = cvt_pk_bf16(o[0], o[1]); ow.y = cvt_pk_bf16(o[2], o[3]);
;           *(u32x2*)(G + (size_t)((r0 + rr) * 64 + jb + q) * DFF + c0) = ow;
;         }
	v_pk_fma_f32 v[172:173], v[164:165], v[188:189], v[190:191]
	v_pk_fma_f32 v[174:175], v[166:167], v[188:189], v[190:191]
	v_pk_fma_f32 v[176:177], v[168:169], v[188:189], v[190:191]
	v_pk_fma_f32 v[178:179], v[170:171], v[188:189], v[190:191]
	v_pk_fma_f32 v[172:173], v[172:173], v[164:165], v[192:193]
	v_pk_fma_f32 v[174:175], v[174:175], v[166:167], v[192:193]
	v_pk_fma_f32 v[176:177], v[176:177], v[168:169], v[192:193]
	v_pk_fma_f32 v[178:179], v[178:179], v[170:171], v[192:193]
	v_pk_fma_f32 v[172:173], v[172:173], v[164:165], v[194:195]
	v_pk_fma_f32 v[174:175], v[174:175], v[166:167], v[194:195]
	v_pk_fma_f32 v[176:177], v[176:177], v[168:169], v[194:195]
	v_pk_fma_f32 v[178:179], v[178:179], v[170:171], v[194:195]
	v_pk_fma_f32 v[172:173], v[172:173], v[164:165], v[196:197]
	v_pk_fma_f32 v[174:175], v[174:175], v[166:167], v[196:197]
	v_pk_fma_f32 v[176:177], v[176:177], v[168:169], v[196:197]
	v_pk_fma_f32 v[178:179], v[178:179], v[170:171], v[196:197]
	v_pk_mul_f32 v[172:173], v[172:173], v[164:165]
	v_pk_mul_f32 v[174:175], v[174:175], v[166:167]
	v_pk_mul_f32 v[176:177], v[176:177], v[168:169]
	v_pk_mul_f32 v[178:179], v[178:179], v[170:171]
	v_pk_mul_f32 v[164:165], v[148:149], v[148:149]
	v_pk_mul_f32 v[166:167], v[150:151], v[150:151]
	v_pk_mul_f32 v[168:169], v[152:153], v[152:153]
	v_pk_mul_f32 v[170:171], v[154:155], v[154:155]
	v_pk_mul_f32 v[164:165], v[164:165], v[198:199]
	v_pk_mul_f32 v[166:167], v[166:167], v[198:199]
	v_pk_mul_f32 v[168:169], v[168:169], v[198:199]
	v_pk_mul_f32 v[170:171], v[170:171], v[198:199]
	v_exp_f32_e32 v164, v164
	v_exp_f32_e32 v165, v165
	v_exp_f32_e32 v166, v166
	v_exp_f32_e32 v167, v167
	v_exp_f32_e32 v168, v168
	v_exp_f32_e32 v169, v169
	v_exp_f32_e32 v170, v170
	v_exp_f32_e32 v171, v171
	v_pk_mul_f32 v[172:173], v[172:173], v[164:165]
	v_pk_mul_f32 v[174:175], v[174:175], v[166:167]
	v_pk_mul_f32 v[176:177], v[176:177], v[168:169]
	v_pk_mul_f32 v[178:179], v[178:179], v[170:171]
	v_pk_mul_f32 v[172:173], v[156:157], v[172:173]
	v_pk_mul_f32 v[174:175], v[158:159], v[174:175]
	v_pk_mul_f32 v[176:177], v[160:161], v[176:177]
	v_pk_mul_f32 v[178:179], v[162:163], v[178:179]
	v_max_f32_e32 v164, 0, v148
	v_max_f32_e32 v165, 0, v149
	v_max_f32_e32 v166, 0, v150
	v_max_f32_e32 v167, 0, v151
	v_max_f32_e32 v168, 0, v152
	v_max_f32_e32 v169, 0, v153
	v_max_f32_e32 v170, 0, v154
	v_max_f32_e32 v171, 0, v155
	v_pk_add_f32 v[164:165], v[164:165], v[172:173] neg_lo:[0,1] neg_hi:[0,1]
	v_pk_add_f32 v[166:167], v[166:167], v[174:175] neg_lo:[0,1] neg_hi:[0,1]
	v_pk_add_f32 v[168:169], v[168:169], v[176:177] neg_lo:[0,1] neg_hi:[0,1]
	v_pk_add_f32 v[170:171], v[170:171], v[178:179] neg_lo:[0,1] neg_hi:[0,1]
	v_pk_mul_f32 v[164:165], v[164:165], v[124:125]
	v_pk_mul_f32 v[166:167], v[166:167], v[126:127]
	v_pk_mul_f32 v[168:169], v[168:169], v[128:129]
	v_pk_mul_f32 v[170:171], v[170:171], v[130:131]
	v_cvt_pk_bf16_f32 v156, v164, v165
	v_cvt_pk_bf16_f32 v157, v166, v167
	v_cvt_pk_bf16_f32 v158, v168, v169
	v_cvt_pk_bf16_f32 v159, v170, v171
	global_store_dwordx2 v218, v[156:157], s[10:11]
	global_store_dwordx2 v219, v[158:159], s[10:11]
	v_add_u32_e32 v210, 0x2c00, v210
	v_add_u32_e32 v211, 0x2c00, v210
	v_add_u32_e32 v212, v206, v211
	global_load_dwordx2 v[96:97], v212, s[6:7]
	v_add_u32_e32 v213, v207, v211
	global_load_dwordx2 v[98:99], v213, s[6:7]
	v_add_u32_e32 v214, v208, v211
	global_load_dwordx2 v[100:101], v214, s[6:7]
	v_add_u32_e32 v215, v209, v211
	global_load_dwordx2 v[102:103], v215, s[6:7]
	v_add_u32_e32 v218, v207, v210
	global_load_dwordx2 v[116:117], v218, s[8:9] nt
	v_add_u32_e32 v219, v208, v210
	global_load_dwordx2 v[118:119], v219, s[8:9] nt
	s_waitcnt vmcnt(16)
	v_lshlrev_b32_e32 v56, 16, v104
	v_and_b32_e32 v57, 0xffff0000, v104
	v_lshlrev_b32_e32 v58, 16, v105
	v_and_b32_e32 v59, 0xffff0000, v105
	v_lshlrev_b32_e32 v60, 16, v106
	v_and_b32_e32 v61, 0xffff0000, v106
	v_lshlrev_b32_e32 v62, 16, v107
	v_and_b32_e32 v63, 0xffff0000, v107
	v_lshlrev_b32_e32 v64, 16, v108
	v_and_b32_e32 v65, 0xffff0000, v108
	v_lshlrev_b32_e32 v66, 16, v109
	v_and_b32_e32 v67, 0xffff0000, v109
	v_lshlrev_b32_e32 v68, 16, v110
	v_and_b32_e32 v69, 0xffff0000, v110
	v_lshlrev_b32_e32 v70, 16, v111
	v_and_b32_e32 v71, 0xffff0000, v111
	v_pk_mul_f32 v[56:57], v[56:57], v[200:201]
	v_pk_mul_f32 v[58:59], v[58:59], v[200:201]
	v_pk_mul_f32 v[68:69], v[68:69], v[202:203]
	v_pk_mul_f32 v[70:71], v[70:71], v[202:203]
	v_lshlrev_b32_e32 v124, 16, v120
	v_and_b32_e32 v125, 0xffff0000, v120
	v_lshlrev_b32_e32 v126, 16, v121
	v_and_b32_e32 v127, 0xffff0000, v121
	v_lshlrev_b32_e32 v128, 16, v122
	v_and_b32_e32 v129, 0xffff0000, v122
	v_lshlrev_b32_e32 v130, 16, v123
	v_and_b32_e32 v131, 0xffff0000, v123
	v_pk_fma_f32 v[148:149], v[72:73], v[0:1], v[36:37]
	v_pk_fma_f32 v[150:151], v[74:75], v[2:3], v[38:39]
	v_pk_fma_f32 v[152:153], v[76:77], v[0:1], v[36:37]
	v_pk_fma_f32 v[154:155], v[78:79], v[2:3], v[38:39]
	v_pk_fma_f32 v[148:149], v[40:41], v[4:5], v[148:149]
	v_pk_fma_f32 v[150:151], v[42:43], v[6:7], v[150:151]
	v_pk_fma_f32 v[152:153], v[44:45], v[4:5], v[152:153]
	v_pk_fma_f32 v[154:155], v[46:47], v[6:7], v[154:155]
	v_pk_fma_f32 v[148:149], v[56:57], v[8:9], v[148:149]
	v_pk_fma_f32 v[150:151], v[58:59], v[10:11], v[150:151]
	v_pk_fma_f32 v[152:153], v[60:61], v[8:9], v[152:153]
	v_pk_fma_f32 v[154:155], v[62:63], v[10:11], v[154:155]
	v_pk_fma_f32 v[148:149], v[76:77], v[12:13], v[148:149]
	v_pk_fma_f32 v[150:151], v[78:79], v[14:15], v[150:151]
	v_pk_fma_f32 v[152:153], v[80:81], v[12:13], v[152:153]
	v_pk_fma_f32 v[154:155], v[82:83], v[14:15], v[154:155]
	v_pk_fma_f32 v[148:149], v[44:45], v[16:17], v[148:149]
; __device__ __forceinline__ unsigned cvt_pk_bf16(float lo, float hi) { unsigned r; asm volatile("v_cvt_pk_bf16_f32 %0, %1, %2" : "=v"(r) : "v"(lo), "v"(hi)); return r; }
; __device__ __forceinline__ float gelu_as(float v) {
;   const float av = fabsf(v); const float t = __builtin_amdgcn_rcpf(av * 0.2316418882f + 1.0f);
;   float q = t * 0.5307027145f + (-0.7265760135f); q = q * t + 0.7107068705f; q = q * t + (-0.142248368f); q = q * t + 0.127414796f; q = q * t;
;   const float e = __builtin_amdgcn_exp2f((v * v) * (-0.72134752044f));
;   const float m = v * (q * e);
;   return v < 0.f ? m : v - m;
; __device__ __forceinline__ void phase_conv(KP p, int l, int tid) {
;     ...
;       for (int q = 0; q < CB; ++q) { const int col = jb + q + 1; const int cl = col > 63 ? 63 : col;
; #pragma unroll
;         for (int di = 0; di < RB + 2; ++di) an[q][di] = *(const u32x2*)(rowp[di] + (size_t)cl * DFF);
; #pragma unroll
;         for (int rr = 0; rr < RB; ++rr) ur[q][rr] = *(const u32x2*)(U + (size_t)((r0 + rr) * 64 + jb + q) * DFF + c0); }
;       __builtin_amdgcn_sched_barrier(0);
; #pragma unroll
;       for (int q = 0; q < CB; ++q) {
;         const int col = jb + q + 1;
; #pragma unroll
;         for (int di = 0; di < RB + 2; ++di) { const bool ok = rv[di] && (col < 64); unpack4(an[q][di], win[2][di]);
; #pragma unroll
;           for (int k = 0; k < 4; ++k) win[2][di][k] = ok ? win[2][di][k] : 0.f; }
; #pragma unroll
;         for (int rr = 0; rr < RB; ++rr) {
;           float uv[4]; unpack4(ur[q][rr], uv);
;           float o[4];
; #pragma unroll
;           for (int k = 0; k < 4; ++k) {
;             float a = bsv[k];
; #pragma unroll
;             for (int di = 0; di < 3; ++di)
; #pragma unroll
;               for (int dj = 0; dj < 3; ++dj) a += win[dj][rr + di][k] * w[di * 3 + dj][k];
;             o[k] = gelu_as(a) * uv[k];
;           }
;           u32x2 ow; ow.x = cvt_pk_bf16(o[0], o[1]); ow.y = cvt_pk_bf16(o[2], o[3]);
;           *(u32x2*)(G + (size_t)((r0 + rr) * 64 + jb + q) * DFF + c0) = ow;
;         }
	v_pk_fma_f32 v[150:151], v[46:47], v[18:19], v[150:151]
	v_pk_fma_f32 v[152:153], v[48:49], v[16:17], v[152:153]
	v_pk_fma_f32 v[154:155], v[50:51], v[18:19], v[154:155]
	v_pk_fma_f32 v[148:149], v[60:61], v[20:21], v[148:149]
	v_pk_fma_f32 v[150:151], v[62:63], v[22:23], v[150:151]
	v_pk_fma_f32 v[152:153], v[64:65], v[20:21], v[152:153]
	v_pk_fma_f32 v[154:155], v[66:67], v[22:23], v[154:155]
	v_pk_fma_f32 v[148:149], v[80:81], v[24:25], v[148:149]
	v_pk_fma_f32 v[150:151], v[82:83], v[26:27], v[150:151]
	v_pk_fma_f32 v[152:153], v[84:85], v[24:25], v[152:153]
	v_pk_fma_f32 v[154:155], v[86:87], v[26:27], v[154:155]
	v_pk_fma_f32 v[148:149], v[48:49], v[28:29], v[148:149]
	v_pk_fma_f32 v[150:151], v[50:51], v[30:31], v[150:151]
	v_pk_fma_f32 v[152:153], v[52:53], v[28:29], v[152:153]
	v_pk_fma_f32 v[154:155], v[54:55], v[30:31], v[154:155]
	v_pk_fma_f32 v[148:149], v[64:65], v[32:33], v[148:149]
	v_pk_fma_f32 v[150:151], v[66:67], v[34:35], v[150:151]
	v_pk_fma_f32 v[152:153], v[68:69], v[32:33], v[152:153]
	v_pk_fma_f32 v[154:155], v[70:71], v[34:35], v[154:155]
	v_and_b32_e32 v156, 0x7fffffff, v148
	v_and_b32_e32 v157, 0x7fffffff, v149
	v_and_b32_e32 v158, 0x7fffffff, v150
	v_and_b32_e32 v159, 0x7fffffff, v151
	v_and_b32_e32 v160, 0x7fffffff, v152
	v_and_b32_e32 v161, 0x7fffffff, v153
	v_and_b32_e32 v162, 0x7fffffff, v154
	v_and_b32_e32 v163, 0x7fffffff, v155
	v_pk_fma_f32 v[164:165], v[156:157], v[184:185], v[186:187]
	v_pk_fma_f32 v[166:167], v[158:159], v[184:185], v[186:187]
	v_pk_fma_f32 v[168:169], v[160:161], v[184:185], v[186:187]
	v_pk_fma_f32 v[170:171], v[162:163], v[184:185], v[186:187]
	v_rcp_f32_e32 v164, v164
	v_rcp_f32_e32 v165, v165
	v_rcp_f32_e32 v166, v166
	v_rcp_f32_e32 v167, v167
	v_rcp_f32_e32 v168, v168
	v_rcp_f32_e32 v169, v169
	v_rcp_f32_e32 v170, v170
	v_rcp_f32_e32 v171, v171
	v_pk_fma_f32 v[172:173], v[164:165], v[188:189], v[190:191]
	v_pk_fma_f32 v[174:175], v[166:167], v[188:189], v[190:191]
	v_pk_fma_f32 v[176:177], v[168:169], v[188:189], v[190:191]
	v_pk_fma_f32 v[178:179], v[170:171], v[188:189], v[190:191]
	v_pk_fma_f32 v[172:173], v[172:173], v[164:165], v[192:193]
	v_pk_fma_f32 v[174:175], v[174:175], v[166:167], v[192:193]
	v_pk_fma_f32 v[176:177], v[176:177], v[168:169], v[192:193]
	v_pk_fma_f32 v[178:179], v[178:179], v[170:171], v[192:193]
	v_pk_fma_f32 v[172:173], v[172:173], v[164:165], v[194:195]
	v_pk_fma_f32 v[174:175], v[174:175], v[166:167], v[194:195]
	v_pk_fma_f32 v[176:177], v[176:177], v[168:169], v[194:195]
	v_pk_fma_f32 v[178:179], v[178:179], v[170:171], v[194:195]
	v_pk_fma_f32 v[172:173], v[172:173], v[164:165], v[196:197]
	v_pk_fma_f32 v[174:175], v[174:175], v[166:167], v[196:197]
	v_pk_fma_f32 v[176:177], v[176:177], v[168:169], v[196:197]
	v_pk_fma_f32 v[178:179], v[178:179], v[170:171], v[196:197]
	v_pk_mul_f32 v[172:173], v[172:173], v[164:165]
	v_pk_mul_f32 v[174:175], v[174:175], v[166:167]
	v_pk_mul_f32 v[176:177], v[176:177], v[168:169]
	v_pk_mul_f32 v[178:179], v[178:179], v[170:171]
	v_pk_mul_f32 v[164:165], v[148:149], v[148:149]
	v_pk_mul_f32 v[166:167], v[150:151], v[150:151]
	v_pk_mul_f32 v[168:169], v[152:153], v[152:153]
	v_pk_mul_f32 v[170:171], v[154:155], v[154:155]
	v_pk_mul_f32 v[164:165], v[164:165], v[198:199]
	v_pk_mul_f32 v[166:167], v[166:167], v[198:199]
	v_pk_mul_f32 v[168:169], v[168:169], v[198:199]
	v_pk_mul_f32 v[170:171], v[170:171], v[198:199]
	v_exp_f32_e32 v164, v164
	v_exp_f32_e32 v165, v165
	v_exp_f32_e32 v166, v166
	v_exp_f32_e32 v167, v167
	v_exp_f32_e32 v168, v168
	v_exp_f32_e32 v169, v169
	v_exp_f32_e32 v170, v170
	v_exp_f32_e32 v171, v171
	v_pk_mul_f32 v[172:173], v[172:173], v[164:165]
	v_pk_mul_f32 v[174:175], v[174:175], v[166:167]
	v_pk_mul_f32 v[176:177], v[176:177], v[168:169]
	v_pk_mul_f32 v[178:179], v[178:179], v[170:171]
	v_pk_mul_f32 v[172:173], v[156:157], v[172:173]
	v_pk_mul_f32 v[174:175], v[158:159], v[174:175]
	v_pk_mul_f32 v[176:177], v[160:161], v[176:177]
	v_pk_mul_f32 v[178:179], v[162:163], v[178:179]
	v_max_f32_e32 v164, 0, v148
	v_max_f32_e32 v165, 0, v149
	v_max_f32_e32 v166, 0, v150
	v_max_f32_e32 v167, 0, v151
	v_max_f32_e32 v168, 0, v152
	v_max_f32_e32 v169, 0, v153
	v_max_f32_e32 v170, 0, v154
	v_max_f32_e32 v171, 0, v155
	v_pk_add_f32 v[164:165], v[164:165], v[172:173] neg_lo:[0,1] neg_hi:[0,1]
	v_pk_add_f32 v[166:167], v[166:167], v[174:175] neg_lo:[0,1] neg_hi:[0,1]
	v_pk_add_f32 v[168:169], v[168:169], v[176:177] neg_lo:[0,1] neg_hi:[0,1]
	v_pk_add_f32 v[170:171], v[170:171], v[178:179] neg_lo:[0,1] neg_hi:[0,1]
	v_pk_mul_f32 v[164:165], v[164:165], v[124:125]
	v_pk_mul_f32 v[166:167], v[166:167], v[126:127]
	v_pk_mul_f32 v[168:169], v[168:169], v[128:129]
	v_pk_mul_f32 v[170:171], v[170:171], v[130:131]
	v_cvt_pk_bf16_f32 v156, v164, v165
	v_cvt_pk_bf16_f32 v157, v166, v167
	v_cvt_pk_bf16_f32 v158, v168, v169
	v_cvt_pk_bf16_f32 v159, v170, v171
	global_store_dwordx2 v220, v[156:157], s[10:11]
	global_store_dwordx2 v221, v[158:159], s[10:11]
	v_add_u32_e32 v210, 0x2c00, v210
	v_add_u32_e32 v211, 0x2c00, v210
	v_add_u32_e32 v212, v206, v211
	global_load_dwordx2 v[104:105], v212, s[6:7]
	v_add_u32_e32 v213, v207, v211
	global_load_dwordx2 v[106:107], v213, s[6:7]
	v_add_u32_e32 v214, v208, v211
	global_load_dwordx2 v[108:109], v214, s[6:7]
	v_add_u32_e32 v215, v209, v211
	global_load_dwordx2 v[110:111], v215, s[6:7]
	v_add_u32_e32 v220, v207, v210
	global_load_dwordx2 v[120:121], v220, s[8:9] nt
	v_add_u32_e32 v221, v208, v210
	global_load_dwordx2 v[122:123], v221, s[8:9] nt
	s_waitcnt vmcnt(16)
; __device__ __forceinline__ unsigned cvt_pk_bf16(float lo, float hi) { unsigned r; asm volatile("v_cvt_pk_bf16_f32 %0, %1, %2" : "=v"(r) : "v"(lo), "v"(hi)); return r; }
; __device__ __forceinline__ float gelu_as(float v) {
;   const float av = fabsf(v); const float t = __builtin_amdgcn_rcpf(av * 0.2316418882f + 1.0f);
;   float q = t * 0.5307027145f + (-0.7265760135f); q = q * t + 0.7107068705f; q = q * t + (-0.142248368f); q = q * t + 0.127414796f; q = q * t;
;   const float e = __builtin_amdgcn_exp2f((v * v) * (-0.72134752044f));
;   const float m = v * (q * e);
;   return v < 0.f ? m : v - m;
; __device__ __forceinline__ void phase_conv(KP p, int l, int tid) {
;     ...
;       for (int q = 0; q < CB; ++q) { const int col = jb + q + 1; const int cl = col > 63 ? 63 : col;
; #pragma unroll
;         for (int di = 0; di < RB + 2; ++di) an[q][di] = *(const u32x2*)(rowp[di] + (size_t)cl * DFF);
; #pragma unroll
;         for (int rr = 0; rr < RB; ++rr) ur[q][rr] = *(const u32x2*)(U + (size_t)((r0 + rr) * 64 + jb + q) * DFF + c0); }
;       __builtin_amdgcn_sched_barrier(0);
; #pragma unroll
;       for (int q = 0; q < CB; ++q) {
;         const int col = jb + q + 1;
; #pragma unroll
;         for (int di = 0; di < RB + 2; ++di) { const bool ok = rv[di] && (col < 64); unpack4(an[q][di], win[2][di]);
; #pragma unroll
;           for (int k = 0; k < 4; ++k) win[2][di][k] = ok ? win[2][di][k] : 0.f; }
; #pragma unroll
;         for (int rr = 0; rr < RB; ++rr) {
;           float uv[4]; unpack4(ur[q][rr], uv);
;           float o[4];
; #pragma unroll
;           for (int k = 0; k < 4; ++k) {
;             float a = bsv[k];
; #pragma unroll
;             for (int di = 0; di < 3; ++di)
; #pragma unroll
;               for (int dj = 0; dj < 3; ++dj) a += win[dj][rr + di][k] * w[di * 3 + dj][k];
;             o[k] = gelu_as(a) * uv[k];
;           }
;           u32x2 ow; ow.x = cvt_pk_bf16(o[0], o[1]); ow.y = cvt_pk_bf16(o[2], o[3]);
;           *(u32x2*)(G + (size_t)((r0 + rr) * 64 + jb + q) * DFF + c0) = ow;
;         }
	v_lshlrev_b32_e32 v72, 16, v88
	v_and_b32_e32 v73, 0xffff0000, v88
	v_lshlrev_b32_e32 v74, 16, v89
	v_and_b32_e32 v75, 0xffff0000, v89
	v_lshlrev_b32_e32 v76, 16, v90
	v_and_b32_e32 v77, 0xffff0000, v90
	v_lshlrev_b32_e32 v78, 16, v91
	v_and_b32_e32 v79, 0xffff0000, v91
	v_lshlrev_b32_e32 v80, 16, v92
	v_and_b32_e32 v81, 0xffff0000, v92
	v_lshlrev_b32_e32 v82, 16, v93
	v_and_b32_e32 v83, 0xffff0000, v93
	v_lshlrev_b32_e32 v84, 16, v94
	v_and_b32_e32 v85, 0xffff0000, v94
	v_lshlrev_b32_e32 v86, 16, v95
	v_and_b32_e32 v87, 0xffff0000, v95
	v_pk_mul_f32 v[72:73], v[72:73], v[200:201]
	v_pk_mul_f32 v[74:75], v[74:75], v[200:201]
	v_pk_mul_f32 v[84:85], v[84:85], v[202:203]
	v_pk_mul_f32 v[86:87], v[86:87], v[202:203]
	v_lshlrev_b32_e32 v124, 16, v112
	v_and_b32_e32 v125, 0xffff0000, v112
	v_lshlrev_b32_e32 v126, 16, v113
	v_and_b32_e32 v127, 0xffff0000, v113
	v_lshlrev_b32_e32 v128, 16, v114
	v_and_b32_e32 v129, 0xffff0000, v114
	v_lshlrev_b32_e32 v130, 16, v115
	v_and_b32_e32 v131, 0xffff0000, v115
	v_pk_fma_f32 v[148:149], v[40:41], v[0:1], v[36:37]
	v_pk_fma_f32 v[150:151], v[42:43], v[2:3], v[38:39]
	v_pk_fma_f32 v[152:153], v[44:45], v[0:1], v[36:37]
	v_pk_fma_f32 v[154:155], v[46:47], v[2:3], v[38:39]
	v_pk_fma_f32 v[148:149], v[56:57], v[4:5], v[148:149]
	v_pk_fma_f32 v[150:151], v[58:59], v[6:7], v[150:151]
	v_pk_fma_f32 v[152:153], v[60:61], v[4:5], v[152:153]
	v_pk_fma_f32 v[154:155], v[62:63], v[6:7], v[154:155]
	v_pk_fma_f32 v[148:149], v[72:73], v[8:9], v[148:149]
	v_pk_fma_f32 v[150:151], v[74:75], v[10:11], v[150:151]
	v_pk_fma_f32 v[152:153], v[76:77], v[8:9], v[152:153]
	v_pk_fma_f32 v[154:155], v[78:79], v[10:11], v[154:155]
	v_pk_fma_f32 v[148:149], v[44:45], v[12:13], v[148:149]
	v_pk_fma_f32 v[150:151], v[46:47], v[14:15], v[150:151]
	v_pk_fma_f32 v[152:153], v[48:49], v[12:13], v[152:153]
	v_pk_fma_f32 v[154:155], v[50:51], v[14:15], v[154:155]
	v_pk_fma_f32 v[148:149], v[60:61], v[16:17], v[148:149]
	v_pk_fma_f32 v[150:151], v[62:63], v[18:19], v[150:151]
	v_pk_fma_f32 v[152:153], v[64:65], v[16:17], v[152:153]
	v_pk_fma_f32 v[154:155], v[66:67], v[18:19], v[154:155]
	v_pk_fma_f32 v[148:149], v[76:77], v[20:21], v[148:149]
	v_pk_fma_f32 v[150:151], v[78:79], v[22:23], v[150:151]
	v_pk_fma_f32 v[152:153], v[80:81], v[20:21], v[152:153]
	v_pk_fma_f32 v[154:155], v[82:83], v[22:23], v[154:155]
	v_pk_fma_f32 v[148:149], v[48:49], v[24:25], v[148:149]
	v_pk_fma_f32 v[150:151], v[50:51], v[26:27], v[150:151]
	v_pk_fma_f32 v[152:153], v[52:53], v[24:25], v[152:153]
	v_pk_fma_f32 v[154:155], v[54:55], v[26:27], v[154:155]
	v_pk_fma_f32 v[148:149], v[64:65], v[28:29], v[148:149]
	v_pk_fma_f32 v[150:151], v[66:67], v[30:31], v[150:151]
	v_pk_fma_f32 v[152:153], v[68:69], v[28:29], v[152:153]
	v_pk_fma_f32 v[154:155], v[70:71], v[30:31], v[154:155]
	v_pk_fma_f32 v[148:149], v[80:81], v[32:33], v[148:149]
	v_pk_fma_f32 v[150:151], v[82:83], v[34:35], v[150:151]
	v_pk_fma_f32 v[152:153], v[84:85], v[32:33], v[152:153]
	v_pk_fma_f32 v[154:155], v[86:87], v[34:35], v[154:155]
	v_and_b32_e32 v156, 0x7fffffff, v148
	v_and_b32_e32 v157, 0x7fffffff, v149
	v_and_b32_e32 v158, 0x7fffffff, v150
	v_and_b32_e32 v159, 0x7fffffff, v151
	v_and_b32_e32 v160, 0x7fffffff, v152
	v_and_b32_e32 v161, 0x7fffffff, v153
	v_and_b32_e32 v162, 0x7fffffff, v154
	v_and_b32_e32 v163, 0x7fffffff, v155
	v_pk_fma_f32 v[164:165], v[156:157], v[184:185], v[186:187]
	v_pk_fma_f32 v[166:167], v[158:159], v[184:185], v[186:187]
	v_pk_fma_f32 v[168:169], v[160:161], v[184:185], v[186:187]
	v_pk_fma_f32 v[170:171], v[162:163], v[184:185], v[186:187]
	v_rcp_f32_e32 v164, v164
	v_rcp_f32_e32 v165, v165
	v_rcp_f32_e32 v166, v166
	v_rcp_f32_e32 v167, v167
	v_rcp_f32_e32 v168, v168
	v_rcp_f32_e32 v169, v169
	v_rcp_f32_e32 v170, v170
	v_rcp_f32_e32 v171, v171
	v_pk_fma_f32 v[172:173], v[164:165], v[188:189], v[190:191]
	v_pk_fma_f32 v[174:175], v[166:167], v[188:189], v[190:191]
	v_pk_fma_f32 v[176:177], v[168:169], v[188:189], v[190:191]
	v_pk_fma_f32 v[178:179], v[170:171], v[188:189], v[190:191]
	v_pk_fma_f32 v[172:173], v[172:173], v[164:165], v[192:193]
	v_pk_fma_f32 v[174:175], v[174:175], v[166:167], v[192:193]
	v_pk_fma_f32 v[176:177], v[176:177], v[168:169], v[192:193]
	v_pk_fma_f32 v[178:179], v[178:179], v[170:171], v[192:193]
	v_pk_fma_f32 v[172:173], v[172:173], v[164:165], v[194:195]
	v_pk_fma_f32 v[174:175], v[174:175], v[166:167], v[194:195]
	v_pk_fma_f32 v[176:177], v[176:177], v[168:169], v[194:195]
	v_pk_fma_f32 v[178:179], v[178:179], v[170:171], v[194:195]
	v_pk_fma_f32 v[172:173], v[172:173], v[164:165], v[196:197]
	v_pk_fma_f32 v[174:175], v[174:175], v[166:167], v[196:197]
	v_pk_fma_f32 v[176:177], v[176:177], v[168:169], v[196:197]
	v_pk_fma_f32 v[178:179], v[178:179], v[170:171], v[196:197]
	v_pk_mul_f32 v[172:173], v[172:173], v[164:165]
	v_pk_mul_f32 v[174:175], v[174:175], v[166:167]
	v_pk_mul_f32 v[176:177], v[176:177], v[168:169]
	v_pk_mul_f32 v[178:179], v[178:179], v[170:171]
	v_pk_mul_f32 v[164:165], v[148:149], v[148:149]
	v_pk_mul_f32 v[166:167], v[150:151], v[150:151]
	v_pk_mul_f32 v[168:169], v[152:153], v[152:153]
	v_pk_mul_f32 v[170:171], v[154:155], v[154:155]
	v_pk_mul_f32 v[164:165], v[164:165], v[198:199]
	v_pk_mul_f32 v[166:167], v[166:167], v[198:199]
	v_pk_mul_f32 v[168:169], v[168:169], v[198:199]
	v_pk_mul_f32 v[170:171], v[170:171], v[198:199]
	v_exp_f32_e32 v164, v164
	v_exp_f32_e32 v165, v165
	v_exp_f32_e32 v166, v166
	v_exp_f32_e32 v167, v167
	v_exp_f32_e32 v168, v168
	v_exp_f32_e32 v169, v169
	v_exp_f32_e32 v170, v170
	v_exp_f32_e32 v171, v171
	v_pk_mul_f32 v[172:173], v[172:173], v[164:165]
	v_pk_mul_f32 v[174:175], v[174:175], v[166:167]
; __device__ __forceinline__ unsigned cvt_pk_bf16(float lo, float hi) { unsigned r; asm volatile("v_cvt_pk_bf16_f32 %0, %1, %2" : "=v"(r) : "v"(lo), "v"(hi)); return r; }
; __device__ __forceinline__ float gelu_as(float v) {
;   const float av = fabsf(v); const float t = __builtin_amdgcn_rcpf(av * 0.2316418882f + 1.0f);
;   float q = t * 0.5307027145f + (-0.7265760135f); q = q * t + 0.7107068705f; q = q * t + (-0.142248368f); q = q * t + 0.127414796f; q = q * t;
;   const float e = __builtin_amdgcn_exp2f((v * v) * (-0.72134752044f));
;   const float m = v * (q * e);
;   return v < 0.f ? m : v - m;
; __device__ __forceinline__ void phase_conv(KP p, int l, int tid) {
;     ...
;       for (int q = 0; q < CB; ++q) { const int col = jb + q + 1; const int cl = col > 63 ? 63 : col;
; #pragma unroll
;         for (int di = 0; di < RB + 2; ++di) an[q][di] = *(const u32x2*)(rowp[di] + (size_t)cl * DFF);
; #pragma unroll
;         for (int rr = 0; rr < RB; ++rr) ur[q][rr] = *(const u32x2*)(U + (size_t)((r0 + rr) * 64 + jb + q) * DFF + c0); }
;       __builtin_amdgcn_sched_barrier(0);
; #pragma unroll
;       for (int q = 0; q < CB; ++q) {
;         const int col = jb + q + 1;
; #pragma unroll
;         for (int di = 0; di < RB + 2; ++di) { const bool ok = rv[di] && (col < 64); unpack4(an[q][di], win[2][di]);
; #pragma unroll
;           for (int k = 0; k < 4; ++k) win[2][di][k] = ok ? win[2][di][k] : 0.f; }
; #pragma unroll
;         for (int rr = 0; rr < RB; ++rr) {
;           float uv[4]; unpack4(ur[q][rr], uv);
;           float o[4];
; #pragma unroll
;           for (int k = 0; k < 4; ++k) {
;             float a = bsv[k];
; #pragma unroll
;             for (int di = 0; di < 3; ++di)
; #pragma unroll
;               for (int dj = 0; dj < 3; ++dj) a += win[dj][rr + di][k] * w[di * 3 + dj][k];
;             o[k] = gelu_as(a) * uv[k];
;           }
;           u32x2 ow; ow.x = cvt_pk_bf16(o[0], o[1]); ow.y = cvt_pk_bf16(o[2], o[3]);
;           *(u32x2*)(G + (size_t)((r0 + rr) * 64 + jb + q) * DFF + c0) = ow;
;         }
	v_pk_mul_f32 v[176:177], v[176:177], v[168:169]
	v_pk_mul_f32 v[178:179], v[178:179], v[170:171]
	v_pk_mul_f32 v[172:173], v[156:157], v[172:173]
	v_pk_mul_f32 v[174:175], v[158:159], v[174:175]
	v_pk_mul_f32 v[176:177], v[160:161], v[176:177]
	v_pk_mul_f32 v[178:179], v[162:163], v[178:179]
	v_max_f32_e32 v164, 0, v148
	v_max_f32_e32 v165, 0, v149
	v_max_f32_e32 v166, 0, v150
	v_max_f32_e32 v167, 0, v151
	v_max_f32_e32 v168, 0, v152
	v_max_f32_e32 v169, 0, v153
	v_max_f32_e32 v170, 0, v154
	v_max_f32_e32 v171, 0, v155
	v_pk_add_f32 v[164:165], v[164:165], v[172:173] neg_lo:[0,1] neg_hi:[0,1]
	v_pk_add_f32 v[166:167], v[166:167], v[174:175] neg_lo:[0,1] neg_hi:[0,1]
	v_pk_add_f32 v[168:169], v[168:169], v[176:177] neg_lo:[0,1] neg_hi:[0,1]
	v_pk_add_f32 v[170:171], v[170:171], v[178:179] neg_lo:[0,1] neg_hi:[0,1]
	v_pk_mul_f32 v[164:165], v[164:165], v[124:125]
	v_pk_mul_f32 v[166:167], v[166:167], v[126:127]
	v_pk_mul_f32 v[168:169], v[168:169], v[128:129]
	v_pk_mul_f32 v[170:171], v[170:171], v[130:131]
	v_cvt_pk_bf16_f32 v156, v164, v165
	v_cvt_pk_bf16_f32 v157, v166, v167
	v_cvt_pk_bf16_f32 v158, v168, v169
	v_cvt_pk_bf16_f32 v159, v170, v171
	global_store_dwordx2 v216, v[156:157], s[10:11]
	global_store_dwordx2 v217, v[158:159], s[10:11]
	v_add_u32_e32 v210, 0x2c00, v210
	v_add_u32_e32 v211, 0x2c00, v210
	v_min_u32_e32 v211, 0xad400, v211
	v_add_u32_e32 v212, v206, v211
	global_load_dwordx2 v[88:89], v212, s[6:7]
	v_add_u32_e32 v213, v207, v211
	global_load_dwordx2 v[90:91], v213, s[6:7]
	v_add_u32_e32 v214, v208, v211
	global_load_dwordx2 v[92:93], v214, s[6:7]
	v_add_u32_e32 v215, v209, v211
	global_load_dwordx2 v[94:95], v215, s[6:7]
	v_add_u32_e32 v216, v207, v210
	global_load_dwordx2 v[112:113], v216, s[8:9] nt
	v_add_u32_e32 v217, v208, v210
	global_load_dwordx2 v[114:115], v217, s[8:9] nt
	s_waitcnt vmcnt(16)
	v_lshlrev_b32_e32 v40, 16, v96
	v_and_b32_e32 v41, 0xffff0000, v96
	v_lshlrev_b32_e32 v42, 16, v97
	v_and_b32_e32 v43, 0xffff0000, v97
	v_lshlrev_b32_e32 v44, 16, v98
	v_and_b32_e32 v45, 0xffff0000, v98
	v_lshlrev_b32_e32 v46, 16, v99
	v_and_b32_e32 v47, 0xffff0000, v99
	v_lshlrev_b32_e32 v48, 16, v100
	v_and_b32_e32 v49, 0xffff0000, v100
	v_lshlrev_b32_e32 v50, 16, v101
	v_and_b32_e32 v51, 0xffff0000, v101
	v_lshlrev_b32_e32 v52, 16, v102
	v_and_b32_e32 v53, 0xffff0000, v102
	v_lshlrev_b32_e32 v54, 16, v103
	v_and_b32_e32 v55, 0xffff0000, v103
	v_pk_mul_f32 v[40:41], v[40:41], v[200:201]
	v_pk_mul_f32 v[42:43], v[42:43], v[200:201]
	v_pk_mul_f32 v[52:53], v[52:53], v[202:203]
	v_pk_mul_f32 v[54:55], v[54:55], v[202:203]
	v_lshlrev_b32_e32 v124, 16, v116
	v_and_b32_e32 v125, 0xffff0000, v116
	v_lshlrev_b32_e32 v126, 16, v117
	v_and_b32_e32 v127, 0xffff0000, v117
	v_lshlrev_b32_e32 v128, 16, v118
	v_and_b32_e32 v129, 0xffff0000, v118
	v_lshlrev_b32_e32 v130, 16, v119
	v_and_b32_e32 v131, 0xffff0000, v119
	v_pk_fma_f32 v[148:149], v[56:57], v[0:1], v[36:37]
	v_pk_fma_f32 v[150:151], v[58:59], v[2:3], v[38:39]
	v_pk_fma_f32 v[152:153], v[60:61], v[0:1], v[36:37]
	v_pk_fma_f32 v[154:155], v[62:63], v[2:3], v[38:39]
	v_pk_fma_f32 v[148:149], v[72:73], v[4:5], v[148:149]
	v_pk_fma_f32 v[150:151], v[74:75], v[6:7], v[150:151]
	v_pk_fma_f32 v[152:153], v[76:77], v[4:5], v[152:153]
	v_pk_fma_f32 v[154:155], v[78:79], v[6:7], v[154:155]
	v_pk_fma_f32 v[148:149], v[40:41], v[8:9], v[148:149]
	v_pk_fma_f32 v[150:151], v[42:43], v[10:11], v[150:151]
	v_pk_fma_f32 v[152:153], v[44:45], v[8:9], v[152:153]
	v_pk_fma_f32 v[154:155], v[46:47], v[10:11], v[154:155]
	v_pk_fma_f32 v[148:149], v[60:61], v[12:13], v[148:149]
	v_pk_fma_f32 v[150:151], v[62:63], v[14:15], v[150:151]
	v_pk_fma_f32 v[152:153], v[64:65], v[12:13], v[152:153]
	v_pk_fma_f32 v[154:155], v[66:67], v[14:15], v[154:155]
	v_pk_fma_f32 v[148:149], v[76:77], v[16:17], v[148:149]
	v_pk_fma_f32 v[150:151], v[78:79], v[18:19], v[150:151]
	v_pk_fma_f32 v[152:153], v[80:81], v[16:17], v[152:153]
	v_pk_fma_f32 v[154:155], v[82:83], v[18:19], v[154:155]
	v_pk_fma_f32 v[148:149], v[44:45], v[20:21], v[148:149]
	v_pk_fma_f32 v[150:151], v[46:47], v[22:23], v[150:151]
	v_pk_fma_f32 v[152:153], v[48:49], v[20:21], v[152:153]
	v_pk_fma_f32 v[154:155], v[50:51], v[22:23], v[154:155]
	v_pk_fma_f32 v[148:149], v[64:65], v[24:25], v[148:149]
	v_pk_fma_f32 v[150:151], v[66:67], v[26:27], v[150:151]
	v_pk_fma_f32 v[152:153], v[68:69], v[24:25], v[152:153]
	v_pk_fma_f32 v[154:155], v[70:71], v[26:27], v[154:155]
	v_pk_fma_f32 v[148:149], v[80:81], v[28:29], v[148:149]
	v_pk_fma_f32 v[150:151], v[82:83], v[30:31], v[150:151]
	v_pk_fma_f32 v[152:153], v[84:85], v[28:29], v[152:153]
	v_pk_fma_f32 v[154:155], v[86:87], v[30:31], v[154:155]
	v_pk_fma_f32 v[148:149], v[48:49], v[32:33], v[148:149]
	v_pk_fma_f32 v[150:151], v[50:51], v[34:35], v[150:151]
	v_pk_fma_f32 v[152:153], v[52:53], v[32:33], v[152:153]
	v_pk_fma_f32 v[154:155], v[54:55], v[34:35], v[154:155]
	v_and_b32_e32 v156, 0x7fffffff, v148
	v_and_b32_e32 v157, 0x7fffffff, v149
	v_and_b32_e32 v158, 0x7fffffff, v150
	v_and_b32_e32 v159, 0x7fffffff, v151
	v_and_b32_e32 v160, 0x7fffffff, v152
	v_and_b32_e32 v161, 0x7fffffff, v153
	v_and_b32_e32 v162, 0x7fffffff, v154
	v_and_b32_e32 v163, 0x7fffffff, v155
	v_pk_fma_f32 v[164:165], v[156:157], v[184:185], v[186:187]
	v_pk_fma_f32 v[166:167], v[158:159], v[184:185], v[186:187]
	v_pk_fma_f32 v[168:169], v[160:161], v[184:185], v[186:187]
	v_pk_fma_f32 v[170:171], v[162:163], v[184:185], v[186:187]
	v_rcp_f32_e32 v164, v164
	v_rcp_f32_e32 v165, v165
	v_rcp_f32_e32 v166, v166
	v_rcp_f32_e32 v167, v167
	v_rcp_f32_e32 v168, v168
	v_rcp_f32_e32 v169, v169
	v_rcp_f32_e32 v170, v170
; __device__ __forceinline__ unsigned cvt_pk_bf16(float lo, float hi) { unsigned r; asm volatile("v_cvt_pk_bf16_f32 %0, %1, %2" : "=v"(r) : "v"(lo), "v"(hi)); return r; }
; __device__ __forceinline__ void phase_conv(KP p, int l, int tid) {
;     ...
;       for (int q = 0; q < CB; ++q) {
;         const int col = jb + q + 1;
; #pragma unroll
;         for (int di = 0; di < RB + 2; ++di) { const bool ok = rv[di] && (col < 64); unpack4(an[q][di], win[2][di]);
; #pragma unroll
;           for (int k = 0; k < 4; ++k) win[2][di][k] = ok ? win[2][di][k] : 0.f; }
; #pragma unroll
;         for (int rr = 0; rr < RB; ++rr) {
;           float uv[4]; unpack4(ur[q][rr], uv);
;           float o[4];
; #pragma unroll
;           for (int k = 0; k < 4; ++k) {
;             float a = bsv[k];
; #pragma unroll
;             for (int di = 0; di < 3; ++di)
; #pragma unroll
;               for (int dj = 0; dj < 3; ++dj) a += win[dj][rr + di][k] * w[di * 3 + dj][k];
;             o[k] = gelu_as(a) * uv[k];
;           }
;           u32x2 ow; ow.x = cvt_pk_bf16(o[0], o[1]); ow.y = cvt_pk_bf16(o[2], o[3]);
;           *(u32x2*)(G + (size_t)((r0 + rr) * 64 + jb + q) * DFF + c0) = ow;
;         }
	v_rcp_f32_e32 v171, v171
	v_pk_fma_f32 v[172:173], v[164:165], v[188:189], v[190:191]
	v_pk_fma_f32 v[174:175], v[166:167], v[188:189], v[190:191]
	v_pk_fma_f32 v[176:177], v[168:169], v[188:189], v[190:191]
	v_pk_fma_f32 v[178:179], v[170:171], v[188:189], v[190:191]
	v_pk_fma_f32 v[172:173], v[172:173], v[164:165], v[192:193]
	v_pk_fma_f32 v[174:175], v[174:175], v[166:167], v[192:193]
	v_pk_fma_f32 v[176:177], v[176:177], v[168:169], v[192:193]
	v_pk_fma_f32 v[178:179], v[178:179], v[170:171], v[192:193]
	v_pk_fma_f32 v[172:173], v[172:173], v[164:165], v[194:195]
	v_pk_fma_f32 v[174:175], v[174:175], v[166:167], v[194:195]
	v_pk_fma_f32 v[176:177], v[176:177], v[168:169], v[194:195]
	v_pk_fma_f32 v[178:179], v[178:179], v[170:171], v[194:195]
	v_pk_fma_f32 v[172:173], v[172:173], v[164:165], v[196:197]
	v_pk_fma_f32 v[174:175], v[174:175], v[166:167], v[196:197]
	v_pk_fma_f32 v[176:177], v[176:177], v[168:169], v[196:197]
	v_pk_fma_f32 v[178:179], v[178:179], v[170:171], v[196:197]
	v_pk_mul_f32 v[172:173], v[172:173], v[164:165]
	v_pk_mul_f32 v[174:175], v[174:175], v[166:167]
	v_pk_mul_f32 v[176:177], v[176:177], v[168:169]
	v_pk_mul_f32 v[178:179], v[178:179], v[170:171]
	v_pk_mul_f32 v[164:165], v[148:149], v[148:149]
	v_pk_mul_f32 v[166:167], v[150:151], v[150:151]
	v_pk_mul_f32 v[168:169], v[152:153], v[152:153]
	v_pk_mul_f32 v[170:171], v[154:155], v[154:155]
	v_pk_mul_f32 v[164:165], v[164:165], v[198:199]
	v_pk_mul_f32 v[166:167], v[166:167], v[198:199]
	v_pk_mul_f32 v[168:169], v[168:169], v[198:199]
	v_pk_mul_f32 v[170:171], v[170:171], v[198:199]
	v_exp_f32_e32 v164, v164
	v_exp_f32_e32 v165, v165
	v_exp_f32_e32 v166, v166
	v_exp_f32_e32 v167, v167
	v_exp_f32_e32 v168, v168
	v_exp_f32_e32 v169, v169
	v_exp_f32_e32 v170, v170
	v_exp_f32_e32 v171, v171
	v_pk_mul_f32 v[172:173], v[172:173], v[164:165]
	v_pk_mul_f32 v[174:175], v[174:175], v[166:167]
	v_pk_mul_f32 v[176:177], v[176:177], v[168:169]
	v_pk_mul_f32 v[178:179], v[178:179], v[170:171]
	v_pk_mul_f32 v[172:173], v[156:157], v[172:173]
	v_pk_mul_f32 v[174:175], v[158:159], v[174:175]
	v_pk_mul_f32 v[176:177], v[160:161], v[176:177]
	v_pk_mul_f32 v[178:179], v[162:163], v[178:179]
	v_max_f32_e32 v164, 0, v148
	v_max_f32_e32 v165, 0, v149
	v_max_f32_e32 v166, 0, v150
	v_max_f32_e32 v167, 0, v151
	v_max_f32_e32 v168, 0, v152
	v_max_f32_e32 v169, 0, v153
	v_max_f32_e32 v170, 0, v154
	v_max_f32_e32 v171, 0, v155
	v_pk_add_f32 v[164:165], v[164:165], v[172:173] neg_lo:[0,1] neg_hi:[0,1]
	v_pk_add_f32 v[166:167], v[166:167], v[174:175] neg_lo:[0,1] neg_hi:[0,1]
	v_pk_add_f32 v[168:169], v[168:169], v[176:177] neg_lo:[0,1] neg_hi:[0,1]
	v_pk_add_f32 v[170:171], v[170:171], v[178:179] neg_lo:[0,1] neg_hi:[0,1]
	v_pk_mul_f32 v[164:165], v[164:165], v[124:125]
	v_pk_mul_f32 v[166:167], v[166:167], v[126:127]
	v_pk_mul_f32 v[168:169], v[168:169], v[128:129]
	v_pk_mul_f32 v[170:171], v[170:171], v[130:131]
	v_cvt_pk_bf16_f32 v156, v164, v165
	v_cvt_pk_bf16_f32 v157, v166, v167
	v_cvt_pk_bf16_f32 v158, v168, v169
	v_cvt_pk_bf16_f32 v159, v170, v171
	global_store_dwordx2 v218, v[156:157], s[10:11]
	global_store_dwordx2 v219, v[158:159], s[10:11]
	s_waitcnt vmcnt(10)
	v_lshlrev_b32_e32 v56, 16, v104
	v_and_b32_e32 v57, 0xffff0000, v104
	v_lshlrev_b32_e32 v58, 16, v105
	v_and_b32_e32 v59, 0xffff0000, v105
	v_lshlrev_b32_e32 v60, 16, v106
	v_and_b32_e32 v61, 0xffff0000, v106
	v_lshlrev_b32_e32 v62, 16, v107
	v_and_b32_e32 v63, 0xffff0000, v107
	v_lshlrev_b32_e32 v64, 16, v108
	v_and_b32_e32 v65, 0xffff0000, v108
	v_lshlrev_b32_e32 v66, 16, v109
	v_and_b32_e32 v67, 0xffff0000, v109
	v_lshlrev_b32_e32 v68, 16, v110
	v_and_b32_e32 v69, 0xffff0000, v110
	v_lshlrev_b32_e32 v70, 16, v111
	v_and_b32_e32 v71, 0xffff0000, v111
	v_pk_mul_f32 v[56:57], v[56:57], v[200:201]
	v_pk_mul_f32 v[58:59], v[58:59], v[200:201]
	v_pk_mul_f32 v[68:69], v[68:69], v[202:203]
	v_pk_mul_f32 v[70:71], v[70:71], v[202:203]
	v_lshlrev_b32_e32 v124, 16, v120
	v_and_b32_e32 v125, 0xffff0000, v120
	v_lshlrev_b32_e32 v126, 16, v121
	v_and_b32_e32 v127, 0xffff0000, v121
	v_lshlrev_b32_e32 v128, 16, v122
	v_and_b32_e32 v129, 0xffff0000, v122
	v_lshlrev_b32_e32 v130, 16, v123
	v_and_b32_e32 v131, 0xffff0000, v123
	v_pk_fma_f32 v[148:149], v[72:73], v[0:1], v[36:37]
	v_pk_fma_f32 v[150:151], v[74:75], v[2:3], v[38:39]
	v_pk_fma_f32 v[152:153], v[76:77], v[0:1], v[36:37]
	v_pk_fma_f32 v[154:155], v[78:79], v[2:3], v[38:39]
	v_pk_fma_f32 v[148:149], v[40:41], v[4:5], v[148:149]
	v_pk_fma_f32 v[150:151], v[42:43], v[6:7], v[150:151]
	v_pk_fma_f32 v[152:153], v[44:45], v[4:5], v[152:153]
	v_pk_fma_f32 v[154:155], v[46:47], v[6:7], v[154:155]
	v_pk_fma_f32 v[148:149], v[56:57], v[8:9], v[148:149]
	v_pk_fma_f32 v[150:151], v[58:59], v[10:11], v[150:151]
	v_pk_fma_f32 v[152:153], v[60:61], v[8:9], v[152:153]
	v_pk_fma_f32 v[154:155], v[62:63], v[10:11], v[154:155]
	v_pk_fma_f32 v[148:149], v[76:77], v[12:13], v[148:149]
	v_pk_fma_f32 v[150:151], v[78:79], v[14:15], v[150:151]
	v_pk_fma_f32 v[152:153], v[80:81], v[12:13], v[152:153]
	v_pk_fma_f32 v[154:155], v[82:83], v[14:15], v[154:155]
	v_pk_fma_f32 v[148:149], v[44:45], v[16:17], v[148:149]
	v_pk_fma_f32 v[150:151], v[46:47], v[18:19], v[150:151]
	v_pk_fma_f32 v[152:153], v[48:49], v[16:17], v[152:153]
	v_pk_fma_f32 v[154:155], v[50:51], v[18:19], v[154:155]
	v_pk_fma_f32 v[148:149], v[60:61], v[20:21], v[148:149]
	v_pk_fma_f32 v[150:151], v[62:63], v[22:23], v[150:151]
	v_pk_fma_f32 v[152:153], v[64:65], v[20:21], v[152:153]
	v_pk_fma_f32 v[154:155], v[66:67], v[22:23], v[154:155]
	v_pk_fma_f32 v[148:149], v[80:81], v[24:25], v[148:149]
	v_pk_fma_f32 v[150:151], v[82:83], v[26:27], v[150:151]
; __device__ __forceinline__ unsigned cvt_pk_bf16(float lo, float hi) { unsigned r; asm volatile("v_cvt_pk_bf16_f32 %0, %1, %2" : "=v"(r) : "v"(lo), "v"(hi)); return r; }
; __device__ __forceinline__ void phase_conv(KP p, int l, int tid) {
;     ...
;       for (int q = 0; q < CB; ++q) {
;         const int col = jb + q + 1;
; #pragma unroll
;         for (int di = 0; di < RB + 2; ++di) { const bool ok = rv[di] && (col < 64); unpack4(an[q][di], win[2][di]);
; #pragma unroll
;           for (int k = 0; k < 4; ++k) win[2][di][k] = ok ? win[2][di][k] : 0.f; }
; #pragma unroll
;         for (int rr = 0; rr < RB; ++rr) {
;           float uv[4]; unpack4(ur[q][rr], uv);
;           float o[4];
; #pragma unroll
;           for (int k = 0; k < 4; ++k) {
;             float a = bsv[k];
; #pragma unroll
;             for (int di = 0; di < 3; ++di)
; #pragma unroll
;               for (int dj = 0; dj < 3; ++dj) a += win[dj][rr + di][k] * w[di * 3 + dj][k];
;             o[k] = gelu_as(a) * uv[k];
;           }
;           u32x2 ow; ow.x = cvt_pk_bf16(o[0], o[1]); ow.y = cvt_pk_bf16(o[2], o[3]);
;           *(u32x2*)(G + (size_t)((r0 + rr) * 64 + jb + q) * DFF + c0) = ow;
;         }
	v_pk_fma_f32 v[152:153], v[84:85], v[24:25], v[152:153]
	v_pk_fma_f32 v[154:155], v[86:87], v[26:27], v[154:155]
	v_pk_fma_f32 v[148:149], v[48:49], v[28:29], v[148:149]
	v_pk_fma_f32 v[150:151], v[50:51], v[30:31], v[150:151]
	v_pk_fma_f32 v[152:153], v[52:53], v[28:29], v[152:153]
	v_pk_fma_f32 v[154:155], v[54:55], v[30:31], v[154:155]
	v_pk_fma_f32 v[148:149], v[64:65], v[32:33], v[148:149]
	v_pk_fma_f32 v[150:151], v[66:67], v[34:35], v[150:151]
	v_pk_fma_f32 v[152:153], v[68:69], v[32:33], v[152:153]
	v_pk_fma_f32 v[154:155], v[70:71], v[34:35], v[154:155]
	v_and_b32_e32 v156, 0x7fffffff, v148
	v_and_b32_e32 v157, 0x7fffffff, v149
	v_and_b32_e32 v158, 0x7fffffff, v150
	v_and_b32_e32 v159, 0x7fffffff, v151
	v_and_b32_e32 v160, 0x7fffffff, v152
	v_and_b32_e32 v161, 0x7fffffff, v153
	v_and_b32_e32 v162, 0x7fffffff, v154
	v_and_b32_e32 v163, 0x7fffffff, v155
	v_pk_fma_f32 v[164:165], v[156:157], v[184:185], v[186:187]
	v_pk_fma_f32 v[166:167], v[158:159], v[184:185], v[186:187]
	v_pk_fma_f32 v[168:169], v[160:161], v[184:185], v[186:187]
	v_pk_fma_f32 v[170:171], v[162:163], v[184:185], v[186:187]
	v_rcp_f32_e32 v164, v164
	v_rcp_f32_e32 v165, v165
	v_rcp_f32_e32 v166, v166
	v_rcp_f32_e32 v167, v167
	v_rcp_f32_e32 v168, v168
	v_rcp_f32_e32 v169, v169
	v_rcp_f32_e32 v170, v170
	v_rcp_f32_e32 v171, v171
	v_pk_fma_f32 v[172:173], v[164:165], v[188:189], v[190:191]
	v_pk_fma_f32 v[174:175], v[166:167], v[188:189], v[190:191]
	v_pk_fma_f32 v[176:177], v[168:169], v[188:189], v[190:191]
	v_pk_fma_f32 v[178:179], v[170:171], v[188:189], v[190:191]
	v_pk_fma_f32 v[172:173], v[172:173], v[164:165], v[192:193]
	v_pk_fma_f32 v[174:175], v[174:175], v[166:167], v[192:193]
	v_pk_fma_f32 v[176:177], v[176:177], v[168:169], v[192:193]
	v_pk_fma_f32 v[178:179], v[178:179], v[170:171], v[192:193]
	v_pk_fma_f32 v[172:173], v[172:173], v[164:165], v[194:195]
	v_pk_fma_f32 v[174:175], v[174:175], v[166:167], v[194:195]
	v_pk_fma_f32 v[176:177], v[176:177], v[168:169], v[194:195]
	v_pk_fma_f32 v[178:179], v[178:179], v[170:171], v[194:195]
	v_pk_fma_f32 v[172:173], v[172:173], v[164:165], v[196:197]
	v_pk_fma_f32 v[174:175], v[174:175], v[166:167], v[196:197]
	v_pk_fma_f32 v[176:177], v[176:177], v[168:169], v[196:197]
	v_pk_fma_f32 v[178:179], v[178:179], v[170:171], v[196:197]
	v_pk_mul_f32 v[172:173], v[172:173], v[164:165]
	v_pk_mul_f32 v[174:175], v[174:175], v[166:167]
	v_pk_mul_f32 v[176:177], v[176:177], v[168:169]
	v_pk_mul_f32 v[178:179], v[178:179], v[170:171]
	v_pk_mul_f32 v[164:165], v[148:149], v[148:149]
	v_pk_mul_f32 v[166:167], v[150:151], v[150:151]
	v_pk_mul_f32 v[168:169], v[152:153], v[152:153]
	v_pk_mul_f32 v[170:171], v[154:155], v[154:155]
	v_pk_mul_f32 v[164:165], v[164:165], v[198:199]
	v_pk_mul_f32 v[166:167], v[166:167], v[198:199]
	v_pk_mul_f32 v[168:169], v[168:169], v[198:199]
	v_pk_mul_f32 v[170:171], v[170:171], v[198:199]
	v_exp_f32_e32 v164, v164
	v_exp_f32_e32 v165, v165
	v_exp_f32_e32 v166, v166
	v_exp_f32_e32 v167, v167
	v_exp_f32_e32 v168, v168
	v_exp_f32_e32 v169, v169
	v_exp_f32_e32 v170, v170
	v_exp_f32_e32 v171, v171
	v_pk_mul_f32 v[172:173], v[172:173], v[164:165]
	v_pk_mul_f32 v[174:175], v[174:175], v[166:167]
	v_pk_mul_f32 v[176:177], v[176:177], v[168:169]
	v_pk_mul_f32 v[178:179], v[178:179], v[170:171]
	v_pk_mul_f32 v[172:173], v[156:157], v[172:173]
	v_pk_mul_f32 v[174:175], v[158:159], v[174:175]
	v_pk_mul_f32 v[176:177], v[160:161], v[176:177]
	v_pk_mul_f32 v[178:179], v[162:163], v[178:179]
	v_max_f32_e32 v164, 0, v148
	v_max_f32_e32 v165, 0, v149
	v_max_f32_e32 v166, 0, v150
	v_max_f32_e32 v167, 0, v151
	v_max_f32_e32 v168, 0, v152
	v_max_f32_e32 v169, 0, v153
	v_max_f32_e32 v170, 0, v154
	v_max_f32_e32 v171, 0, v155
	v_pk_add_f32 v[164:165], v[164:165], v[172:173] neg_lo:[0,1] neg_hi:[0,1]
	v_pk_add_f32 v[166:167], v[166:167], v[174:175] neg_lo:[0,1] neg_hi:[0,1]
	v_pk_add_f32 v[168:169], v[168:169], v[176:177] neg_lo:[0,1] neg_hi:[0,1]
	v_pk_add_f32 v[170:171], v[170:171], v[178:179] neg_lo:[0,1] neg_hi:[0,1]
	v_pk_mul_f32 v[164:165], v[164:165], v[124:125]
	v_pk_mul_f32 v[166:167], v[166:167], v[126:127]
	v_pk_mul_f32 v[168:169], v[168:169], v[128:129]
	v_pk_mul_f32 v[170:171], v[170:171], v[130:131]
	v_cvt_pk_bf16_f32 v156, v164, v165
	v_cvt_pk_bf16_f32 v157, v166, v167
	v_cvt_pk_bf16_f32 v158, v168, v169
	v_cvt_pk_bf16_f32 v159, v170, v171
	global_store_dwordx2 v220, v[156:157], s[10:11]
	global_store_dwordx2 v221, v[158:159], s[10:11]
	s_waitcnt vmcnt(4)
; __device__ __forceinline__ void phase_conv(KP p, int l, int tid) {
;     ...
;       for (int q = 0; q < CB; ++q) {
;         const int col = jb + q + 1;
; #pragma unroll
;         for (int di = 0; di < RB + 2; ++di) { const bool ok = rv[di] && (col < 64); unpack4(an[q][di], win[2][di]);
; #pragma unroll
;           for (int k = 0; k < 4; ++k) win[2][di][k] = ok ? win[2][di][k] : 0.f; }
; #pragma unroll
;         for (int rr = 0; rr < RB; ++rr) {
;           float uv[4]; unpack4(ur[q][rr], uv);
;           float o[4];
; #pragma unroll
;           for (int k = 0; k < 4; ++k) {
;             float a = bsv[k];
; #pragma unroll
;             for (int di = 0; di < 3; ++di)
; #pragma unroll
;               for (int dj = 0; dj < 3; ++dj) a += win[dj][rr + di][k] * w[di * 3 + dj][k];
;             o[k] = gelu_as(a) * uv[k];
	v_lshlrev_b32_e32 v72, 16, v88
	v_and_b32_e32 v73, 0xffff0000, v88
	v_lshlrev_b32_e32 v74, 16, v89
	v_and_b32_e32 v75, 0xffff0000, v89
	v_lshlrev_b32_e32 v76, 16, v90
	v_and_b32_e32 v77, 0xffff0000, v90
	v_lshlrev_b32_e32 v78, 16, v91
	v_and_b32_e32 v79, 0xffff0000, v91
	v_lshlrev_b32_e32 v80, 16, v92
	v_and_b32_e32 v81, 0xffff0000, v92
	v_lshlrev_b32_e32 v82, 16, v93
	v_and_b32_e32 v83, 0xffff0000, v93
	v_lshlrev_b32_e32 v84, 16, v94
	v_and_b32_e32 v85, 0xffff0000, v94
	v_lshlrev_b32_e32 v86, 16, v95
	v_and_b32_e32 v87, 0xffff0000, v95
	v_pk_mul_f32 v[72:73], v[72:73], v[200:201]
	v_pk_mul_f32 v[74:75], v[74:75], v[200:201]
	v_pk_mul_f32 v[84:85], v[84:85], v[202:203]
	v_pk_mul_f32 v[86:87], v[86:87], v[202:203]
	v_pk_mul_f32 v[72:73], v[72:73], v[204:205]
	v_pk_mul_f32 v[74:75], v[74:75], v[204:205]
	v_pk_mul_f32 v[76:77], v[76:77], v[204:205]
	v_pk_mul_f32 v[78:79], v[78:79], v[204:205]
	v_pk_mul_f32 v[80:81], v[80:81], v[204:205]
	v_pk_mul_f32 v[82:83], v[82:83], v[204:205]
	v_pk_mul_f32 v[84:85], v[84:85], v[204:205]
	v_pk_mul_f32 v[86:87], v[86:87], v[204:205]
	v_lshlrev_b32_e32 v124, 16, v112
	v_and_b32_e32 v125, 0xffff0000, v112
	v_lshlrev_b32_e32 v126, 16, v113
	v_and_b32_e32 v127, 0xffff0000, v113
	v_lshlrev_b32_e32 v128, 16, v114
	v_and_b32_e32 v129, 0xffff0000, v114
	v_lshlrev_b32_e32 v130, 16, v115
	v_and_b32_e32 v131, 0xffff0000, v115
	v_pk_fma_f32 v[148:149], v[40:41], v[0:1], v[36:37]
	v_pk_fma_f32 v[150:151], v[42:43], v[2:3], v[38:39]
	v_pk_fma_f32 v[152:153], v[44:45], v[0:1], v[36:37]
	v_pk_fma_f32 v[154:155], v[46:47], v[2:3], v[38:39]
	v_pk_fma_f32 v[148:149], v[56:57], v[4:5], v[148:149]
	v_pk_fma_f32 v[150:151], v[58:59], v[6:7], v[150:151]
	v_pk_fma_f32 v[152:153], v[60:61], v[4:5], v[152:153]
	v_pk_fma_f32 v[154:155], v[62:63], v[6:7], v[154:155]
	v_pk_fma_f32 v[148:149], v[72:73], v[8:9], v[148:149]
	v_pk_fma_f32 v[150:151], v[74:75], v[10:11], v[150:151]
	v_pk_fma_f32 v[152:153], v[76:77], v[8:9], v[152:153]
	v_pk_fma_f32 v[154:155], v[78:79], v[10:11], v[154:155]
	v_pk_fma_f32 v[148:149], v[44:45], v[12:13], v[148:149]
	v_pk_fma_f32 v[150:151], v[46:47], v[14:15], v[150:151]
	v_pk_fma_f32 v[152:153], v[48:49], v[12:13], v[152:153]
	v_pk_fma_f32 v[154:155], v[50:51], v[14:15], v[154:155]
	v_pk_fma_f32 v[148:149], v[60:61], v[16:17], v[148:149]
	v_pk_fma_f32 v[150:151], v[62:63], v[18:19], v[150:151]
	v_pk_fma_f32 v[152:153], v[64:65], v[16:17], v[152:153]
	v_pk_fma_f32 v[154:155], v[66:67], v[18:19], v[154:155]
	v_pk_fma_f32 v[148:149], v[76:77], v[20:21], v[148:149]
	v_pk_fma_f32 v[150:151], v[78:79], v[22:23], v[150:151]
	v_pk_fma_f32 v[152:153], v[80:81], v[20:21], v[152:153]
	v_pk_fma_f32 v[154:155], v[82:83], v[22:23], v[154:155]
	v_pk_fma_f32 v[148:149], v[48:49], v[24:25], v[148:149]
	v_pk_fma_f32 v[150:151], v[50:51], v[26:27], v[150:151]
	v_pk_fma_f32 v[152:153], v[52:53], v[24:25], v[152:153]
	v_pk_fma_f32 v[154:155], v[54:55], v[26:27], v[154:155]
	v_pk_fma_f32 v[148:149], v[64:65], v[28:29], v[148:149]
	v_pk_fma_f32 v[150:151], v[66:67], v[30:31], v[150:151]
	v_pk_fma_f32 v[152:153], v[68:69], v[28:29], v[152:153]
	v_pk_fma_f32 v[154:155], v[70:71], v[30:31], v[154:155]
	v_pk_fma_f32 v[148:149], v[80:81], v[32:33], v[148:149]
	v_pk_fma_f32 v[150:151], v[82:83], v[34:35], v[150:151]
	v_pk_fma_f32 v[152:153], v[84:85], v[32:33], v[152:153]
	v_pk_fma_f32 v[154:155], v[86:87], v[34:35], v[154:155]
	v_and_b32_e32 v156, 0x7fffffff, v148
	v_and_b32_e32 v157, 0x7fffffff, v149
	v_and_b32_e32 v158, 0x7fffffff, v150
	v_and_b32_e32 v159, 0x7fffffff, v151
	v_and_b32_e32 v160, 0x7fffffff, v152
	v_and_b32_e32 v161, 0x7fffffff, v153
	v_and_b32_e32 v162, 0x7fffffff, v154
	v_and_b32_e32 v163, 0x7fffffff, v155
	v_pk_fma_f32 v[164:165], v[156:157], v[184:185], v[186:187]
; __device__ __forceinline__ unsigned cvt_pk_bf16(float lo, float hi) { unsigned r; asm volatile("v_cvt_pk_bf16_f32 %0, %1, %2" : "=v"(r) : "v"(lo), "v"(hi)); return r; }
; __device__ __forceinline__ void phase_conv(KP p, int l, int tid) {
;     ...
;   for (int it = blockIdx.x * NTH + tid; it < total; it += gridDim.x * NTH) {
;     ...
;       for (int q = 0; q < CB; ++q) {
;         const int col = jb + q + 1;
; #pragma unroll
;         for (int di = 0; di < RB + 2; ++di) { const bool ok = rv[di] && (col < 64); unpack4(an[q][di], win[2][di]);
; #pragma unroll
;           for (int k = 0; k < 4; ++k) win[2][di][k] = ok ? win[2][di][k] : 0.f; }
; #pragma unroll
;         for (int rr = 0; rr < RB; ++rr) {
;           float uv[4]; unpack4(ur[q][rr], uv);
;           float o[4];
; #pragma unroll
;           for (int k = 0; k < 4; ++k) {
;             float a = bsv[k];
; #pragma unroll
;             for (int di = 0; di < 3; ++di)
; #pragma unroll
;               for (int dj = 0; dj < 3; ++dj) a += win[dj][rr + di][k] * w[di * 3 + dj][k];
;             o[k] = gelu_as(a) * uv[k];
;           }
;           u32x2 ow; ow.x = cvt_pk_bf16(o[0], o[1]); ow.y = cvt_pk_bf16(o[2], o[3]);
;           *(u32x2*)(G + (size_t)((r0 + rr) * 64 + jb + q) * DFF + c0) = ow;
;         }
	v_pk_fma_f32 v[166:167], v[158:159], v[184:185], v[186:187]
	v_pk_fma_f32 v[168:169], v[160:161], v[184:185], v[186:187]
	v_pk_fma_f32 v[170:171], v[162:163], v[184:185], v[186:187]
	v_rcp_f32_e32 v164, v164
	v_rcp_f32_e32 v165, v165
	v_rcp_f32_e32 v166, v166
	v_rcp_f32_e32 v167, v167
	v_rcp_f32_e32 v168, v168
	v_rcp_f32_e32 v169, v169
	v_rcp_f32_e32 v170, v170
	v_rcp_f32_e32 v171, v171
	v_pk_fma_f32 v[172:173], v[164:165], v[188:189], v[190:191]
	v_pk_fma_f32 v[174:175], v[166:167], v[188:189], v[190:191]
	v_pk_fma_f32 v[176:177], v[168:169], v[188:189], v[190:191]
	v_pk_fma_f32 v[178:179], v[170:171], v[188:189], v[190:191]
	v_pk_fma_f32 v[172:173], v[172:173], v[164:165], v[192:193]
	v_pk_fma_f32 v[174:175], v[174:175], v[166:167], v[192:193]
	v_pk_fma_f32 v[176:177], v[176:177], v[168:169], v[192:193]
	v_pk_fma_f32 v[178:179], v[178:179], v[170:171], v[192:193]
	v_pk_fma_f32 v[172:173], v[172:173], v[164:165], v[194:195]
	v_pk_fma_f32 v[174:175], v[174:175], v[166:167], v[194:195]
	v_pk_fma_f32 v[176:177], v[176:177], v[168:169], v[194:195]
	v_pk_fma_f32 v[178:179], v[178:179], v[170:171], v[194:195]
	v_pk_fma_f32 v[172:173], v[172:173], v[164:165], v[196:197]
	v_pk_fma_f32 v[174:175], v[174:175], v[166:167], v[196:197]
	v_pk_fma_f32 v[176:177], v[176:177], v[168:169], v[196:197]
	v_pk_fma_f32 v[178:179], v[178:179], v[170:171], v[196:197]
	v_pk_mul_f32 v[172:173], v[172:173], v[164:165]
	v_pk_mul_f32 v[174:175], v[174:175], v[166:167]
	v_pk_mul_f32 v[176:177], v[176:177], v[168:169]
	v_pk_mul_f32 v[178:179], v[178:179], v[170:171]
	v_pk_mul_f32 v[164:165], v[148:149], v[148:149]
	v_pk_mul_f32 v[166:167], v[150:151], v[150:151]
	v_pk_mul_f32 v[168:169], v[152:153], v[152:153]
	v_pk_mul_f32 v[170:171], v[154:155], v[154:155]
	v_pk_mul_f32 v[164:165], v[164:165], v[198:199]
	v_pk_mul_f32 v[166:167], v[166:167], v[198:199]
	v_pk_mul_f32 v[168:169], v[168:169], v[198:199]
	v_pk_mul_f32 v[170:171], v[170:171], v[198:199]
	v_exp_f32_e32 v164, v164
	v_exp_f32_e32 v165, v165
	v_exp_f32_e32 v166, v166
	v_exp_f32_e32 v167, v167
	v_exp_f32_e32 v168, v168
	v_exp_f32_e32 v169, v169
	v_exp_f32_e32 v170, v170
	v_exp_f32_e32 v171, v171
	v_pk_mul_f32 v[172:173], v[172:173], v[164:165]
	v_pk_mul_f32 v[174:175], v[174:175], v[166:167]
	v_pk_mul_f32 v[176:177], v[176:177], v[168:169]
	v_pk_mul_f32 v[178:179], v[178:179], v[170:171]
	v_pk_mul_f32 v[172:173], v[156:157], v[172:173]
	v_pk_mul_f32 v[174:175], v[158:159], v[174:175]
	v_pk_mul_f32 v[176:177], v[160:161], v[176:177]
	v_pk_mul_f32 v[178:179], v[162:163], v[178:179]
	v_max_f32_e32 v164, 0, v148
	v_max_f32_e32 v165, 0, v149
	v_max_f32_e32 v166, 0, v150
	v_max_f32_e32 v167, 0, v151
	v_max_f32_e32 v168, 0, v152
	v_max_f32_e32 v169, 0, v153
	v_max_f32_e32 v170, 0, v154
	v_max_f32_e32 v171, 0, v155
	v_pk_add_f32 v[164:165], v[164:165], v[172:173] neg_lo:[0,1] neg_hi:[0,1]
	v_pk_add_f32 v[166:167], v[166:167], v[174:175] neg_lo:[0,1] neg_hi:[0,1]
	v_pk_add_f32 v[168:169], v[168:169], v[176:177] neg_lo:[0,1] neg_hi:[0,1]
	v_pk_add_f32 v[170:171], v[170:171], v[178:179] neg_lo:[0,1] neg_hi:[0,1]
	v_pk_mul_f32 v[164:165], v[164:165], v[124:125]
	v_pk_mul_f32 v[166:167], v[166:167], v[126:127]
	v_pk_mul_f32 v[168:169], v[168:169], v[128:129]
	v_pk_mul_f32 v[170:171], v[170:171], v[130:131]
	v_cvt_pk_bf16_f32 v156, v164, v165
	v_cvt_pk_bf16_f32 v157, v166, v167
	v_cvt_pk_bf16_f32 v158, v168, v169
	v_cvt_pk_bf16_f32 v159, v170, v171
	global_store_dwordx2 v216, v[156:157], s[10:11]
	global_store_dwordx2 v217, v[158:159], s[10:11]
	v_add_u32_e32 v142, s73, v142
	s_mov_b32 s0, 0xaffff
	v_cmp_lt_i32_e32 vcc, s0, v142
	s_or_b64 s[28:29], vcc, s[28:29]
	s_andn2_b64 exec, exec, s[28:29]
	s_cbranch_execnz .Lcv_item
